# speedup vs baseline: 1.0267x; 1.0083x over previous
.Llate_p1_done:
.LBB0_89:
	ds_read_b128 v[128:131], v222
	ds_read_b128 v[132:135], v222 offset:2048
	ds_read_b128 v[136:139], v223
	ds_read_b128 v[140:143], v223 offset:2048
	s_mov_b32 m0, s74
	ds_read_b128 v[144:147], v224
	ds_read_b128 v[148:151], v224 offset:2048
	ds_read_b128 v[152:155], v225
	ds_read_b128 v[156:159], v225 offset:2048
	ds_read_b128 v[160:163], v224 offset:4096
	ds_read_b128 v[164:167], v224 offset:6144
	ds_read_b128 v[168:171], v225 offset:4096
	ds_read_b128 v[172:175], v225 offset:6144
	s_add_u32 s82, s38, 0x80080
	s_addc_u32 s83, s39, 0x0
	s_nop 0
	global_load_lds_dwordx4 v212, s[82:83]
	s_mov_b32 m0, s75
	s_nop 0
	s_add_u32 s82, s38, 0xc0080
	s_addc_u32 s83, s39, 0x0
	s_nop 0
	global_load_lds_dwordx4 v212, s[82:83]
	s_waitcnt lgkmcnt(8)
	s_barrier
	s_waitcnt lgkmcnt(0)
	v_mfma_f32_16x16x32_bf16 v[124:127], v[128:131], v[144:147], v[124:127]
	v_mfma_f32_16x16x32_bf16 v[120:123], v[132:135], v[144:147], v[120:123]
	v_mfma_f32_16x16x32_bf16 v[116:119], v[128:131], v[148:151], v[116:119]
	v_mfma_f32_16x16x32_bf16 v[112:115], v[132:135], v[148:151], v[112:115]
	v_mfma_f32_16x16x32_bf16 v[108:111], v[128:131], v[160:163], v[108:111]
	v_mfma_f32_16x16x32_bf16 v[104:107], v[132:135], v[160:163], v[104:107]
	v_mfma_f32_16x16x32_bf16 v[100:103], v[128:131], v[164:167], v[100:103]
	v_mfma_f32_16x16x32_bf16 v[96:99], v[132:135], v[164:167], v[96:99]
	v_mfma_f32_16x16x32_bf16 v[124:127], v[136:139], v[152:155], v[124:127]
	v_mfma_f32_16x16x32_bf16 v[120:123], v[140:143], v[152:155], v[120:123]
	v_mfma_f32_16x16x32_bf16 v[116:119], v[136:139], v[156:159], v[116:119]
	v_mfma_f32_16x16x32_bf16 v[112:115], v[140:143], v[156:159], v[112:115]
	v_mfma_f32_16x16x32_bf16 v[108:111], v[136:139], v[168:171], v[108:111]
	v_mfma_f32_16x16x32_bf16 v[104:107], v[140:143], v[168:171], v[104:107]
	v_mfma_f32_16x16x32_bf16 v[100:103], v[136:139], v[172:175], v[100:103]
	v_mfma_f32_16x16x32_bf16 v[96:99], v[140:143], v[172:175], v[96:99]
	s_barrier
	s_mov_b32 m0, s30
	ds_read_b128 v[176:179], v226
	ds_read_b128 v[180:183], v226 offset:2048
	ds_read_b128 v[184:187], v227
	ds_read_b128 v[188:191], v227 offset:2048
	s_add_u32 s82, s40, s24
	s_addc_u32 s83, s41, s25
	s_nop 0
	global_load_lds_dwordx4 v212, s[82:83]
	s_mov_b32 m0, s31
	s_nop 0
	s_add_u32 s82, s40, s26
	s_addc_u32 s83, s41, s27
	s_nop 0
	global_load_lds_dwordx4 v212, s[82:83]
	s_barrier
	s_waitcnt lgkmcnt(0)
	v_mfma_f32_16x16x32_bf16 v[92:95], v[176:179], v[144:147], v[92:95]
	v_mfma_f32_16x16x32_bf16 v[88:91], v[180:183], v[144:147], v[88:91]
	v_mfma_f32_16x16x32_bf16 v[84:87], v[176:179], v[148:151], v[84:87]
	v_mfma_f32_16x16x32_bf16 v[80:83], v[180:183], v[148:151], v[80:83]
	v_mfma_f32_16x16x32_bf16 v[76:79], v[176:179], v[160:163], v[76:79]
	v_mfma_f32_16x16x32_bf16 v[72:75], v[180:183], v[160:163], v[72:75]
	v_mfma_f32_16x16x32_bf16 v[68:71], v[176:179], v[164:167], v[68:71]
	v_mfma_f32_16x16x32_bf16 v[56:59], v[180:183], v[164:167], v[56:59]
	v_mfma_f32_16x16x32_bf16 v[92:95], v[184:187], v[152:155], v[92:95]
	v_mfma_f32_16x16x32_bf16 v[88:91], v[188:191], v[152:155], v[88:91]
	v_mfma_f32_16x16x32_bf16 v[84:87], v[184:187], v[156:159], v[84:87]
	v_mfma_f32_16x16x32_bf16 v[80:83], v[188:191], v[156:159], v[80:83]
	v_mfma_f32_16x16x32_bf16 v[76:79], v[184:187], v[168:171], v[76:79]
	v_mfma_f32_16x16x32_bf16 v[72:75], v[188:191], v[168:171], v[72:75]
	v_mfma_f32_16x16x32_bf16 v[68:71], v[184:187], v[172:175], v[68:71]
	v_mfma_f32_16x16x32_bf16 v[56:59], v[188:191], v[172:175], v[56:59]
	s_barrier
	s_mov_b32 m0, s22
	ds_read_b128 v[144:147], v224 offset:16384
	ds_read_b128 v[148:151], v224 offset:18432
	ds_read_b128 v[152:155], v225 offset:16384
	ds_read_b128 v[156:159], v225 offset:18432
	ds_read_b128 v[160:163], v224 offset:20480
	ds_read_b128 v[164:167], v224 offset:22528
	ds_read_b128 v[168:171], v225 offset:20480
	ds_read_b128 v[172:175], v225 offset:22528
	s_add_u32 s82, s38, s24
	s_addc_u32 s83, s39, s25
	s_nop 0
	global_load_lds_dwordx4 v212, s[82:83]
	s_mov_b32 m0, s33
	s_nop 0
	s_add_u32 s82, s38, s26
	s_addc_u32 s83, s39, s27
	s_nop 0
	global_load_lds_dwordx4 v212, s[82:83]
	s_barrier
	s_waitcnt lgkmcnt(0)
	v_mfma_f32_16x16x32_bf16 v[28:31], v[128:131], v[144:147], v[28:31]
	v_mfma_f32_16x16x32_bf16 v[24:27], v[132:135], v[144:147], v[24:27]
	v_mfma_f32_16x16x32_bf16 v[20:23], v[128:131], v[148:151], v[20:23]
	v_mfma_f32_16x16x32_bf16 v[16:19], v[132:135], v[148:151], v[16:19]
	v_mfma_f32_16x16x32_bf16 v[12:15], v[128:131], v[160:163], v[12:15]
	v_mfma_f32_16x16x32_bf16 v[8:11], v[132:135], v[160:163], v[8:11]
	v_mfma_f32_16x16x32_bf16 v[4:7], v[128:131], v[164:167], v[4:7]
	v_mfma_f32_16x16x32_bf16 v[0:3], v[132:135], v[164:167], v[0:3]
	v_mfma_f32_16x16x32_bf16 v[28:31], v[136:139], v[152:155], v[28:31]
	v_mfma_f32_16x16x32_bf16 v[24:27], v[140:143], v[152:155], v[24:27]
	v_mfma_f32_16x16x32_bf16 v[20:23], v[136:139], v[156:159], v[20:23]
	v_mfma_f32_16x16x32_bf16 v[16:19], v[140:143], v[156:159], v[16:19]
	v_mfma_f32_16x16x32_bf16 v[12:15], v[136:139], v[168:171], v[12:15]
	v_mfma_f32_16x16x32_bf16 v[8:11], v[140:143], v[168:171], v[8:11]
	v_mfma_f32_16x16x32_bf16 v[4:7], v[136:139], v[172:175], v[4:7]
	v_mfma_f32_16x16x32_bf16 v[0:3], v[140:143], v[172:175], v[0:3]
	s_barrier
	s_mov_b32 m0, s34
	s_add_u32 s82, s4, s24
	s_addc_u32 s83, s5, s25
	s_nop 0
	global_load_lds_dwordx4 v212, s[82:83]
	s_mov_b32 m0, s35
	s_nop 0
	s_add_u32 s82, s4, s26
	s_addc_u32 s83, s5, s27
	s_nop 0
	global_load_lds_dwordx4 v212, s[82:83]
	s_waitcnt vmcnt(6)
	s_barrier
	v_mfma_f32_16x16x32_bf16 v[32:35], v[176:179], v[144:147], v[32:35]
	v_mfma_f32_16x16x32_bf16 v[36:39], v[180:183], v[144:147], v[36:39]
	v_mfma_f32_16x16x32_bf16 v[40:43], v[176:179], v[148:151], v[40:43]
	v_mfma_f32_16x16x32_bf16 v[44:47], v[180:183], v[148:151], v[44:47]
	v_mfma_f32_16x16x32_bf16 v[48:51], v[176:179], v[160:163], v[48:51]
	v_mfma_f32_16x16x32_bf16 v[52:55], v[180:183], v[160:163], v[52:55]
	v_mfma_f32_16x16x32_bf16 v[60:63], v[176:179], v[164:167], v[60:63]
	v_mfma_f32_16x16x32_bf16 v[64:67], v[180:183], v[164:167], v[64:67]
	v_mfma_f32_16x16x32_bf16 v[32:35], v[184:187], v[152:155], v[32:35]
	v_mfma_f32_16x16x32_bf16 v[36:39], v[188:191], v[152:155], v[36:39]
	v_mfma_f32_16x16x32_bf16 v[40:43], v[184:187], v[156:159], v[40:43]
	v_mfma_f32_16x16x32_bf16 v[44:47], v[188:191], v[156:159], v[44:47]
	v_mfma_f32_16x16x32_bf16 v[48:51], v[184:187], v[168:171], v[48:51]
	v_mfma_f32_16x16x32_bf16 v[52:55], v[188:191], v[168:171], v[52:55]
	v_mfma_f32_16x16x32_bf16 v[60:63], v[184:187], v[172:175], v[60:63]
	v_mfma_f32_16x16x32_bf16 v[64:67], v[188:191], v[172:175], v[64:67]
	s_barrier
	ds_read_b128 v[128:131], v228
	ds_read_b128 v[132:135], v228 offset:2048
	ds_read_b128 v[136:139], v229
	ds_read_b128 v[140:143], v229 offset:2048
	s_mov_b32 m0, s42
	ds_read_b128 v[144:147], v224 offset:32768
	ds_read_b128 v[148:151], v224 offset:34816
	ds_read_b128 v[152:155], v225 offset:32768
	ds_read_b128 v[156:159], v225 offset:34816
	ds_read_b128 v[160:163], v224 offset:36864
	ds_read_b128 v[164:167], v224 offset:38912
	ds_read_b128 v[168:171], v225 offset:36864
	ds_read_b128 v[172:175], v225 offset:38912
	s_add_u32 s82, s38, 0x80100
	s_addc_u32 s83, s39, 0x0
	s_nop 0
	global_load_lds_dwordx4 v212, s[82:83]
	s_mov_b32 m0, s43
	s_nop 0
	s_add_u32 s82, s38, 0xc0100
	s_addc_u32 s83, s39, 0x0
	s_nop 0
	global_load_lds_dwordx4 v212, s[82:83]
	s_waitcnt lgkmcnt(8)
	s_barrier
	s_waitcnt lgkmcnt(0)
	v_mfma_f32_16x16x32_bf16 v[124:127], v[128:131], v[144:147], v[124:127]
	v_mfma_f32_16x16x32_bf16 v[120:123], v[132:135], v[144:147], v[120:123]
	v_mfma_f32_16x16x32_bf16 v[116:119], v[128:131], v[148:151], v[116:119]
	v_mfma_f32_16x16x32_bf16 v[112:115], v[132:135], v[148:151], v[112:115]
	v_mfma_f32_16x16x32_bf16 v[108:111], v[128:131], v[160:163], v[108:111]
	v_mfma_f32_16x16x32_bf16 v[104:107], v[132:135], v[160:163], v[104:107]
	v_mfma_f32_16x16x32_bf16 v[100:103], v[128:131], v[164:167], v[100:103]
	v_mfma_f32_16x16x32_bf16 v[96:99], v[132:135], v[164:167], v[96:99]
	v_mfma_f32_16x16x32_bf16 v[124:127], v[136:139], v[152:155], v[124:127]
	v_mfma_f32_16x16x32_bf16 v[120:123], v[140:143], v[152:155], v[120:123]
	v_mfma_f32_16x16x32_bf16 v[116:119], v[136:139], v[156:159], v[116:119]
	v_mfma_f32_16x16x32_bf16 v[112:115], v[140:143], v[156:159], v[112:115]
	v_mfma_f32_16x16x32_bf16 v[108:111], v[136:139], v[168:171], v[108:111]
	v_mfma_f32_16x16x32_bf16 v[104:107], v[140:143], v[168:171], v[104:107]
	v_mfma_f32_16x16x32_bf16 v[100:103], v[136:139], v[172:175], v[100:103]
	v_mfma_f32_16x16x32_bf16 v[96:99], v[140:143], v[172:175], v[96:99]
	s_barrier
	s_mov_b32 m0, s44
	ds_read_b128 v[176:179], v232
	ds_read_b128 v[180:183], v232 offset:2048
	ds_read_b128 v[184:187], v233
	ds_read_b128 v[188:191], v233 offset:2048
	s_add_u32 s82, s40, s28
	s_addc_u32 s83, s41, s29
	s_nop 0
	global_load_lds_dwordx4 v212, s[82:83]
	s_mov_b32 m0, s45
	s_nop 0
	s_add_u32 s82, s40, s36
	s_addc_u32 s83, s41, s37
	s_nop 0
	global_load_lds_dwordx4 v212, s[82:83]
	s_barrier
	s_waitcnt lgkmcnt(0)
	v_mfma_f32_16x16x32_bf16 v[92:95], v[176:179], v[144:147], v[92:95]
	v_mfma_f32_16x16x32_bf16 v[88:91], v[180:183], v[144:147], v[88:91]
	v_mfma_f32_16x16x32_bf16 v[84:87], v[176:179], v[148:151], v[84:87]
	v_mfma_f32_16x16x32_bf16 v[80:83], v[180:183], v[148:151], v[80:83]
	v_mfma_f32_16x16x32_bf16 v[76:79], v[176:179], v[160:163], v[76:79]
	v_mfma_f32_16x16x32_bf16 v[72:75], v[180:183], v[160:163], v[72:75]
	v_mfma_f32_16x16x32_bf16 v[68:71], v[176:179], v[164:167], v[68:71]
	v_mfma_f32_16x16x32_bf16 v[56:59], v[180:183], v[164:167], v[56:59]
	v_mfma_f32_16x16x32_bf16 v[92:95], v[184:187], v[152:155], v[92:95]
	v_mfma_f32_16x16x32_bf16 v[88:91], v[188:191], v[152:155], v[88:91]
	v_mfma_f32_16x16x32_bf16 v[84:87], v[184:187], v[156:159], v[84:87]
	v_mfma_f32_16x16x32_bf16 v[80:83], v[188:191], v[156:159], v[80:83]
	v_mfma_f32_16x16x32_bf16 v[76:79], v[184:187], v[168:171], v[76:79]
	v_mfma_f32_16x16x32_bf16 v[72:75], v[188:191], v[168:171], v[72:75]
	v_mfma_f32_16x16x32_bf16 v[68:71], v[184:187], v[172:175], v[68:71]
	v_mfma_f32_16x16x32_bf16 v[56:59], v[188:191], v[172:175], v[56:59]
	s_barrier
	s_mov_b32 m0, s46
	ds_read_b128 v[144:147], v224 offset:49152
	ds_read_b128 v[148:151], v224 offset:51200
	ds_read_b128 v[152:155], v225 offset:49152
	ds_read_b128 v[156:159], v225 offset:51200
	ds_read_b128 v[160:163], v224 offset:53248
	ds_read_b128 v[164:167], v224 offset:55296
	ds_read_b128 v[168:171], v225 offset:53248
	ds_read_b128 v[172:175], v225 offset:55296
	s_add_u32 s82, s38, s28
	s_addc_u32 s83, s39, s29
	s_nop 0
	global_load_lds_dwordx4 v212, s[82:83]
	s_mov_b32 m0, s47
	s_nop 0
	s_add_u32 s82, s38, s36
	s_addc_u32 s83, s39, s37
	s_nop 0
	global_load_lds_dwordx4 v212, s[82:83]
	s_barrier
	s_waitcnt lgkmcnt(0)
	v_mfma_f32_16x16x32_bf16 v[28:31], v[128:131], v[144:147], v[28:31]
	v_mfma_f32_16x16x32_bf16 v[24:27], v[132:135], v[144:147], v[24:27]
	v_mfma_f32_16x16x32_bf16 v[20:23], v[128:131], v[148:151], v[20:23]
	v_mfma_f32_16x16x32_bf16 v[16:19], v[132:135], v[148:151], v[16:19]
	v_mfma_f32_16x16x32_bf16 v[12:15], v[128:131], v[160:163], v[12:15]
	v_mfma_f32_16x16x32_bf16 v[8:11], v[132:135], v[160:163], v[8:11]
	v_mfma_f32_16x16x32_bf16 v[4:7], v[128:131], v[164:167], v[4:7]
	v_mfma_f32_16x16x32_bf16 v[0:3], v[132:135], v[164:167], v[0:3]
	v_mfma_f32_16x16x32_bf16 v[28:31], v[136:139], v[152:155], v[28:31]
	v_mfma_f32_16x16x32_bf16 v[24:27], v[140:143], v[152:155], v[24:27]
	v_mfma_f32_16x16x32_bf16 v[20:23], v[136:139], v[156:159], v[20:23]
	v_mfma_f32_16x16x32_bf16 v[16:19], v[140:143], v[156:159], v[16:19]
	v_mfma_f32_16x16x32_bf16 v[12:15], v[136:139], v[168:171], v[12:15]
	v_mfma_f32_16x16x32_bf16 v[8:11], v[140:143], v[168:171], v[8:11]
	v_mfma_f32_16x16x32_bf16 v[4:7], v[136:139], v[172:175], v[4:7]
	v_mfma_f32_16x16x32_bf16 v[0:3], v[140:143], v[172:175], v[0:3]
	s_barrier
	s_mov_b32 m0, s48
	s_add_u32 s82, s4, s28
	s_addc_u32 s83, s5, s29
	s_nop 0
	global_load_lds_dwordx4 v212, s[82:83]
	s_mov_b32 m0, s49
	s_nop 0
	s_add_u32 s82, s4, s36
	s_addc_u32 s83, s5, s37
	s_nop 0
	global_load_lds_dwordx4 v212, s[82:83]
	s_waitcnt vmcnt(6)
	s_barrier
	v_mfma_f32_16x16x32_bf16 v[32:35], v[176:179], v[144:147], v[32:35]
	v_mfma_f32_16x16x32_bf16 v[36:39], v[180:183], v[144:147], v[36:39]
	v_mfma_f32_16x16x32_bf16 v[40:43], v[176:179], v[148:151], v[40:43]
	v_mfma_f32_16x16x32_bf16 v[44:47], v[180:183], v[148:151], v[44:47]
	v_mfma_f32_16x16x32_bf16 v[48:51], v[176:179], v[160:163], v[48:51]
	v_mfma_f32_16x16x32_bf16 v[52:55], v[180:183], v[160:163], v[52:55]
	v_mfma_f32_16x16x32_bf16 v[60:63], v[176:179], v[164:167], v[60:63]
	v_mfma_f32_16x16x32_bf16 v[64:67], v[180:183], v[164:167], v[64:67]
	v_mfma_f32_16x16x32_bf16 v[32:35], v[184:187], v[152:155], v[32:35]
	v_mfma_f32_16x16x32_bf16 v[36:39], v[188:191], v[152:155], v[36:39]
	v_mfma_f32_16x16x32_bf16 v[40:43], v[184:187], v[156:159], v[40:43]
	v_mfma_f32_16x16x32_bf16 v[44:47], v[188:191], v[156:159], v[44:47]
	v_mfma_f32_16x16x32_bf16 v[48:51], v[184:187], v[168:171], v[48:51]
	v_mfma_f32_16x16x32_bf16 v[52:55], v[188:191], v[168:171], v[52:55]
	v_mfma_f32_16x16x32_bf16 v[60:63], v[184:187], v[172:175], v[60:63]
	v_mfma_f32_16x16x32_bf16 v[64:67], v[188:191], v[172:175], v[64:67]
	s_barrier
	s_add_i32 s81, s81, 2
	s_add_u32 s40, s40, 0x100
	s_addc_u32 s41, s41, 0
	s_add_u32 s38, s38, 0x100
	s_addc_u32 s39, s39, 0
	s_add_u32 s4, s4, 0x100
	s_addc_u32 s5, s5, 0
	s_cmp_lt_u32 s81, 28
	s_cbranch_scc1 .LBB0_89
; #define LDA(dst,b,h) _Pragma("unroll") for(int m=0;m<4;++m) _Pragma("unroll") for(int k=0;k<2;++k) \
;     dst[m][k]=*reinterpret_cast<const bf16x8*>(SA(b,h)+(wr*64+m*16)*128+koff[k])
; #define LDB(dst,b,h) _Pragma("unroll") for(int n=0;n<2;++n) _Pragma("unroll") for(int k=0;k<2;++k) \
;     dst[n][k]=*reinterpret_cast<const bf16x8*>(SB(b,h)+(wc*32+n*16)*128+koff[k])
; #define MMA(ai,bj,Af,Bf) do{__builtin_amdgcn_s_setprio(1); \
;     _Pragma("unroll") for(int m=0;m<4;++m) _Pragma("unroll") for(int n=0;n<2;++n) _Pragma("unroll") for(int k=0;k<2;++k) \
;       acc[ai][bj][m][n]=__builtin_amdgcn_mfma_f32_16x16x32_bf16(Bf[n][k],Af[m][k],acc[ai][bj][m][n],0,0,0); \
;     __builtin_amdgcn_s_setprio(0);}while(0)
; #define WAIT_L(n) asm volatile("s_waitcnt lgkmcnt(" #n ")":::"memory")
; #define BAR __builtin_amdgcn_s_barrier()
; #define SCHED __builtin_amdgcn_sched_barrier(0)
; #define STAGE_A(b,h,kt) do{ unsigned char* _d = SA(b,h) + wbase; \
;     if constexpr (BLK) { const char* _s = baseA + ((size_t)(h)*(K/64) + (kt)) * 16384; GLDS(_s + voa, _d); GLDS(_s + 8192 + voa, _d + 8192); } \
;     else { const char* _s = baseA + ((size_t)(h)*128*K + (kt)*64) * 2; GLDS(_s + voa, _d); GLDS(_s + (size_t)128*K + voa, _d + 8192); } }while(0)
; template <int K, int EPI, bool MIX = false>
; __device__ __forceinline__ void gemm_phase(const Params& p, const u16* __restrict__ A, const u16* __restrict__ Bt,
;                            const float* __restrict__ rs_in, float* __restrict__ ssq_out, float alpha, bool rev = false) {
;     ...
;         for (int m = 0; m < 4; ++m) rsq[ai][m] = rsrc[cpm * 256 + ai * 128 + wr * 64 + m * 16 + fr_p];
;     }
;     ++it;
;     id = item_id(it);
;     const bool more = id < ntiles;
;     if (rev) id = ntiles - 1 - id;
;     {
;       LDB(B0,0,0); SCHED; LDA(At,0,0); STAGE_A(1,1,nt-1);
;       WAIT_L(8); BAR; WAIT_L(0); MMA(0,0,At,B0); BAR; SCHED;
;       if (more) SETUP_TILE();
	v_mov_b32_e32 v128, v221
	s_lshl_b32 s41, s23, 8
	s_add_i32 s41, s41, s50
	v_add_u32_e32 v128, s41, v128
	v_readlane_b32 s52, v254, 32
	v_ashrrev_i32_e32 v129, 31, v128
	v_readlane_b32 s62, v254, 42
	v_readlane_b32 s63, v254, 43
	s_add_i32 s79, s79, 1
	s_mul_i32 s4, s79, s76
	v_lshl_add_u64 v[128:129], v[128:129], 2, s[62:63]
	global_load_dword v210, v[128:129], off
	global_load_dword v241, v[128:129], off offset:64
	global_load_dword v240, v[128:129], off offset:128
	global_load_dword v239, v[128:129], off offset:192
	global_load_dword v238, v[128:129], off offset:512
	global_load_dword v237, v[128:129], off offset:576
	global_load_dword v236, v[128:129], off offset:640
	global_load_dword v235, v[128:129], off offset:704
	ds_read_b128 v[144:147], v222
	ds_read_b128 v[148:151], v222 offset:2048
	ds_read_b128 v[156:159], v223
	ds_read_b128 v[152:155], v223 offset:2048
	s_add_i32 s4, s4, s77
	v_readlane_b32 s53, v254, 33
	v_readlane_b32 s54, v254, 34
	v_readlane_b32 s55, v254, 35
	v_readlane_b32 s56, v254, 36
	v_readlane_b32 s57, v254, 37
	v_readlane_b32 s58, v254, 38
	v_readlane_b32 s59, v254, 39
	v_readlane_b32 s60, v254, 40
	v_readlane_b32 s61, v254, 41
	v_readlane_b32 s64, v254, 44
	v_readlane_b32 s65, v254, 45
	v_readlane_b32 s66, v254, 46
	v_readlane_b32 s67, v254, 47
	v_lshl_add_u64 v[128:129], s[0:1], 0, v[208:209]
	s_mov_b64 s[38:39], 0x80f80
	s_mov_b32 m0, s74
	v_lshl_add_u64 v[130:131], v[128:129], 0, s[38:39]
	s_mov_b64 s[38:39], 0xc0f80
	ds_read_b128 v[160:163], v224
	ds_read_b128 v[164:167], v224 offset:2048
	ds_read_b128 v[188:191], v225
	ds_read_b128 v[180:183], v225 offset:2048
	ds_read_b128 v[168:171], v224 offset:4096
	ds_read_b128 v[172:175], v224 offset:6144
	ds_read_b128 v[184:187], v225 offset:4096
	ds_read_b128 v[176:179], v225 offset:6144
	global_load_lds_dwordx4 v[130:131], off
	v_lshl_add_u64 v[128:129], v[128:129], 0, s[38:39]
	s_mov_b32 m0, s75
	s_nop 0
	global_load_lds_dwordx4 v[128:129], off
	s_waitcnt lgkmcnt(8)
	s_barrier
	s_waitcnt lgkmcnt(0)
	v_mfma_f32_16x16x32_bf16 v[124:127], v[144:147], v[160:163], v[124:127]
	s_cmpk_lt_i32 s4, 0x2100
	s_cselect_b64 s[38:39], -1, 0
	s_cmpk_gt_i32 s4, 0x20ff
	v_mfma_f32_16x16x32_bf16 v[120:123], v[148:151], v[160:163], v[120:123]
	v_mfma_f32_16x16x32_bf16 v[116:119], v[144:147], v[164:167], v[116:119]
	v_mfma_f32_16x16x32_bf16 v[112:115], v[148:151], v[164:167], v[112:115]
	v_mfma_f32_16x16x32_bf16 v[108:111], v[144:147], v[168:171], v[108:111]
	v_mfma_f32_16x16x32_bf16 v[104:107], v[148:151], v[168:171], v[104:107]
	v_mfma_f32_16x16x32_bf16 v[100:103], v[144:147], v[172:175], v[100:103]
	v_mfma_f32_16x16x32_bf16 v[96:99], v[148:151], v[172:175], v[96:99]
	v_mfma_f32_16x16x32_bf16 v[124:127], v[156:159], v[188:191], v[124:127]
	v_mfma_f32_16x16x32_bf16 v[128:131], v[152:155], v[188:191], v[120:123]
	v_mfma_f32_16x16x32_bf16 v[116:119], v[156:159], v[180:183], v[116:119]
	v_mfma_f32_16x16x32_bf16 v[132:135], v[152:155], v[180:183], v[112:115]
	v_mfma_f32_16x16x32_bf16 v[108:111], v[156:159], v[184:187], v[108:111]
	v_mfma_f32_16x16x32_bf16 v[136:139], v[152:155], v[184:187], v[104:107]
	v_mfma_f32_16x16x32_bf16 v[100:103], v[156:159], v[176:179], v[100:103]
	v_mfma_f32_16x16x32_bf16 v[140:143], v[152:155], v[176:179], v[96:99]
	s_barrier
	s_mov_b32 s40, s80
	s_cbranch_scc1 .LBB0_92
	s_mul_hi_i32 s0, s4, 0x2e8ba2e9
	s_lshr_b32 s1, s0, 31
	s_ashr_i32 s0, s0, 6
	s_add_i32 s0, s0, s1
	s_lshl_b32 s1, s0, 3
	s_mulk_i32 s0, 0xfea0
	s_add_i32 s0, s0, s4
	s_and_b32 s4, s4, 7
	s_or_b32 s23, s1, s4
	s_ashr_i32 s40, s0, 3
	s_lshl_b32 s0, s23, 8
	s_ashr_i32 s1, s0, 31
	s_lshl_b64 s[0:1], s[0:1], 12
	s_add_u32 s0, s90, s0
	s_addc_u32 s1, s91, s1
	s_lshl_b32 s4, s40, 7
	s_ashr_i32 s5, s4, 31
	v_readlane_b32 s52, v254, 16
	s_lshl_b64 s[4:5], s[4:5], 12
	v_readlane_b32 s62, v254, 26
	v_readlane_b32 s63, v254, 27
	s_add_u32 s6, s62, s4
	s_addc_u32 s7, s63, s5
	s_add_u32 s8, s6, 0x1600000
	v_readlane_b32 s76, v255, 6
	s_addc_u32 s9, s7, 0
	v_readlane_b32 s53, v254, 17
	v_readlane_b32 s54, v254, 18
	v_readlane_b32 s55, v254, 19
	v_readlane_b32 s56, v254, 20
	v_readlane_b32 s57, v254, 21
	v_readlane_b32 s58, v254, 22
	v_readlane_b32 s59, v254, 23
	v_readlane_b32 s60, v254, 24
	v_readlane_b32 s61, v254, 25
	v_readlane_b32 s64, v254, 28
	v_readlane_b32 s65, v254, 29
	v_readlane_b32 s66, v254, 30
	v_readlane_b32 s67, v254, 31

.Llate_p2_done:
.LBB0_128:
	ds_read_b128 v[128:131], v219
	ds_read_b128 v[132:135], v219 offset:2048
	ds_read_b128 v[136:139], v220
	ds_read_b128 v[140:143], v220 offset:2048
	s_mov_b32 m0, s74
	ds_read_b128 v[144:147], v221
	ds_read_b128 v[148:151], v221 offset:2048
	ds_read_b128 v[152:155], v222
	ds_read_b128 v[156:159], v222 offset:2048
	ds_read_b128 v[160:163], v221 offset:4096
	ds_read_b128 v[164:167], v221 offset:6144
	ds_read_b128 v[168:171], v222 offset:4096
	ds_read_b128 v[172:175], v222 offset:6144
	s_add_u32 s96, s46, s18
	s_addc_u32 s97, s47, s19
	s_nop 0
	global_load_lds_dwordx4 v210, s[96:97]
	s_mov_b32 m0, s75
	s_nop 0
	s_add_u32 s96, s46, s20
	s_addc_u32 s97, s47, s21
	s_nop 0
	global_load_lds_dwordx4 v210, s[96:97]
	s_waitcnt lgkmcnt(8)
	s_barrier
	s_waitcnt lgkmcnt(0)
	v_mfma_f32_16x16x32_bf16 v[124:127], v[128:131], v[144:147], v[124:127]
	v_mfma_f32_16x16x32_bf16 v[120:123], v[132:135], v[144:147], v[120:123]
	v_mfma_f32_16x16x32_bf16 v[116:119], v[128:131], v[148:151], v[116:119]
	v_mfma_f32_16x16x32_bf16 v[112:115], v[132:135], v[148:151], v[112:115]
	v_mfma_f32_16x16x32_bf16 v[108:111], v[128:131], v[160:163], v[108:111]
	v_mfma_f32_16x16x32_bf16 v[104:107], v[132:135], v[160:163], v[104:107]
	v_mfma_f32_16x16x32_bf16 v[100:103], v[128:131], v[164:167], v[100:103]
	v_mfma_f32_16x16x32_bf16 v[96:99], v[132:135], v[164:167], v[96:99]
	v_mfma_f32_16x16x32_bf16 v[124:127], v[136:139], v[152:155], v[124:127]
	v_mfma_f32_16x16x32_bf16 v[120:123], v[140:143], v[152:155], v[120:123]
	v_mfma_f32_16x16x32_bf16 v[116:119], v[136:139], v[156:159], v[116:119]
	v_mfma_f32_16x16x32_bf16 v[112:115], v[140:143], v[156:159], v[112:115]
	v_mfma_f32_16x16x32_bf16 v[108:111], v[136:139], v[168:171], v[108:111]
	v_mfma_f32_16x16x32_bf16 v[104:107], v[140:143], v[168:171], v[104:107]
	v_mfma_f32_16x16x32_bf16 v[100:103], v[136:139], v[172:175], v[100:103]
	v_mfma_f32_16x16x32_bf16 v[96:99], v[140:143], v[172:175], v[96:99]
	s_barrier
	s_mov_b32 m0, s23
	ds_read_b128 v[176:179], v223
	ds_read_b128 v[180:183], v223 offset:2048
	ds_read_b128 v[184:187], v224
	ds_read_b128 v[188:191], v224 offset:2048
	s_add_u32 s96, s62, s28
	s_addc_u32 s97, s63, s29
	s_nop 0
	global_load_lds_dwordx4 v210, s[96:97]
	s_mov_b32 m0, s30
	s_nop 0
	s_add_u32 s96, s62, s36
	s_addc_u32 s97, s63, s37
	s_nop 0
	global_load_lds_dwordx4 v210, s[96:97]
	s_barrier
	s_waitcnt lgkmcnt(0)
	v_mfma_f32_16x16x32_bf16 v[92:95], v[176:179], v[144:147], v[92:95]
	v_mfma_f32_16x16x32_bf16 v[88:91], v[180:183], v[144:147], v[88:91]
	v_mfma_f32_16x16x32_bf16 v[84:87], v[176:179], v[148:151], v[84:87]
	v_mfma_f32_16x16x32_bf16 v[80:83], v[180:183], v[148:151], v[80:83]
	v_mfma_f32_16x16x32_bf16 v[76:79], v[176:179], v[160:163], v[76:79]
	v_mfma_f32_16x16x32_bf16 v[72:75], v[180:183], v[160:163], v[72:75]
	v_mfma_f32_16x16x32_bf16 v[68:71], v[176:179], v[164:167], v[68:71]
	v_mfma_f32_16x16x32_bf16 v[64:67], v[180:183], v[164:167], v[64:67]
	v_mfma_f32_16x16x32_bf16 v[92:95], v[184:187], v[152:155], v[92:95]
	v_mfma_f32_16x16x32_bf16 v[88:91], v[188:191], v[152:155], v[88:91]
	v_mfma_f32_16x16x32_bf16 v[84:87], v[184:187], v[156:159], v[84:87]
	v_mfma_f32_16x16x32_bf16 v[80:83], v[188:191], v[156:159], v[80:83]
	v_mfma_f32_16x16x32_bf16 v[76:79], v[184:187], v[168:171], v[76:79]
	v_mfma_f32_16x16x32_bf16 v[72:75], v[188:191], v[168:171], v[72:75]
	v_mfma_f32_16x16x32_bf16 v[68:71], v[184:187], v[172:175], v[68:71]
	v_mfma_f32_16x16x32_bf16 v[64:67], v[188:191], v[172:175], v[64:67]
	s_barrier
	s_mov_b32 m0, s22
	ds_read_b128 v[144:147], v221 offset:16384
	ds_read_b128 v[148:151], v221 offset:18432
	ds_read_b128 v[152:155], v222 offset:16384
	ds_read_b128 v[156:159], v222 offset:18432
	ds_read_b128 v[160:163], v221 offset:20480
	ds_read_b128 v[164:167], v221 offset:22528
	ds_read_b128 v[168:171], v222 offset:20480
	ds_read_b128 v[172:175], v222 offset:22528
	s_add_u32 s96, s46, s28
	s_addc_u32 s97, s47, s29
	s_nop 0
	global_load_lds_dwordx4 v210, s[96:97]
	s_mov_b32 m0, s31
	s_nop 0
	s_add_u32 s96, s46, s36
	s_addc_u32 s97, s47, s37
	s_nop 0
	global_load_lds_dwordx4 v210, s[96:97]
	s_barrier
	s_waitcnt lgkmcnt(0)
	v_mfma_f32_16x16x32_bf16 v[60:63], v[128:131], v[144:147], v[60:63]
	v_mfma_f32_16x16x32_bf16 v[56:59], v[132:135], v[144:147], v[56:59]
	v_mfma_f32_16x16x32_bf16 v[52:55], v[128:131], v[148:151], v[52:55]
	v_mfma_f32_16x16x32_bf16 v[48:51], v[132:135], v[148:151], v[48:51]
	v_mfma_f32_16x16x32_bf16 v[44:47], v[128:131], v[160:163], v[44:47]
	v_mfma_f32_16x16x32_bf16 v[40:43], v[132:135], v[160:163], v[40:43]
	v_mfma_f32_16x16x32_bf16 v[36:39], v[128:131], v[164:167], v[36:39]
	v_mfma_f32_16x16x32_bf16 v[32:35], v[132:135], v[164:167], v[32:35]
	v_mfma_f32_16x16x32_bf16 v[60:63], v[136:139], v[152:155], v[60:63]
	v_mfma_f32_16x16x32_bf16 v[56:59], v[140:143], v[152:155], v[56:59]
	v_mfma_f32_16x16x32_bf16 v[52:55], v[136:139], v[156:159], v[52:55]
	v_mfma_f32_16x16x32_bf16 v[48:51], v[140:143], v[156:159], v[48:51]
	v_mfma_f32_16x16x32_bf16 v[44:47], v[136:139], v[168:171], v[44:47]
	v_mfma_f32_16x16x32_bf16 v[40:43], v[140:143], v[168:171], v[40:43]
	v_mfma_f32_16x16x32_bf16 v[36:39], v[136:139], v[172:175], v[36:39]
	v_mfma_f32_16x16x32_bf16 v[32:35], v[140:143], v[172:175], v[32:35]
	s_barrier
	s_mov_b32 m0, s33
	s_add_u32 s96, s4, s28
	s_addc_u32 s97, s5, s29
	s_nop 0
	global_load_lds_dwordx4 v210, s[96:97]
	s_mov_b32 m0, s34
	s_nop 0
	s_add_u32 s96, s4, s36
	s_addc_u32 s97, s5, s37
	s_nop 0
	global_load_lds_dwordx4 v210, s[96:97]
	s_waitcnt vmcnt(6)
	s_barrier
	v_mfma_f32_16x16x32_bf16 v[28:31], v[176:179], v[144:147], v[28:31]
	v_mfma_f32_16x16x32_bf16 v[24:27], v[180:183], v[144:147], v[24:27]
	v_mfma_f32_16x16x32_bf16 v[20:23], v[176:179], v[148:151], v[20:23]
	v_mfma_f32_16x16x32_bf16 v[16:19], v[180:183], v[148:151], v[16:19]
	v_mfma_f32_16x16x32_bf16 v[12:15], v[176:179], v[160:163], v[12:15]
	v_mfma_f32_16x16x32_bf16 v[8:11], v[180:183], v[160:163], v[8:11]
	v_mfma_f32_16x16x32_bf16 v[4:7], v[176:179], v[164:167], v[4:7]
	v_mfma_f32_16x16x32_bf16 v[0:3], v[180:183], v[164:167], v[0:3]
	v_mfma_f32_16x16x32_bf16 v[28:31], v[184:187], v[152:155], v[28:31]
	v_mfma_f32_16x16x32_bf16 v[24:27], v[188:191], v[152:155], v[24:27]
	v_mfma_f32_16x16x32_bf16 v[20:23], v[184:187], v[156:159], v[20:23]
	v_mfma_f32_16x16x32_bf16 v[16:19], v[188:191], v[156:159], v[16:19]
	v_mfma_f32_16x16x32_bf16 v[12:15], v[184:187], v[168:171], v[12:15]
	v_mfma_f32_16x16x32_bf16 v[8:11], v[188:191], v[168:171], v[8:11]
	v_mfma_f32_16x16x32_bf16 v[4:7], v[184:187], v[172:175], v[4:7]
	v_mfma_f32_16x16x32_bf16 v[0:3], v[188:191], v[172:175], v[0:3]
	s_barrier
	ds_read_b128 v[128:131], v225
	ds_read_b128 v[132:135], v225 offset:2048
	ds_read_b128 v[136:139], v226
	ds_read_b128 v[140:143], v226 offset:2048
	s_mov_b32 m0, s35
	ds_read_b128 v[144:147], v221 offset:32768
	ds_read_b128 v[148:151], v221 offset:34816
	ds_read_b128 v[152:155], v222 offset:32768
	ds_read_b128 v[156:159], v222 offset:34816
	ds_read_b128 v[160:163], v221 offset:36864
	ds_read_b128 v[164:167], v221 offset:38912
	ds_read_b128 v[168:171], v222 offset:36864
	ds_read_b128 v[172:175], v222 offset:38912
	s_add_u32 s96, s46, 0x168000
	s_addc_u32 s97, s47, 0x0
	s_nop 0
	global_load_lds_dwordx4 v210, s[96:97]
	s_mov_b32 m0, s42
	s_nop 0
	s_add_u32 s96, s46, 0x16a000
	s_addc_u32 s97, s47, 0x0
	s_nop 0
	global_load_lds_dwordx4 v210, s[96:97]
	s_waitcnt lgkmcnt(8)
	s_barrier
	s_waitcnt lgkmcnt(0)
	v_mfma_f32_16x16x32_bf16 v[124:127], v[128:131], v[144:147], v[124:127]
	v_mfma_f32_16x16x32_bf16 v[120:123], v[132:135], v[144:147], v[120:123]
	v_mfma_f32_16x16x32_bf16 v[116:119], v[128:131], v[148:151], v[116:119]
	v_mfma_f32_16x16x32_bf16 v[112:115], v[132:135], v[148:151], v[112:115]
	v_mfma_f32_16x16x32_bf16 v[108:111], v[128:131], v[160:163], v[108:111]
	v_mfma_f32_16x16x32_bf16 v[104:107], v[132:135], v[160:163], v[104:107]
	v_mfma_f32_16x16x32_bf16 v[100:103], v[128:131], v[164:167], v[100:103]
	v_mfma_f32_16x16x32_bf16 v[96:99], v[132:135], v[164:167], v[96:99]
	v_mfma_f32_16x16x32_bf16 v[124:127], v[136:139], v[152:155], v[124:127]
	v_mfma_f32_16x16x32_bf16 v[120:123], v[140:143], v[152:155], v[120:123]
	v_mfma_f32_16x16x32_bf16 v[116:119], v[136:139], v[156:159], v[116:119]
	v_mfma_f32_16x16x32_bf16 v[112:115], v[140:143], v[156:159], v[112:115]
	v_mfma_f32_16x16x32_bf16 v[108:111], v[136:139], v[168:171], v[108:111]
	v_mfma_f32_16x16x32_bf16 v[104:107], v[140:143], v[168:171], v[104:107]
	v_mfma_f32_16x16x32_bf16 v[100:103], v[136:139], v[172:175], v[100:103]
	v_mfma_f32_16x16x32_bf16 v[96:99], v[140:143], v[172:175], v[96:99]
	s_barrier
	s_mov_b32 m0, s43
	ds_read_b128 v[176:179], v227
	ds_read_b128 v[180:183], v227 offset:2048
	ds_read_b128 v[184:187], v228
	ds_read_b128 v[188:191], v228 offset:2048
	s_add_u32 s96, s62, s38
	s_addc_u32 s97, s63, s39
	s_nop 0
	global_load_lds_dwordx4 v210, s[96:97]
	s_mov_b32 m0, s44
	s_nop 0
	s_add_u32 s96, s62, s40
	s_addc_u32 s97, s63, s41
	s_nop 0
	global_load_lds_dwordx4 v210, s[96:97]
	s_barrier
	s_waitcnt lgkmcnt(0)
	v_mfma_f32_16x16x32_bf16 v[92:95], v[176:179], v[144:147], v[92:95]
	v_mfma_f32_16x16x32_bf16 v[88:91], v[180:183], v[144:147], v[88:91]
	v_mfma_f32_16x16x32_bf16 v[84:87], v[176:179], v[148:151], v[84:87]
	v_mfma_f32_16x16x32_bf16 v[80:83], v[180:183], v[148:151], v[80:83]
	v_mfma_f32_16x16x32_bf16 v[76:79], v[176:179], v[160:163], v[76:79]
	v_mfma_f32_16x16x32_bf16 v[72:75], v[180:183], v[160:163], v[72:75]
	v_mfma_f32_16x16x32_bf16 v[68:71], v[176:179], v[164:167], v[68:71]
	v_mfma_f32_16x16x32_bf16 v[64:67], v[180:183], v[164:167], v[64:67]
	v_mfma_f32_16x16x32_bf16 v[92:95], v[184:187], v[152:155], v[92:95]
	v_mfma_f32_16x16x32_bf16 v[88:91], v[188:191], v[152:155], v[88:91]
	v_mfma_f32_16x16x32_bf16 v[84:87], v[184:187], v[156:159], v[84:87]
	v_mfma_f32_16x16x32_bf16 v[80:83], v[188:191], v[156:159], v[80:83]
	v_mfma_f32_16x16x32_bf16 v[76:79], v[184:187], v[168:171], v[76:79]
	v_mfma_f32_16x16x32_bf16 v[72:75], v[188:191], v[168:171], v[72:75]
	v_mfma_f32_16x16x32_bf16 v[68:71], v[184:187], v[172:175], v[68:71]
	v_mfma_f32_16x16x32_bf16 v[64:67], v[188:191], v[172:175], v[64:67]
	s_barrier
	s_mov_b32 m0, s45
	ds_read_b128 v[144:147], v221 offset:49152
	ds_read_b128 v[148:151], v221 offset:51200
	ds_read_b128 v[152:155], v222 offset:49152
	ds_read_b128 v[156:159], v222 offset:51200
	ds_read_b128 v[160:163], v221 offset:53248
	ds_read_b128 v[164:167], v221 offset:55296
	ds_read_b128 v[168:171], v222 offset:53248
	ds_read_b128 v[172:175], v222 offset:55296
	s_add_u32 s96, s46, s38
	s_addc_u32 s97, s47, s39
	s_nop 0
	global_load_lds_dwordx4 v210, s[96:97]
	s_mov_b32 m0, s48
	s_nop 0
	s_add_u32 s96, s46, s40
	s_addc_u32 s97, s47, s41
	s_nop 0
	global_load_lds_dwordx4 v210, s[96:97]
	s_barrier
; #define LDA(dst,b,h) _Pragma("unroll") for(int m=0;m<4;++m) _Pragma("unroll") for(int k=0;k<2;++k) \
;     dst[m][k]=*reinterpret_cast<const bf16x8*>(SA(b,h)+(wr*64+m*16)*128+koff[k])
; #define LDB(dst,b,h) _Pragma("unroll") for(int n=0;n<2;++n) _Pragma("unroll") for(int k=0;k<2;++k) \
;     dst[n][k]=*reinterpret_cast<const bf16x8*>(SB(b,h)+(wc*32+n*16)*128+koff[k])
; #define MMA(ai,bj,Af,Bf) do{__builtin_amdgcn_s_setprio(1); \
;     _Pragma("unroll") for(int m=0;m<4;++m) _Pragma("unroll") for(int n=0;n<2;++n) _Pragma("unroll") for(int k=0;k<2;++k) \
;       acc[ai][bj][m][n]=__builtin_amdgcn_mfma_f32_16x16x32_bf16(Bf[n][k],Af[m][k],acc[ai][bj][m][n],0,0,0); \
;     __builtin_amdgcn_s_setprio(0);}while(0)
; #define WAIT_L(n) asm volatile("s_waitcnt lgkmcnt(" #n ")":::"memory")
; #define BAR __builtin_amdgcn_s_barrier()
; #define SCHED __builtin_amdgcn_sched_barrier(0)
; #define STAGE_A(b,h,kt) do{ unsigned char* _d = SA(b,h) + wbase; \
;     if constexpr (BLK) { const char* _s = baseA + ((size_t)(h)*(K/64) + (kt)) * 16384; GLDS(_s + voa, _d); GLDS(_s + 8192 + voa, _d + 8192); } \
;     else { const char* _s = baseA + ((size_t)(h)*128*K + (kt)*64) * 2; GLDS(_s + voa, _d); GLDS(_s + (size_t)128*K + voa, _d + 8192); } }while(0)
; template <int K, int EPI, bool MIX = false>
; __device__ __forceinline__ void gemm_phase(const Params& p, const u16* __restrict__ A, const u16* __restrict__ Bt,
;                            const float* __restrict__ rs_in, float* __restrict__ ssq_out, float alpha, bool rev = false) {
;     ...
;     ++it;
;     id = item_id(it);
;     const bool more = id < ntiles;
;     if (rev) id = ntiles - 1 - id;
;     {
;       LDB(B0,0,0); SCHED; LDA(At,0,0); STAGE_A(1,1,nt-1);
;       WAIT_L(8); BAR; WAIT_L(0); MMA(0,0,At,B0); BAR; SCHED;
;       if (more) SETUP_TILE();
	s_waitcnt lgkmcnt(0)
	v_mfma_f32_16x16x32_bf16 v[60:63], v[128:131], v[144:147], v[60:63]
	v_mfma_f32_16x16x32_bf16 v[56:59], v[132:135], v[144:147], v[56:59]
	v_mfma_f32_16x16x32_bf16 v[52:55], v[128:131], v[148:151], v[52:55]
	v_mfma_f32_16x16x32_bf16 v[48:51], v[132:135], v[148:151], v[48:51]
	v_mfma_f32_16x16x32_bf16 v[44:47], v[128:131], v[160:163], v[44:47]
	v_mfma_f32_16x16x32_bf16 v[40:43], v[132:135], v[160:163], v[40:43]
	v_mfma_f32_16x16x32_bf16 v[36:39], v[128:131], v[164:167], v[36:39]
	v_mfma_f32_16x16x32_bf16 v[32:35], v[132:135], v[164:167], v[32:35]
	v_mfma_f32_16x16x32_bf16 v[60:63], v[136:139], v[152:155], v[60:63]
	v_mfma_f32_16x16x32_bf16 v[56:59], v[140:143], v[152:155], v[56:59]
	v_mfma_f32_16x16x32_bf16 v[52:55], v[136:139], v[156:159], v[52:55]
	v_mfma_f32_16x16x32_bf16 v[48:51], v[140:143], v[156:159], v[48:51]
	v_mfma_f32_16x16x32_bf16 v[44:47], v[136:139], v[168:171], v[44:47]
	v_mfma_f32_16x16x32_bf16 v[40:43], v[140:143], v[168:171], v[40:43]
	v_mfma_f32_16x16x32_bf16 v[36:39], v[136:139], v[172:175], v[36:39]
	v_mfma_f32_16x16x32_bf16 v[32:35], v[140:143], v[172:175], v[32:35]
	s_barrier
	s_mov_b32 m0, s49
	s_add_u32 s96, s4, s38
	s_addc_u32 s97, s5, s39
	s_nop 0
	global_load_lds_dwordx4 v210, s[96:97]
	s_mov_b32 m0, s50
	s_nop 0
	s_add_u32 s96, s4, s40
	s_addc_u32 s97, s5, s41
	s_nop 0
	global_load_lds_dwordx4 v210, s[96:97]
	s_waitcnt vmcnt(6)
	s_barrier
	v_mfma_f32_16x16x32_bf16 v[28:31], v[176:179], v[144:147], v[28:31]
	v_mfma_f32_16x16x32_bf16 v[24:27], v[180:183], v[144:147], v[24:27]
	v_mfma_f32_16x16x32_bf16 v[20:23], v[176:179], v[148:151], v[20:23]
	v_mfma_f32_16x16x32_bf16 v[16:19], v[180:183], v[148:151], v[16:19]
	v_mfma_f32_16x16x32_bf16 v[12:15], v[176:179], v[160:163], v[12:15]
	v_mfma_f32_16x16x32_bf16 v[8:11], v[180:183], v[160:163], v[8:11]
	v_mfma_f32_16x16x32_bf16 v[4:7], v[176:179], v[164:167], v[4:7]
	v_mfma_f32_16x16x32_bf16 v[0:3], v[180:183], v[164:167], v[0:3]
	v_mfma_f32_16x16x32_bf16 v[28:31], v[184:187], v[152:155], v[28:31]
	v_mfma_f32_16x16x32_bf16 v[24:27], v[188:191], v[152:155], v[24:27]
	v_mfma_f32_16x16x32_bf16 v[20:23], v[184:187], v[156:159], v[20:23]
	v_mfma_f32_16x16x32_bf16 v[16:19], v[188:191], v[156:159], v[16:19]
	v_mfma_f32_16x16x32_bf16 v[12:15], v[184:187], v[168:171], v[12:15]
	v_mfma_f32_16x16x32_bf16 v[8:11], v[188:191], v[168:171], v[8:11]
	v_mfma_f32_16x16x32_bf16 v[4:7], v[184:187], v[172:175], v[4:7]
	v_mfma_f32_16x16x32_bf16 v[0:3], v[188:191], v[172:175], v[0:3]
	s_barrier
	s_add_i32 s79, s79, 2
	s_add_u32 s62, s62, 0x8000
	s_addc_u32 s63, s63, 0
	s_add_u32 s46, s46, 0x8000
	s_addc_u32 s47, s47, 0
	s_add_u32 s4, s4, 0x8000
	s_addc_u32 s5, s5, 0
	s_cmpk_lt_u32 s79, 0x54
	s_cbranch_scc1 .LBB0_128
	ds_read_b128 v[136:139], v219
	ds_read_b128 v[140:143], v219 offset:2048
	ds_read_b128 v[148:151], v220
	ds_read_b128 v[144:147], v220 offset:2048
	s_add_i32 s78, s78, 1
	s_mul_i32 s4, s78, s76
	s_add_i32 s4, s4, s77
	s_cmpk_lt_i32 s4, 0x600
	s_cselect_b64 s[46:47], -1, 0
	s_cmpk_gt_i32 s4, 0x5ff
	v_lshl_add_u64 v[128:129], s[2:3], 0, v[208:209]
	s_mov_b64 s[62:63], 0x2bc000
	s_mov_b32 m0, s74
	v_lshl_add_u64 v[130:131], v[128:129], 0, s[62:63]
	s_mov_b64 s[62:63], 0x2be000
	ds_read_b128 v[156:159], v221
	ds_read_b128 v[160:163], v221 offset:2048
	ds_read_b128 v[184:187], v222
	ds_read_b128 v[176:179], v222 offset:2048
	ds_read_b128 v[164:167], v221 offset:4096
	ds_read_b128 v[168:171], v221 offset:6144
	ds_read_b128 v[180:183], v222 offset:4096
	ds_read_b128 v[172:175], v222 offset:6144
	global_load_lds_dwordx4 v[130:131], off
	v_lshl_add_u64 v[128:129], v[128:129], 0, s[62:63]
	s_mov_b32 m0, s75
	s_nop 0
	global_load_lds_dwordx4 v[128:129], off
	s_waitcnt lgkmcnt(8)
	s_barrier
	s_waitcnt lgkmcnt(0)
	v_mfma_f32_16x16x32_bf16 v[124:127], v[136:139], v[156:159], v[124:127]
	v_mfma_f32_16x16x32_bf16 v[120:123], v[140:143], v[156:159], v[120:123]
	v_mfma_f32_16x16x32_bf16 v[116:119], v[136:139], v[160:163], v[116:119]
	v_mfma_f32_16x16x32_bf16 v[112:115], v[140:143], v[160:163], v[112:115]
	v_mfma_f32_16x16x32_bf16 v[108:111], v[136:139], v[164:167], v[108:111]
	v_mfma_f32_16x16x32_bf16 v[104:107], v[140:143], v[164:167], v[104:107]
	v_mfma_f32_16x16x32_bf16 v[100:103], v[136:139], v[168:171], v[100:103]
	v_mfma_f32_16x16x32_bf16 v[96:99], v[140:143], v[168:171], v[96:99]
	v_mfma_f32_16x16x32_bf16 v[124:127], v[148:151], v[184:187], v[124:127]
	v_mfma_f32_16x16x32_bf16 v[120:123], v[144:147], v[184:187], v[120:123]
	v_mfma_f32_16x16x32_bf16 v[116:119], v[148:151], v[176:179], v[116:119]
	v_mfma_f32_16x16x32_bf16 v[112:115], v[144:147], v[176:179], v[112:115]
	v_mfma_f32_16x16x32_bf16 v[128:131], v[148:151], v[180:183], v[108:111]
	v_mfma_f32_16x16x32_bf16 v[132:135], v[144:147], v[180:183], v[104:107]
	v_mfma_f32_16x16x32_bf16 v[100:103], v[148:151], v[172:175], v[100:103]
	v_mfma_f32_16x16x32_bf16 v[96:99], v[144:147], v[172:175], v[96:99]
	s_barrier
	s_mov_b32 s79, s81
	s_mov_b32 s80, s82
	s_cbranch_scc1 .LBB0_131
	s_sub_i32 s2, 0x5ff, s4
	s_lshr_b32 s3, s2, 3
	s_and_b32 s3, s3, 0x1ffffff8
	s_lshl_b32 s4, s3, 3
	s_sub_i32 s4, s2, s4
	s_and_b32 s2, s2, 7
	s_or_b32 s80, s3, s2
	s_ashr_i32 s79, s4, 3
	s_lshl_b32 s2, s80, 1
	s_mul_i32 s3, s80, 0x2c0000
	v_readlane_b32 s52, v254, 16
	s_mul_hi_u32 s4, s2, 0x160000
	s_add_u32 s2, s92, s3
	v_readlane_b32 s60, v254, 24
	v_readlane_b32 s61, v254, 25
	v_readlane_b32 s62, v254, 26
	v_readlane_b32 s63, v254, 27
	v_readlane_b32 s64, v254, 28
	v_readlane_b32 s65, v254, 29
	s_addc_u32 s3, s93, s4
	s_lshl_b32 s4, s79, 1
	s_mul_i32 s5, s79, 0x2c0000
	v_readlane_b32 s66, v254, 30
	v_readlane_b32 s67, v254, 31
	s_mov_b64 s[60:61], s[64:65]
	s_mul_hi_i32 s4, s4, 0x160000
	s_add_u32 s8, s60, s5
	s_addc_u32 s9, s61, s4
	s_add_u32 s10, s8, 0x160000
	v_readlane_b32 s76, v255, 6
	s_addc_u32 s11, s9, 0
	v_readlane_b32 s53, v254, 17
	v_readlane_b32 s54, v254, 18
	v_readlane_b32 s55, v254, 19
	v_readlane_b32 s56, v254, 20
	v_readlane_b32 s57, v254, 21
	v_readlane_b32 s58, v254, 22
	v_readlane_b32 s59, v254, 23
	s_mov_b64 s[62:63], s[66:67]

.Llate_p3_done:
.LBB0_183:
	ds_read_b128 v[128:131], v220
	s_waitcnt lgkmcnt(0)
	ds_read_b128 v[132:135], v220 offset:2048
	ds_read_b128 v[136:139], v221
	ds_read_b128 v[140:143], v221 offset:2048
	s_mov_b32 m0, s28
	ds_read_b128 v[144:147], v222
	ds_read_b128 v[148:151], v222 offset:2048
	ds_read_b128 v[152:155], v223
	ds_read_b128 v[156:159], v223 offset:2048
	ds_read_b128 v[160:163], v222 offset:4096
	ds_read_b128 v[164:167], v222 offset:6144
	ds_read_b128 v[168:171], v223 offset:4096
	ds_read_b128 v[172:175], v223 offset:6144
	s_add_u32 s10, s6, s72
	s_addc_u32 s11, s7, s73
	s_nop 0
	global_load_lds_dwordx4 v210, s[10:11]
	s_mov_b32 m0, s22
	s_nop 0
	s_add_u32 s10, s6, s70
	s_addc_u32 s11, s7, s71
	s_nop 0
	global_load_lds_dwordx4 v210, s[10:11]
	s_waitcnt lgkmcnt(8)
	s_barrier
	s_waitcnt lgkmcnt(0)
	v_mfma_f32_16x16x32_bf16 v[124:127], v[128:131], v[144:147], v[124:127]
	v_mfma_f32_16x16x32_bf16 v[120:123], v[132:135], v[144:147], v[120:123]
	v_mfma_f32_16x16x32_bf16 v[116:119], v[128:131], v[148:151], v[116:119]
	v_mfma_f32_16x16x32_bf16 v[112:115], v[132:135], v[148:151], v[112:115]
	v_mfma_f32_16x16x32_bf16 v[108:111], v[128:131], v[160:163], v[108:111]
	v_mfma_f32_16x16x32_bf16 v[104:107], v[132:135], v[160:163], v[104:107]
	v_mfma_f32_16x16x32_bf16 v[100:103], v[128:131], v[164:167], v[100:103]
	v_mfma_f32_16x16x32_bf16 v[96:99], v[132:135], v[164:167], v[96:99]
	v_mfma_f32_16x16x32_bf16 v[124:127], v[136:139], v[152:155], v[124:127]
	v_mfma_f32_16x16x32_bf16 v[120:123], v[140:143], v[152:155], v[120:123]
	v_mfma_f32_16x16x32_bf16 v[116:119], v[136:139], v[156:159], v[116:119]
	v_mfma_f32_16x16x32_bf16 v[112:115], v[140:143], v[156:159], v[112:115]
	v_mfma_f32_16x16x32_bf16 v[108:111], v[136:139], v[168:171], v[108:111]
	v_mfma_f32_16x16x32_bf16 v[104:107], v[140:143], v[168:171], v[104:107]
	v_mfma_f32_16x16x32_bf16 v[100:103], v[136:139], v[172:175], v[100:103]
	v_mfma_f32_16x16x32_bf16 v[96:99], v[140:143], v[172:175], v[96:99]
	s_barrier
	s_mov_b32 m0, s37
	ds_read_b128 v[176:179], v224
	ds_read_b128 v[180:183], v224 offset:2048
	ds_read_b128 v[184:187], v225
	ds_read_b128 v[188:191], v225 offset:2048
	s_add_u32 s10, s8, s78
	s_addc_u32 s11, s9, s79
	s_nop 0
	global_load_lds_dwordx4 v210, s[10:11]
	s_mov_b32 m0, s39
	s_nop 0
	s_add_u32 s10, s8, s80
	s_addc_u32 s11, s9, s81
	s_nop 0
	global_load_lds_dwordx4 v210, s[10:11]
	s_barrier
	s_waitcnt lgkmcnt(0)
	v_mfma_f32_16x16x32_bf16 v[56:59], v[176:179], v[144:147], v[56:59]
	v_mfma_f32_16x16x32_bf16 v[64:67], v[180:183], v[144:147], v[64:67]
	v_mfma_f32_16x16x32_bf16 v[72:75], v[176:179], v[148:151], v[72:75]
	v_mfma_f32_16x16x32_bf16 v[76:79], v[180:183], v[148:151], v[76:79]
	v_mfma_f32_16x16x32_bf16 v[80:83], v[176:179], v[160:163], v[80:83]
	v_mfma_f32_16x16x32_bf16 v[84:87], v[180:183], v[160:163], v[84:87]
	v_mfma_f32_16x16x32_bf16 v[88:91], v[176:179], v[164:167], v[88:91]
	v_mfma_f32_16x16x32_bf16 v[92:95], v[180:183], v[164:167], v[92:95]
	v_mfma_f32_16x16x32_bf16 v[56:59], v[184:187], v[152:155], v[56:59]
	v_mfma_f32_16x16x32_bf16 v[64:67], v[188:191], v[152:155], v[64:67]
	v_mfma_f32_16x16x32_bf16 v[72:75], v[184:187], v[156:159], v[72:75]
	v_mfma_f32_16x16x32_bf16 v[76:79], v[188:191], v[156:159], v[76:79]
	v_mfma_f32_16x16x32_bf16 v[80:83], v[184:187], v[168:171], v[80:83]
	v_mfma_f32_16x16x32_bf16 v[84:87], v[188:191], v[168:171], v[84:87]
	v_mfma_f32_16x16x32_bf16 v[88:91], v[184:187], v[172:175], v[88:91]
	v_mfma_f32_16x16x32_bf16 v[92:95], v[188:191], v[172:175], v[92:95]
	s_barrier
	s_mov_b32 m0, s76
	ds_read_b128 v[144:147], v222 offset:16384
	ds_read_b128 v[148:151], v222 offset:18432
	ds_read_b128 v[152:155], v223 offset:16384
	ds_read_b128 v[156:159], v223 offset:18432
	ds_read_b128 v[160:163], v222 offset:20480
	ds_read_b128 v[164:167], v222 offset:22528
	ds_read_b128 v[168:171], v223 offset:20480
	ds_read_b128 v[172:175], v223 offset:22528
	s_add_u32 s10, s6, s78
	s_addc_u32 s11, s7, s79
	s_nop 0
	global_load_lds_dwordx4 v210, s[10:11]
	s_mov_b32 m0, s77
	s_nop 0
	s_add_u32 s10, s6, s80
	s_addc_u32 s11, s7, s81
	s_nop 0
	global_load_lds_dwordx4 v210, s[10:11]
	s_barrier
	s_waitcnt lgkmcnt(0)
	v_mfma_f32_16x16x32_bf16 v[32:35], v[128:131], v[144:147], v[32:35]
	v_mfma_f32_16x16x32_bf16 v[36:39], v[132:135], v[144:147], v[36:39]
	v_mfma_f32_16x16x32_bf16 v[40:43], v[128:131], v[148:151], v[40:43]
	v_mfma_f32_16x16x32_bf16 v[44:47], v[132:135], v[148:151], v[44:47]
	v_mfma_f32_16x16x32_bf16 v[48:51], v[128:131], v[160:163], v[48:51]
	v_mfma_f32_16x16x32_bf16 v[52:55], v[132:135], v[160:163], v[52:55]
	v_mfma_f32_16x16x32_bf16 v[60:63], v[128:131], v[164:167], v[60:63]
	v_mfma_f32_16x16x32_bf16 v[68:71], v[132:135], v[164:167], v[68:71]
	v_mfma_f32_16x16x32_bf16 v[32:35], v[136:139], v[152:155], v[32:35]
	v_mfma_f32_16x16x32_bf16 v[36:39], v[140:143], v[152:155], v[36:39]
	v_mfma_f32_16x16x32_bf16 v[40:43], v[136:139], v[156:159], v[40:43]
	v_mfma_f32_16x16x32_bf16 v[44:47], v[140:143], v[156:159], v[44:47]
	v_mfma_f32_16x16x32_bf16 v[48:51], v[136:139], v[168:171], v[48:51]
	v_mfma_f32_16x16x32_bf16 v[52:55], v[140:143], v[168:171], v[52:55]
	v_mfma_f32_16x16x32_bf16 v[60:63], v[136:139], v[172:175], v[60:63]
	v_mfma_f32_16x16x32_bf16 v[68:71], v[140:143], v[172:175], v[68:71]
	s_barrier
	s_mov_b32 m0, s23
	s_add_u32 s10, s4, s78
	s_addc_u32 s11, s5, s79
	s_nop 0
	global_load_lds_dwordx4 v210, s[10:11]
	s_mov_b32 m0, s33
	s_nop 0
	s_add_u32 s10, s4, s80
	s_addc_u32 s11, s5, s81
	s_nop 0
	global_load_lds_dwordx4 v210, s[10:11]
	s_waitcnt vmcnt(6)
	s_barrier
	v_mfma_f32_16x16x32_bf16 v[0:3], v[176:179], v[144:147], v[0:3]
	v_mfma_f32_16x16x32_bf16 v[4:7], v[180:183], v[144:147], v[4:7]
	v_mfma_f32_16x16x32_bf16 v[8:11], v[176:179], v[148:151], v[8:11]
	v_mfma_f32_16x16x32_bf16 v[12:15], v[180:183], v[148:151], v[12:15]
	v_mfma_f32_16x16x32_bf16 v[16:19], v[176:179], v[160:163], v[16:19]
	v_mfma_f32_16x16x32_bf16 v[20:23], v[180:183], v[160:163], v[20:23]
	v_mfma_f32_16x16x32_bf16 v[24:27], v[176:179], v[164:167], v[24:27]
	v_mfma_f32_16x16x32_bf16 v[28:31], v[180:183], v[164:167], v[28:31]
	v_mfma_f32_16x16x32_bf16 v[0:3], v[184:187], v[152:155], v[0:3]
	v_mfma_f32_16x16x32_bf16 v[4:7], v[188:191], v[152:155], v[4:7]
	v_mfma_f32_16x16x32_bf16 v[8:11], v[184:187], v[156:159], v[8:11]
	v_mfma_f32_16x16x32_bf16 v[12:15], v[188:191], v[156:159], v[12:15]
	v_mfma_f32_16x16x32_bf16 v[16:19], v[184:187], v[168:171], v[16:19]
	v_mfma_f32_16x16x32_bf16 v[20:23], v[188:191], v[168:171], v[20:23]
	v_mfma_f32_16x16x32_bf16 v[24:27], v[184:187], v[172:175], v[24:27]
	v_mfma_f32_16x16x32_bf16 v[28:31], v[188:191], v[172:175], v[28:31]
	s_barrier
	ds_read_b128 v[128:131], v226
	ds_read_b128 v[132:135], v226 offset:2048
	ds_read_b128 v[136:139], v227
	ds_read_b128 v[140:143], v227 offset:2048
	s_mov_b32 m0, s26
	ds_read_b128 v[144:147], v222 offset:32768
	ds_read_b128 v[148:151], v222 offset:34816
	ds_read_b128 v[152:155], v223 offset:32768
	ds_read_b128 v[156:159], v223 offset:34816
	ds_read_b128 v[160:163], v222 offset:36864
	ds_read_b128 v[164:167], v222 offset:38912
	ds_read_b128 v[168:171], v223 offset:36864
	ds_read_b128 v[172:175], v223 offset:38912
	s_add_u32 s10, s6, 0x80100
	s_addc_u32 s11, s7, 0x0
	s_nop 0
	global_load_lds_dwordx4 v210, s[10:11]
	s_mov_b32 m0, s35
	s_nop 0
	s_add_u32 s10, s6, 0xc0100
	s_addc_u32 s11, s7, 0x0
	s_nop 0
	global_load_lds_dwordx4 v210, s[10:11]
	s_waitcnt lgkmcnt(8)
	s_barrier
	s_waitcnt lgkmcnt(0)
	v_mfma_f32_16x16x32_bf16 v[124:127], v[128:131], v[144:147], v[124:127]
	v_mfma_f32_16x16x32_bf16 v[120:123], v[132:135], v[144:147], v[120:123]
	v_mfma_f32_16x16x32_bf16 v[116:119], v[128:131], v[148:151], v[116:119]
	v_mfma_f32_16x16x32_bf16 v[112:115], v[132:135], v[148:151], v[112:115]
	v_mfma_f32_16x16x32_bf16 v[108:111], v[128:131], v[160:163], v[108:111]
	v_mfma_f32_16x16x32_bf16 v[104:107], v[132:135], v[160:163], v[104:107]
	v_mfma_f32_16x16x32_bf16 v[100:103], v[128:131], v[164:167], v[100:103]
	v_mfma_f32_16x16x32_bf16 v[96:99], v[132:135], v[164:167], v[96:99]
	v_mfma_f32_16x16x32_bf16 v[124:127], v[136:139], v[152:155], v[124:127]
	v_mfma_f32_16x16x32_bf16 v[120:123], v[140:143], v[152:155], v[120:123]
	v_mfma_f32_16x16x32_bf16 v[116:119], v[136:139], v[156:159], v[116:119]
	v_mfma_f32_16x16x32_bf16 v[112:115], v[140:143], v[156:159], v[112:115]
	v_mfma_f32_16x16x32_bf16 v[108:111], v[136:139], v[168:171], v[108:111]
	v_mfma_f32_16x16x32_bf16 v[104:107], v[140:143], v[168:171], v[104:107]
	v_mfma_f32_16x16x32_bf16 v[100:103], v[136:139], v[172:175], v[100:103]
	v_mfma_f32_16x16x32_bf16 v[96:99], v[140:143], v[172:175], v[96:99]
	s_barrier
	s_mov_b32 m0, s27
	ds_read_b128 v[176:179], v228
	ds_read_b128 v[180:183], v228 offset:2048
	ds_read_b128 v[184:187], v229
	ds_read_b128 v[188:191], v229 offset:2048
	s_add_u32 s10, s8, s82
	s_addc_u32 s11, s9, s83
	s_nop 0
	global_load_lds_dwordx4 v210, s[10:11]
	s_mov_b32 m0, s31
	s_nop 0
	s_add_u32 s10, s8, s96
	s_addc_u32 s11, s9, s97
	s_nop 0
	global_load_lds_dwordx4 v210, s[10:11]
	s_barrier
	s_waitcnt lgkmcnt(0)
	v_mfma_f32_16x16x32_bf16 v[56:59], v[176:179], v[144:147], v[56:59]
	v_mfma_f32_16x16x32_bf16 v[64:67], v[180:183], v[144:147], v[64:67]
	v_mfma_f32_16x16x32_bf16 v[72:75], v[176:179], v[148:151], v[72:75]
	v_mfma_f32_16x16x32_bf16 v[76:79], v[180:183], v[148:151], v[76:79]
	v_mfma_f32_16x16x32_bf16 v[80:83], v[176:179], v[160:163], v[80:83]
	v_mfma_f32_16x16x32_bf16 v[84:87], v[180:183], v[160:163], v[84:87]
	v_mfma_f32_16x16x32_bf16 v[88:91], v[176:179], v[164:167], v[88:91]
	v_mfma_f32_16x16x32_bf16 v[92:95], v[180:183], v[164:167], v[92:95]
	v_mfma_f32_16x16x32_bf16 v[56:59], v[184:187], v[152:155], v[56:59]
	v_mfma_f32_16x16x32_bf16 v[64:67], v[188:191], v[152:155], v[64:67]
	v_mfma_f32_16x16x32_bf16 v[72:75], v[184:187], v[156:159], v[72:75]
	v_mfma_f32_16x16x32_bf16 v[76:79], v[188:191], v[156:159], v[76:79]
	v_mfma_f32_16x16x32_bf16 v[80:83], v[184:187], v[168:171], v[80:83]
	v_mfma_f32_16x16x32_bf16 v[84:87], v[188:191], v[168:171], v[84:87]
	v_mfma_f32_16x16x32_bf16 v[88:91], v[184:187], v[172:175], v[88:91]
	v_mfma_f32_16x16x32_bf16 v[92:95], v[188:191], v[172:175], v[92:95]
	s_barrier
	s_mov_b32 m0, s1
	ds_read_b128 v[144:147], v222 offset:49152
	ds_read_b128 v[148:151], v222 offset:51200
	ds_read_b128 v[152:155], v223 offset:49152
	ds_read_b128 v[156:159], v223 offset:51200
	ds_read_b128 v[160:163], v222 offset:53248
	ds_read_b128 v[164:167], v222 offset:55296
	ds_read_b128 v[168:171], v223 offset:53248
	ds_read_b128 v[172:175], v223 offset:55296
	s_add_u32 s10, s6, s82
	s_addc_u32 s11, s7, s83
	s_nop 0
	global_load_lds_dwordx4 v210, s[10:11]
	s_mov_b32 m0, s34
	s_nop 0
	s_add_u32 s10, s6, s96
	s_addc_u32 s11, s7, s97
	s_nop 0
	global_load_lds_dwordx4 v210, s[10:11]
	s_barrier
	s_waitcnt lgkmcnt(0)
	v_mfma_f32_16x16x32_bf16 v[32:35], v[128:131], v[144:147], v[32:35]
	v_mfma_f32_16x16x32_bf16 v[36:39], v[132:135], v[144:147], v[36:39]
	v_mfma_f32_16x16x32_bf16 v[40:43], v[128:131], v[148:151], v[40:43]
	v_mfma_f32_16x16x32_bf16 v[44:47], v[132:135], v[148:151], v[44:47]
	v_mfma_f32_16x16x32_bf16 v[48:51], v[128:131], v[160:163], v[48:51]
	v_mfma_f32_16x16x32_bf16 v[52:55], v[132:135], v[160:163], v[52:55]
	v_mfma_f32_16x16x32_bf16 v[60:63], v[128:131], v[164:167], v[60:63]
	v_mfma_f32_16x16x32_bf16 v[68:71], v[132:135], v[164:167], v[68:71]
	v_mfma_f32_16x16x32_bf16 v[32:35], v[136:139], v[152:155], v[32:35]
	v_mfma_f32_16x16x32_bf16 v[36:39], v[140:143], v[152:155], v[36:39]
	v_mfma_f32_16x16x32_bf16 v[40:43], v[136:139], v[156:159], v[40:43]
	v_mfma_f32_16x16x32_bf16 v[44:47], v[140:143], v[156:159], v[44:47]
	v_mfma_f32_16x16x32_bf16 v[48:51], v[136:139], v[168:171], v[48:51]
	v_mfma_f32_16x16x32_bf16 v[52:55], v[140:143], v[168:171], v[52:55]
	v_mfma_f32_16x16x32_bf16 v[60:63], v[136:139], v[172:175], v[60:63]
	v_mfma_f32_16x16x32_bf16 v[68:71], v[140:143], v[172:175], v[68:71]
	s_barrier
	s_mov_b32 m0, s19
	s_add_u32 s10, s4, s82
	s_addc_u32 s11, s5, s83
	s_nop 0
	global_load_lds_dwordx4 v210, s[10:11]
	s_mov_b32 m0, s18
	s_nop 0
	s_add_u32 s10, s4, s96
	s_addc_u32 s11, s5, s97
	s_nop 0
	global_load_lds_dwordx4 v210, s[10:11]
	s_waitcnt vmcnt(6)
	s_barrier
	v_mfma_f32_16x16x32_bf16 v[0:3], v[176:179], v[144:147], v[0:3]
	v_mfma_f32_16x16x32_bf16 v[4:7], v[180:183], v[144:147], v[4:7]
	v_mfma_f32_16x16x32_bf16 v[8:11], v[176:179], v[148:151], v[8:11]
	v_mfma_f32_16x16x32_bf16 v[12:15], v[180:183], v[148:151], v[12:15]
	v_mfma_f32_16x16x32_bf16 v[16:19], v[176:179], v[160:163], v[16:19]
	v_mfma_f32_16x16x32_bf16 v[20:23], v[180:183], v[160:163], v[20:23]
	v_mfma_f32_16x16x32_bf16 v[24:27], v[176:179], v[164:167], v[24:27]
	v_mfma_f32_16x16x32_bf16 v[28:31], v[180:183], v[164:167], v[28:31]
	v_mfma_f32_16x16x32_bf16 v[0:3], v[184:187], v[152:155], v[0:3]
	v_mfma_f32_16x16x32_bf16 v[4:7], v[188:191], v[152:155], v[4:7]
	v_mfma_f32_16x16x32_bf16 v[8:11], v[184:187], v[156:159], v[8:11]
	v_mfma_f32_16x16x32_bf16 v[12:15], v[188:191], v[156:159], v[12:15]
	v_mfma_f32_16x16x32_bf16 v[16:19], v[184:187], v[168:171], v[16:19]
	v_mfma_f32_16x16x32_bf16 v[20:23], v[188:191], v[168:171], v[20:23]
	v_mfma_f32_16x16x32_bf16 v[24:27], v[184:187], v[172:175], v[24:27]
	v_mfma_f32_16x16x32_bf16 v[28:31], v[188:191], v[172:175], v[28:31]
	s_barrier
	s_add_i32 s2, s2, 2
	s_add_u32 s8, s8, 0x100
	s_addc_u32 s9, s9, 0
	s_add_u32 s6, s6, 0x100
	s_addc_u32 s7, s7, 0
	s_add_u32 s4, s4, 0x100
	s_addc_u32 s5, s5, 0
	s_cmp_lt_u32 s2, 28
	s_cbranch_scc1 .LBB0_183
; #define LDA(dst,b,h) _Pragma("unroll") for(int m=0;m<4;++m) _Pragma("unroll") for(int k=0;k<2;++k) \
;     dst[m][k]=*reinterpret_cast<const bf16x8*>(SA(b,h)+(wr*64+m*16)*128+koff[k])
; #define LDB(dst,b,h) _Pragma("unroll") for(int n=0;n<2;++n) _Pragma("unroll") for(int k=0;k<2;++k) \
;     dst[n][k]=*reinterpret_cast<const bf16x8*>(SB(b,h)+(wc*32+n*16)*128+koff[k])
; #define MMA(ai,bj,Af,Bf) do{__builtin_amdgcn_s_setprio(1); \
;     _Pragma("unroll") for(int m=0;m<4;++m) _Pragma("unroll") for(int n=0;n<2;++n) _Pragma("unroll") for(int k=0;k<2;++k) \
;       acc[ai][bj][m][n]=__builtin_amdgcn_mfma_f32_16x16x32_bf16(Bf[n][k],Af[m][k],acc[ai][bj][m][n],0,0,0); \
;     __builtin_amdgcn_s_setprio(0);}while(0)
; #define WAIT_L(n) asm volatile("s_waitcnt lgkmcnt(" #n ")":::"memory")
; #define BAR __builtin_amdgcn_s_barrier()
; #define SCHED __builtin_amdgcn_sched_barrier(0)
; #define STAGE_A(b,h,kt) do{ unsigned char* _d = SA(b,h) + wbase; \
;     if constexpr (BLK) { const char* _s = baseA + ((size_t)(h)*(K/64) + (kt)) * 16384; GLDS(_s + voa, _d); GLDS(_s + 8192 + voa, _d + 8192); } \
;     else { const char* _s = baseA + ((size_t)(h)*128*K + (kt)*64) * 2; GLDS(_s + voa, _d); GLDS(_s + (size_t)128*K + voa, _d + 8192); } }while(0)
; template <int K, int EPI, bool MIX = false>
; __device__ __forceinline__ void gemm_phase(const Params& p, const u16* __restrict__ A, const u16* __restrict__ Bt,
;                            const float* __restrict__ rs_in, float* __restrict__ ssq_out, float alpha, bool rev = false) {
;     ...
;         for (int m = 0; m < 4; ++m) rsq[ai][m] = rsrc[cpm * 256 + ai * 128 + wr * 64 + m * 16 + fr_p];
;     }
;     ++it;
;     id = item_id(it);
;     const bool more = id < ntiles;
;     if (rev) id = ntiles - 1 - id;
;     {
;       LDB(B0,0,0); SCHED; LDA(At,0,0); STAGE_A(1,1,nt-1);
;       WAIT_L(8); BAR; WAIT_L(0); MMA(0,0,At,B0); BAR; SCHED;
;       if (more) SETUP_TILE();
	v_mov_b32_e32 v128, v219
	s_lshl_b32 s15, s12, 8
	s_add_i32 s15, s15, s13
	v_add_u32_e32 v128, s15, v128
	v_readlane_b32 s52, v254, 32
	v_ashrrev_i32_e32 v129, 31, v128
	v_readlane_b32 s64, v254, 44
	v_readlane_b32 s65, v254, 45
	s_add_i32 s74, s74, 1
	v_readlane_b32 s2, v255, 6
	v_lshl_add_u64 v[128:129], v[128:129], 2, s[64:65]
	global_load_dword v242, v[128:129], off
	global_load_dword v241, v[128:129], off offset:64
	global_load_dword v240, v[128:129], off offset:128
	global_load_dword v239, v[128:129], off offset:192
	global_load_dword v238, v[128:129], off offset:512
	global_load_dword v237, v[128:129], off offset:576
	global_load_dword v236, v[128:129], off offset:640
	global_load_dword v235, v[128:129], off offset:704
	ds_read_b128 v[136:139], v220
	ds_read_b128 v[140:143], v220 offset:2048
	ds_read_b128 v[148:151], v221
	ds_read_b128 v[144:147], v221 offset:2048
	s_mul_i32 s2, s74, s2
	v_readlane_b32 s4, v255, 17
	s_add_i32 s2, s2, s4
	v_readlane_b32 s53, v254, 33
	v_readlane_b32 s54, v254, 34
	v_readlane_b32 s55, v254, 35
	v_readlane_b32 s56, v254, 36
	v_readlane_b32 s57, v254, 37
	v_readlane_b32 s58, v254, 38
	v_readlane_b32 s59, v254, 39
	v_readlane_b32 s60, v254, 40
	v_readlane_b32 s61, v254, 41
	v_readlane_b32 s62, v254, 42
	v_readlane_b32 s63, v254, 43
	v_readlane_b32 s66, v254, 46
	v_readlane_b32 s67, v254, 47
	v_lshl_add_u64 v[128:129], s[16:17], 0, v[208:209]
	s_mov_b64 s[4:5], 0x80f80
	s_mov_b32 m0, s28
	v_lshl_add_u64 v[130:131], v[128:129], 0, s[4:5]
	s_mov_b64 s[4:5], 0xc0f80
	ds_read_b128 v[152:155], v222
	ds_read_b128 v[156:159], v222 offset:2048
	ds_read_b128 v[180:183], v223
	ds_read_b128 v[164:167], v223 offset:2048
	ds_read_b128 v[160:163], v222 offset:4096
	ds_read_b128 v[168:171], v222 offset:6144
	ds_read_b128 v[176:179], v223 offset:4096
	ds_read_b128 v[172:175], v223 offset:6144
	global_load_lds_dwordx4 v[130:131], off
	v_lshl_add_u64 v[128:129], v[128:129], 0, s[4:5]
	s_mov_b32 m0, s22
	s_nop 0
	global_load_lds_dwordx4 v[128:129], off
	s_waitcnt lgkmcnt(8)
	s_barrier
	s_waitcnt lgkmcnt(0)
	v_mfma_f32_16x16x32_bf16 v[124:127], v[136:139], v[152:155], v[124:127]
	s_cmpk_lt_i32 s2, 0xf00
	s_cselect_b64 s[4:5], -1, 0
	s_cmpk_gt_i32 s2, 0xeff
	v_mfma_f32_16x16x32_bf16 v[120:123], v[140:143], v[152:155], v[120:123]
	v_mfma_f32_16x16x32_bf16 v[116:119], v[136:139], v[156:159], v[116:119]
	v_mfma_f32_16x16x32_bf16 v[112:115], v[140:143], v[156:159], v[112:115]
	v_mfma_f32_16x16x32_bf16 v[108:111], v[136:139], v[160:163], v[108:111]
	v_mfma_f32_16x16x32_bf16 v[104:107], v[140:143], v[160:163], v[104:107]
	v_mfma_f32_16x16x32_bf16 v[100:103], v[136:139], v[168:171], v[100:103]
	v_mfma_f32_16x16x32_bf16 v[96:99], v[140:143], v[168:171], v[96:99]
	v_mfma_f32_16x16x32_bf16 v[124:127], v[148:151], v[180:183], v[124:127]
	v_mfma_f32_16x16x32_bf16 v[120:123], v[144:147], v[180:183], v[120:123]
	v_mfma_f32_16x16x32_bf16 v[116:119], v[148:151], v[164:167], v[116:119]
	v_mfma_f32_16x16x32_bf16 v[112:115], v[144:147], v[164:167], v[112:115]
	v_mfma_f32_16x16x32_bf16 v[108:111], v[148:151], v[176:179], v[108:111]
	v_mfma_f32_16x16x32_bf16 v[104:107], v[144:147], v[176:179], v[104:107]
	v_mfma_f32_16x16x32_bf16 v[128:131], v[148:151], v[172:175], v[100:103]
	v_mfma_f32_16x16x32_bf16 v[132:135], v[144:147], v[172:175], v[96:99]
	s_barrier
	s_mov_b32 s75, s25
	s_cbranch_scc1 .LBB0_186
	s_mul_hi_i32 s6, s2, 0x66666667
	s_lshr_b32 s7, s6, 31
	s_ashr_i32 s6, s6, 6
	s_add_i32 s6, s6, s7
	s_lshl_b32 s7, s6, 3
	s_mulk_i32 s6, 0xff60
	s_add_i32 s6, s6, s2
	s_and_b32 s2, s2, 7
	s_or_b32 s12, s7, s2
	s_ashr_i32 s75, s6, 3
	s_lshl_b32 s6, s12, 8
	s_ashr_i32 s7, s6, 31
	s_lshl_b64 s[6:7], s[6:7], 12
	s_add_u32 s16, s90, s6
	s_addc_u32 s17, s91, s7
	s_lshl_b32 s6, s75, 8
	s_ashr_i32 s7, s6, 31
	v_readlane_b32 s52, v254, 16
	s_lshl_b64 s[6:7], s[6:7], 12
	v_readlane_b32 s66, v254, 30
	v_readlane_b32 s67, v254, 31
	s_add_u32 s20, s66, s6
	s_addc_u32 s21, s67, s7
	s_add_u32 s44, s20, 0x80000
	s_addc_u32 s45, s21, 0
	v_readlane_b32 s53, v254, 17
	v_readlane_b32 s54, v254, 18
	v_readlane_b32 s55, v254, 19
	v_readlane_b32 s56, v254, 20
	v_readlane_b32 s57, v254, 21
	v_readlane_b32 s58, v254, 22
	v_readlane_b32 s59, v254, 23
	v_readlane_b32 s60, v254, 24
	v_readlane_b32 s61, v254, 25
	v_readlane_b32 s62, v254, 26
	v_readlane_b32 s63, v254, 27
	v_readlane_b32 s64, v254, 28
	v_readlane_b32 s65, v254, 29

.Llate_p5_done:
.LBB0_365:
	ds_read_b128 v[112:115], v234
	ds_read_b128 v[116:119], v234 offset:2048
	ds_read_b128 v[136:139], v235
	ds_read_b128 v[140:143], v235 offset:2048
	s_mov_b32 m0, s74
	ds_read_b128 v[144:147], v236
	ds_read_b128 v[148:151], v236 offset:2048
	ds_read_b128 v[152:155], v237
	ds_read_b128 v[156:159], v237 offset:2048
	ds_read_b128 v[160:163], v236 offset:4096
	ds_read_b128 v[164:167], v236 offset:6144
	ds_read_b128 v[168:171], v237 offset:4096
	ds_read_b128 v[172:175], v237 offset:6144
	s_add_u32 s80, s6, s22
	s_addc_u32 s81, s7, s23
	s_nop 0
	global_load_lds_dwordx4 v222, s[80:81]
	s_mov_b32 m0, s75
	s_nop 0
	s_add_u32 s80, s6, s24
	s_addc_u32 s81, s7, s25
	s_nop 0
	global_load_lds_dwordx4 v222, s[80:81]
	s_waitcnt lgkmcnt(8)
	s_barrier
	s_waitcnt lgkmcnt(0)
	v_mfma_f32_16x16x32_bf16 v[28:31], v[112:115], v[144:147], v[28:31]
	v_mfma_f32_16x16x32_bf16 v[24:27], v[116:119], v[144:147], v[24:27]
	v_mfma_f32_16x16x32_bf16 v[44:47], v[112:115], v[148:151], v[44:47]
	v_mfma_f32_16x16x32_bf16 v[40:43], v[116:119], v[148:151], v[40:43]
	v_mfma_f32_16x16x32_bf16 v[68:71], v[112:115], v[160:163], v[68:71]
	v_mfma_f32_16x16x32_bf16 v[64:67], v[116:119], v[160:163], v[64:67]
	v_mfma_f32_16x16x32_bf16 v[100:103], v[112:115], v[164:167], v[100:103]
	v_mfma_f32_16x16x32_bf16 v[96:99], v[116:119], v[164:167], v[96:99]
	v_mfma_f32_16x16x32_bf16 v[28:31], v[136:139], v[152:155], v[28:31]
	v_mfma_f32_16x16x32_bf16 v[24:27], v[140:143], v[152:155], v[24:27]
	v_mfma_f32_16x16x32_bf16 v[44:47], v[136:139], v[156:159], v[44:47]
	v_mfma_f32_16x16x32_bf16 v[40:43], v[140:143], v[156:159], v[40:43]
	v_mfma_f32_16x16x32_bf16 v[68:71], v[136:139], v[168:171], v[68:71]
	v_mfma_f32_16x16x32_bf16 v[64:67], v[140:143], v[168:171], v[64:67]
	v_mfma_f32_16x16x32_bf16 v[100:103], v[136:139], v[172:175], v[100:103]
	v_mfma_f32_16x16x32_bf16 v[96:99], v[140:143], v[172:175], v[96:99]
	s_barrier
	s_mov_b32 m0, s42
	ds_read_b128 v[176:179], v238
	ds_read_b128 v[180:183], v238 offset:2048
	ds_read_b128 v[184:187], v239
	ds_read_b128 v[188:191], v239 offset:2048
	s_add_u32 s80, s60, s30
	s_addc_u32 s81, s61, s31
	s_nop 0
	global_load_lds_dwordx4 v222, s[80:81]
	s_mov_b32 m0, s43
	s_nop 0
	s_add_u32 s80, s60, s36
	s_addc_u32 s81, s61, s37
	s_nop 0
	global_load_lds_dwordx4 v222, s[80:81]
	s_barrier
	s_waitcnt lgkmcnt(0)
	v_mfma_f32_16x16x32_bf16 v[20:23], v[176:179], v[144:147], v[20:23]
	v_mfma_f32_16x16x32_bf16 v[16:19], v[180:183], v[144:147], v[16:19]
	v_mfma_f32_16x16x32_bf16 v[36:39], v[176:179], v[148:151], v[36:39]
	v_mfma_f32_16x16x32_bf16 v[32:35], v[180:183], v[148:151], v[32:35]
	v_mfma_f32_16x16x32_bf16 v[52:55], v[176:179], v[160:163], v[52:55]
	v_mfma_f32_16x16x32_bf16 v[48:51], v[180:183], v[160:163], v[48:51]
	v_mfma_f32_16x16x32_bf16 v[76:79], v[176:179], v[164:167], v[76:79]
	v_mfma_f32_16x16x32_bf16 v[72:75], v[180:183], v[164:167], v[72:75]
	v_mfma_f32_16x16x32_bf16 v[20:23], v[184:187], v[152:155], v[20:23]
	v_mfma_f32_16x16x32_bf16 v[16:19], v[188:191], v[152:155], v[16:19]
	v_mfma_f32_16x16x32_bf16 v[36:39], v[184:187], v[156:159], v[36:39]
	v_mfma_f32_16x16x32_bf16 v[32:35], v[188:191], v[156:159], v[32:35]
	v_mfma_f32_16x16x32_bf16 v[52:55], v[184:187], v[168:171], v[52:55]
	v_mfma_f32_16x16x32_bf16 v[48:51], v[188:191], v[168:171], v[48:51]
	v_mfma_f32_16x16x32_bf16 v[76:79], v[184:187], v[172:175], v[76:79]
	v_mfma_f32_16x16x32_bf16 v[72:75], v[188:191], v[172:175], v[72:75]
	s_barrier
	s_mov_b32 m0, s34
	ds_read_b128 v[144:147], v236 offset:16384
	ds_read_b128 v[148:151], v236 offset:18432
	ds_read_b128 v[152:155], v237 offset:16384
	ds_read_b128 v[156:159], v237 offset:18432
	ds_read_b128 v[160:163], v236 offset:20480
	ds_read_b128 v[164:167], v236 offset:22528
	ds_read_b128 v[168:171], v237 offset:20480
	ds_read_b128 v[172:175], v237 offset:22528
	s_add_u32 s80, s6, s30
	s_addc_u32 s81, s7, s31
	s_nop 0
	global_load_lds_dwordx4 v222, s[80:81]
	s_mov_b32 m0, s44
	s_nop 0
	s_add_u32 s80, s6, s36
	s_addc_u32 s81, s7, s37
	s_nop 0
	global_load_lds_dwordx4 v222, s[80:81]
	s_barrier
	s_waitcnt lgkmcnt(0)
	v_mfma_f32_16x16x32_bf16 v[84:87], v[112:115], v[144:147], v[84:87]
	v_mfma_f32_16x16x32_bf16 v[80:83], v[116:119], v[144:147], v[80:83]
	v_mfma_f32_16x16x32_bf16 v[108:111], v[112:115], v[148:151], v[108:111]
	v_mfma_f32_16x16x32_bf16 v[104:107], v[116:119], v[148:151], v[104:107]
	v_mfma_f32_16x16x32_bf16 v[60:63], v[112:115], v[160:163], v[60:63]
	v_mfma_f32_16x16x32_bf16 v[56:59], v[116:119], v[160:163], v[56:59]
	v_mfma_f32_16x16x32_bf16 v[4:7], v[112:115], v[164:167], v[4:7]
	v_mfma_f32_16x16x32_bf16 v[0:3], v[116:119], v[164:167], v[0:3]
	v_mfma_f32_16x16x32_bf16 v[84:87], v[136:139], v[152:155], v[84:87]
	v_mfma_f32_16x16x32_bf16 v[80:83], v[140:143], v[152:155], v[80:83]
	v_mfma_f32_16x16x32_bf16 v[108:111], v[136:139], v[156:159], v[108:111]
	v_mfma_f32_16x16x32_bf16 v[104:107], v[140:143], v[156:159], v[104:107]
	v_mfma_f32_16x16x32_bf16 v[60:63], v[136:139], v[168:171], v[60:63]
	v_mfma_f32_16x16x32_bf16 v[56:59], v[140:143], v[168:171], v[56:59]
	v_mfma_f32_16x16x32_bf16 v[4:7], v[136:139], v[172:175], v[4:7]
	v_mfma_f32_16x16x32_bf16 v[0:3], v[140:143], v[172:175], v[0:3]
	s_barrier
	s_mov_b32 m0, s45
	s_add_u32 s80, s4, s30
	s_addc_u32 s81, s5, s31
	s_nop 0
	global_load_lds_dwordx4 v222, s[80:81]
	s_mov_b32 m0, s62
	s_nop 0
	s_add_u32 s80, s4, s36
	s_addc_u32 s81, s5, s37
	s_nop 0
	global_load_lds_dwordx4 v222, s[80:81]
	s_waitcnt vmcnt(6)
	s_barrier
	v_mfma_f32_16x16x32_bf16 v[120:123], v[176:179], v[148:151], v[120:123]
	v_mfma_f32_16x16x32_bf16 v[124:127], v[180:183], v[148:151], v[124:127]
	v_mfma_f32_16x16x32_bf16 v[88:91], v[176:179], v[160:163], v[88:91]
	v_mfma_f32_16x16x32_bf16 v[92:95], v[180:183], v[160:163], v[92:95]
	v_mfma_f32_16x16x32_bf16 v[12:15], v[176:179], v[164:167], v[12:15]
	v_mfma_f32_16x16x32_bf16 v[8:11], v[180:183], v[164:167], v[8:11]
	v_mfma_f32_16x16x32_bf16 v[112:115], v[176:179], v[144:147], v[128:131]
	v_mfma_f32_16x16x32_bf16 v[116:119], v[180:183], v[144:147], v[132:135]
	v_mfma_f32_16x16x32_bf16 v[120:123], v[184:187], v[156:159], v[120:123]
	v_mfma_f32_16x16x32_bf16 v[124:127], v[188:191], v[156:159], v[124:127]
	v_mfma_f32_16x16x32_bf16 v[88:91], v[184:187], v[168:171], v[88:91]
	v_mfma_f32_16x16x32_bf16 v[92:95], v[188:191], v[168:171], v[92:95]
	v_mfma_f32_16x16x32_bf16 v[12:15], v[184:187], v[172:175], v[12:15]
	v_mfma_f32_16x16x32_bf16 v[8:11], v[188:191], v[172:175], v[8:11]
	v_mfma_f32_16x16x32_bf16 v[112:115], v[184:187], v[152:155], v[112:115]
	v_mfma_f32_16x16x32_bf16 v[116:119], v[188:191], v[152:155], v[116:119]
	s_barrier
	ds_read_b128 v[128:131], v240
	ds_read_b128 v[132:135], v240 offset:2048
	ds_read_b128 v[136:139], v241
	ds_read_b128 v[140:143], v241 offset:2048
	s_mov_b32 m0, s63
	ds_read_b128 v[144:147], v236 offset:32768
	ds_read_b128 v[148:151], v236 offset:34816
	ds_read_b128 v[152:155], v237 offset:32768
	ds_read_b128 v[156:159], v237 offset:34816
	ds_read_b128 v[160:163], v236 offset:36864
	ds_read_b128 v[164:167], v236 offset:38912
	ds_read_b128 v[168:171], v237 offset:36864
	ds_read_b128 v[172:175], v237 offset:38912
	s_add_u32 s80, s6, 0x80100
	s_addc_u32 s81, s7, 0x0
	s_nop 0
	global_load_lds_dwordx4 v222, s[80:81]
	s_mov_b32 m0, s64
	s_nop 0
	s_add_u32 s80, s6, 0xc0100
	s_addc_u32 s81, s7, 0x0
	s_nop 0
	global_load_lds_dwordx4 v222, s[80:81]
	s_waitcnt lgkmcnt(8)
	s_barrier
	s_waitcnt lgkmcnt(0)
	v_mfma_f32_16x16x32_bf16 v[28:31], v[128:131], v[144:147], v[28:31]
	v_mfma_f32_16x16x32_bf16 v[24:27], v[132:135], v[144:147], v[24:27]
	v_mfma_f32_16x16x32_bf16 v[44:47], v[128:131], v[148:151], v[44:47]
	v_mfma_f32_16x16x32_bf16 v[40:43], v[132:135], v[148:151], v[40:43]
	v_mfma_f32_16x16x32_bf16 v[68:71], v[128:131], v[160:163], v[68:71]
	v_mfma_f32_16x16x32_bf16 v[64:67], v[132:135], v[160:163], v[64:67]
	v_mfma_f32_16x16x32_bf16 v[100:103], v[128:131], v[164:167], v[100:103]
	v_mfma_f32_16x16x32_bf16 v[96:99], v[132:135], v[164:167], v[96:99]
	v_mfma_f32_16x16x32_bf16 v[28:31], v[136:139], v[152:155], v[28:31]
	v_mfma_f32_16x16x32_bf16 v[24:27], v[140:143], v[152:155], v[24:27]
	v_mfma_f32_16x16x32_bf16 v[44:47], v[136:139], v[156:159], v[44:47]
	v_mfma_f32_16x16x32_bf16 v[40:43], v[140:143], v[156:159], v[40:43]
	v_mfma_f32_16x16x32_bf16 v[68:71], v[136:139], v[168:171], v[68:71]
	v_mfma_f32_16x16x32_bf16 v[64:67], v[140:143], v[168:171], v[64:67]
	v_mfma_f32_16x16x32_bf16 v[100:103], v[136:139], v[172:175], v[100:103]
	v_mfma_f32_16x16x32_bf16 v[96:99], v[140:143], v[172:175], v[96:99]
	s_barrier
	s_mov_b32 m0, s65
	ds_read_b128 v[176:179], v242
	ds_read_b128 v[180:183], v242 offset:2048
	ds_read_b128 v[184:187], v243
	ds_read_b128 v[188:191], v243 offset:2048
	s_add_u32 s80, s60, s38
	s_addc_u32 s81, s61, s39
	s_nop 0
	global_load_lds_dwordx4 v222, s[80:81]
	s_mov_b32 m0, s68
	s_nop 0
	s_add_u32 s80, s60, s40
	s_addc_u32 s81, s61, s41
	s_nop 0
	global_load_lds_dwordx4 v222, s[80:81]
	s_barrier
	s_waitcnt lgkmcnt(0)
	v_mfma_f32_16x16x32_bf16 v[20:23], v[176:179], v[144:147], v[20:23]
	v_mfma_f32_16x16x32_bf16 v[16:19], v[180:183], v[144:147], v[16:19]
	v_mfma_f32_16x16x32_bf16 v[36:39], v[176:179], v[148:151], v[36:39]
	v_mfma_f32_16x16x32_bf16 v[32:35], v[180:183], v[148:151], v[32:35]
	v_mfma_f32_16x16x32_bf16 v[52:55], v[176:179], v[160:163], v[52:55]
	v_mfma_f32_16x16x32_bf16 v[48:51], v[180:183], v[160:163], v[48:51]
	v_mfma_f32_16x16x32_bf16 v[76:79], v[176:179], v[164:167], v[76:79]
	v_mfma_f32_16x16x32_bf16 v[72:75], v[180:183], v[164:167], v[72:75]
	v_mfma_f32_16x16x32_bf16 v[20:23], v[184:187], v[152:155], v[20:23]
	v_mfma_f32_16x16x32_bf16 v[16:19], v[188:191], v[152:155], v[16:19]
	v_mfma_f32_16x16x32_bf16 v[36:39], v[184:187], v[156:159], v[36:39]
	v_mfma_f32_16x16x32_bf16 v[32:35], v[188:191], v[156:159], v[32:35]
	v_mfma_f32_16x16x32_bf16 v[52:55], v[184:187], v[168:171], v[52:55]
	v_mfma_f32_16x16x32_bf16 v[48:51], v[188:191], v[168:171], v[48:51]
	v_mfma_f32_16x16x32_bf16 v[76:79], v[184:187], v[172:175], v[76:79]
	v_mfma_f32_16x16x32_bf16 v[72:75], v[188:191], v[172:175], v[72:75]
	s_barrier
	s_mov_b32 m0, s69
	ds_read_b128 v[144:147], v236 offset:49152
	ds_read_b128 v[148:151], v236 offset:51200
	ds_read_b128 v[152:155], v237 offset:49152
	ds_read_b128 v[156:159], v237 offset:51200
	ds_read_b128 v[160:163], v236 offset:53248
	ds_read_b128 v[164:167], v236 offset:55296
	ds_read_b128 v[168:171], v237 offset:53248
	ds_read_b128 v[172:175], v237 offset:55296
	s_add_u32 s80, s6, s38
	s_addc_u32 s81, s7, s39
	s_nop 0
	global_load_lds_dwordx4 v222, s[80:81]
	s_mov_b32 m0, s70
	s_nop 0
	s_add_u32 s80, s6, s40
	s_addc_u32 s81, s7, s41
	s_nop 0
	global_load_lds_dwordx4 v222, s[80:81]
	s_barrier
; template <int K, int EPI, bool MIX = false>
; __device__ __forceinline__ void gemm_phase(const Params& p, const u16* __restrict__ A, const u16* __restrict__ Bt,
;                            const float* __restrict__ rs_in, float* __restrict__ ssq_out, float alpha, bool rev = false) {
;     ...
;           int fr_m = fr;
;           asm volatile("" : "+v"(fr_m));
; #pragma unroll
;           for (int ai = 0; ai < 2; ++ai)
; #pragma unroll
;             for (int m = 0; m < 4; ++m) {
;               const int row = pm * 256 + ai * 128 + wr * 64 + m * 16 + fr_m;
;               const float ra = rsqrtf(p.ssqa[row] * (1.f / 1024.f) + 1e-6f);
;               const float rb = rsqrtf(p.ssqb[row] * (1.f / 1024.f) + 1e-6f);
;               const float f = ra * __builtin_amdgcn_rcpf(rb);
; #pragma unroll
;               for (int bj = 0; bj < 2; ++bj)
; #pragma unroll
;                 for (int n = 0; n < 2; ++n) acc[ai][bj][m][n] *= f;
;             }
	s_waitcnt lgkmcnt(0)
	v_mfma_f32_16x16x32_bf16 v[84:87], v[128:131], v[144:147], v[84:87]
	v_mfma_f32_16x16x32_bf16 v[80:83], v[132:135], v[144:147], v[80:83]
	v_mfma_f32_16x16x32_bf16 v[108:111], v[128:131], v[148:151], v[108:111]
	v_mfma_f32_16x16x32_bf16 v[104:107], v[132:135], v[148:151], v[104:107]
	v_mfma_f32_16x16x32_bf16 v[60:63], v[128:131], v[160:163], v[60:63]
	v_mfma_f32_16x16x32_bf16 v[56:59], v[132:135], v[160:163], v[56:59]
	v_mfma_f32_16x16x32_bf16 v[4:7], v[128:131], v[164:167], v[4:7]
	v_mfma_f32_16x16x32_bf16 v[0:3], v[132:135], v[164:167], v[0:3]
	v_mfma_f32_16x16x32_bf16 v[84:87], v[136:139], v[152:155], v[84:87]
	v_mfma_f32_16x16x32_bf16 v[80:83], v[140:143], v[152:155], v[80:83]
	v_mfma_f32_16x16x32_bf16 v[108:111], v[136:139], v[156:159], v[108:111]
	v_mfma_f32_16x16x32_bf16 v[104:107], v[140:143], v[156:159], v[104:107]
	v_mfma_f32_16x16x32_bf16 v[60:63], v[136:139], v[168:171], v[60:63]
	v_mfma_f32_16x16x32_bf16 v[56:59], v[140:143], v[168:171], v[56:59]
	v_mfma_f32_16x16x32_bf16 v[4:7], v[136:139], v[172:175], v[4:7]
	v_mfma_f32_16x16x32_bf16 v[0:3], v[140:143], v[172:175], v[0:3]
	s_barrier
	s_mov_b32 m0, s71
	s_add_u32 s80, s4, s38
	s_addc_u32 s81, s5, s39
	s_nop 0
	global_load_lds_dwordx4 v222, s[80:81]
	s_mov_b32 m0, s72
	s_nop 0
	s_add_u32 s80, s4, s40
	s_addc_u32 s81, s5, s41
	s_nop 0
	global_load_lds_dwordx4 v222, s[80:81]
	s_waitcnt vmcnt(6)
	s_barrier
	v_mfma_f32_16x16x32_bf16 v[112:115], v[176:179], v[144:147], v[112:115]
	v_mfma_f32_16x16x32_bf16 v[128:131], v[184:187], v[152:155], v[112:115]
	v_mfma_f32_16x16x32_bf16 v[112:115], v[180:183], v[144:147], v[116:119]
	v_mfma_f32_16x16x32_bf16 v[132:135], v[188:191], v[152:155], v[112:115]
	v_mfma_f32_16x16x32_bf16 v[112:115], v[176:179], v[148:151], v[120:123]
	v_mfma_f32_16x16x32_bf16 v[120:123], v[184:187], v[156:159], v[112:115]
	v_mfma_f32_16x16x32_bf16 v[112:115], v[180:183], v[148:151], v[124:127]
	v_mfma_f32_16x16x32_bf16 v[88:91], v[176:179], v[160:163], v[88:91]
	v_mfma_f32_16x16x32_bf16 v[92:95], v[180:183], v[160:163], v[92:95]
	v_mfma_f32_16x16x32_bf16 v[12:15], v[176:179], v[164:167], v[12:15]
	v_mfma_f32_16x16x32_bf16 v[8:11], v[180:183], v[164:167], v[8:11]
	v_mfma_f32_16x16x32_bf16 v[124:127], v[188:191], v[156:159], v[112:115]
	v_mfma_f32_16x16x32_bf16 v[88:91], v[184:187], v[168:171], v[88:91]
	v_mfma_f32_16x16x32_bf16 v[92:95], v[188:191], v[168:171], v[92:95]
	v_mfma_f32_16x16x32_bf16 v[12:15], v[184:187], v[172:175], v[12:15]
	v_mfma_f32_16x16x32_bf16 v[8:11], v[188:191], v[172:175], v[8:11]
	s_barrier
	s_add_i32 s33, s33, 2
	s_add_u32 s60, s60, 0x100
	s_addc_u32 s61, s61, 0
	s_add_u32 s6, s6, 0x100
	s_addc_u32 s7, s7, 0
	s_add_u32 s4, s4, 0x100
	s_addc_u32 s5, s5, 0
	s_cmp_lt_u32 s33, 14
	s_cbranch_scc1 .LBB0_365
	v_mov_b32_e32 v112, v233
	s_lshl_b32 s79, s35, 8
	s_add_i32 s79, s79, s73
	v_add_u32_e32 v112, s79, v112
	v_ashrrev_i32_e32 v113, 31, v112
	v_lshlrev_b64 v[112:113], 2, v[112:113]
	v_lshl_add_u64 v[138:139], s[86:87], 0, v[112:113]
	global_load_dword v114, v[138:139], off
	v_lshl_add_u64 v[136:137], s[88:89], 0, v[112:113]
	global_load_dword v112, v[136:137], off
	s_mov_b32 s33, 14
	s_mov_b64 s[4:5], s[16:17]
	s_mov_b64 s[6:7], s[8:9]
	s_mov_b64 s[60:61], s[12:13]
	s_waitcnt vmcnt(0)
	v_fmamk_f32 v114, v114, 0x3a800000, v244
	v_cmp_gt_f32_e32 vcc, s76, v114
	v_mul_f32_e32 v115, 0x4b800000, v114
	v_fmamk_f32 v112, v112, 0x3a800000, v244
	v_cndmask_b32_e32 v114, v114, v115, vcc
	v_rsq_f32_e32 v114, v114
	v_mul_f32_e32 v113, 0x4b800000, v112
	v_mul_f32_e32 v115, 0x45800000, v114
	v_cndmask_b32_e32 v114, v114, v115, vcc
	v_cmp_gt_f32_e32 vcc, s76, v112
	s_nop 1
	v_cndmask_b32_e32 v112, v112, v113, vcc
	v_rsq_f32_e32 v112, v112
	s_nop 0
	v_mul_f32_e32 v113, 0x45800000, v112
	v_cndmask_b32_e32 v112, v112, v113, vcc
	v_rcp_f32_e32 v112, v112
	s_nop 0
	v_mul_f32_e32 v112, v114, v112
	v_pk_mul_f32 v[30:31], v[30:31], v[112:113] op_sel_hi:[1,0]
	v_pk_mul_f32 v[28:29], v[28:29], v[112:113] op_sel_hi:[1,0]
	v_pk_mul_f32 v[26:27], v[26:27], v[112:113] op_sel_hi:[1,0]
	v_pk_mul_f32 v[24:25], v[24:25], v[112:113] op_sel_hi:[1,0]
	v_pk_mul_f32 v[22:23], v[22:23], v[112:113] op_sel_hi:[1,0]
	v_pk_mul_f32 v[20:21], v[20:21], v[112:113] op_sel_hi:[1,0]
	v_pk_mul_f32 v[18:19], v[18:19], v[112:113] op_sel_hi:[1,0]
	v_pk_mul_f32 v[16:17], v[16:17], v[112:113] op_sel_hi:[1,0]
	global_load_dword v112, v[138:139], off offset:64
	s_waitcnt vmcnt(0)
	v_fmamk_f32 v112, v112, 0x3a800000, v244
	v_cmp_gt_f32_e32 vcc, s76, v112
	v_mul_f32_e32 v113, 0x4b800000, v112
	s_nop 0
	v_cndmask_b32_e32 v112, v112, v113, vcc
	v_rsq_f32_e32 v112, v112
	s_nop 0
	v_mul_f32_e32 v113, 0x45800000, v112
	v_cndmask_b32_e32 v112, v112, v113, vcc
	global_load_dword v113, v[136:137], off offset:64
	s_waitcnt vmcnt(0)
	v_fmamk_f32 v113, v113, 0x3a800000, v244
	v_cmp_gt_f32_e32 vcc, s76, v113
	v_mul_f32_e32 v114, 0x4b800000, v113
	s_nop 0
	v_cndmask_b32_e32 v113, v113, v114, vcc
	v_rsq_f32_e32 v113, v113
	s_nop 0
	v_mul_f32_e32 v114, 0x45800000, v113
	v_cndmask_b32_e32 v113, v113, v114, vcc
	v_rcp_f32_e32 v113, v113
	s_nop 0
	v_mul_f32_e32 v112, v112, v113
	v_pk_mul_f32 v[46:47], v[46:47], v[112:113] op_sel_hi:[1,0]
	v_pk_mul_f32 v[44:45], v[44:45], v[112:113] op_sel_hi:[1,0]
	v_pk_mul_f32 v[42:43], v[42:43], v[112:113] op_sel_hi:[1,0]
	v_pk_mul_f32 v[40:41], v[40:41], v[112:113] op_sel_hi:[1,0]
	v_pk_mul_f32 v[38:39], v[38:39], v[112:113] op_sel_hi:[1,0]
	v_pk_mul_f32 v[36:37], v[36:37], v[112:113] op_sel_hi:[1,0]
	v_pk_mul_f32 v[34:35], v[34:35], v[112:113] op_sel_hi:[1,0]
	v_pk_mul_f32 v[32:33], v[32:33], v[112:113] op_sel_hi:[1,0]
	global_load_dword v112, v[138:139], off offset:128
	s_waitcnt vmcnt(0)
; template <int K, int EPI, bool MIX = false>
; __device__ __forceinline__ void gemm_phase(const Params& p, const u16* __restrict__ A, const u16* __restrict__ Bt,
;                            const float* __restrict__ rs_in, float* __restrict__ ssq_out, float alpha, bool rev = false) {
;     ...
;           for (int ai = 0; ai < 2; ++ai)
; #pragma unroll
;             for (int m = 0; m < 4; ++m) {
;               const int row = pm * 256 + ai * 128 + wr * 64 + m * 16 + fr_m;
;               const float ra = rsqrtf(p.ssqa[row] * (1.f / 1024.f) + 1e-6f);
;               const float rb = rsqrtf(p.ssqb[row] * (1.f / 1024.f) + 1e-6f);
;               const float f = ra * __builtin_amdgcn_rcpf(rb);
; #pragma unroll
;               for (int bj = 0; bj < 2; ++bj)
; #pragma unroll
;                 for (int n = 0; n < 2; ++n) acc[ai][bj][m][n] *= f;
;             }
	v_fmamk_f32 v112, v112, 0x3a800000, v244
	v_cmp_gt_f32_e32 vcc, s76, v112
	v_mul_f32_e32 v113, 0x4b800000, v112
	s_nop 0
	v_cndmask_b32_e32 v112, v112, v113, vcc
	v_rsq_f32_e32 v112, v112
	s_nop 0
	v_mul_f32_e32 v113, 0x45800000, v112
	v_cndmask_b32_e32 v112, v112, v113, vcc
	global_load_dword v113, v[136:137], off offset:128
	s_waitcnt vmcnt(0)
	v_fmamk_f32 v113, v113, 0x3a800000, v244
	v_cmp_gt_f32_e32 vcc, s76, v113
	v_mul_f32_e32 v114, 0x4b800000, v113
	s_nop 0
	v_cndmask_b32_e32 v113, v113, v114, vcc
	v_rsq_f32_e32 v113, v113
	s_nop 0
	v_mul_f32_e32 v114, 0x45800000, v113
	v_cndmask_b32_e32 v113, v113, v114, vcc
	v_rcp_f32_e32 v113, v113
	s_nop 0
	v_mul_f32_e32 v112, v112, v113
	v_pk_mul_f32 v[70:71], v[70:71], v[112:113] op_sel_hi:[1,0]
	v_pk_mul_f32 v[68:69], v[68:69], v[112:113] op_sel_hi:[1,0]
	v_pk_mul_f32 v[66:67], v[66:67], v[112:113] op_sel_hi:[1,0]
	v_pk_mul_f32 v[64:65], v[64:65], v[112:113] op_sel_hi:[1,0]
	v_pk_mul_f32 v[54:55], v[54:55], v[112:113] op_sel_hi:[1,0]
	v_pk_mul_f32 v[52:53], v[52:53], v[112:113] op_sel_hi:[1,0]
	v_pk_mul_f32 v[50:51], v[50:51], v[112:113] op_sel_hi:[1,0]
	v_pk_mul_f32 v[48:49], v[48:49], v[112:113] op_sel_hi:[1,0]
	global_load_dword v112, v[138:139], off offset:192
	s_waitcnt vmcnt(0)
	v_fmamk_f32 v112, v112, 0x3a800000, v244
	v_cmp_gt_f32_e32 vcc, s76, v112
	v_mul_f32_e32 v113, 0x4b800000, v112
	s_nop 0
	v_cndmask_b32_e32 v112, v112, v113, vcc
	v_rsq_f32_e32 v112, v112
	s_nop 0
	v_mul_f32_e32 v113, 0x45800000, v112
	v_cndmask_b32_e32 v112, v112, v113, vcc
	global_load_dword v113, v[136:137], off offset:192
	s_waitcnt vmcnt(0)
	v_fmamk_f32 v113, v113, 0x3a800000, v244
	v_cmp_gt_f32_e32 vcc, s76, v113
	v_mul_f32_e32 v114, 0x4b800000, v113
	s_nop 0
	v_cndmask_b32_e32 v113, v113, v114, vcc
	v_rsq_f32_e32 v113, v113
	s_nop 0
	v_mul_f32_e32 v114, 0x45800000, v113
	v_cndmask_b32_e32 v113, v113, v114, vcc
	v_rcp_f32_e32 v113, v113
	s_nop 0
	v_mul_f32_e32 v140, v112, v113
	v_pk_mul_f32 v[112:113], v[96:97], v[140:141] op_sel_hi:[1,0]
	global_load_dword v96, v[138:139], off offset:512
	v_pk_mul_f32 v[114:115], v[98:99], v[140:141] op_sel_hi:[1,0]
	v_pk_mul_f32 v[118:119], v[102:103], v[140:141] op_sel_hi:[1,0]
	v_pk_mul_f32 v[116:117], v[100:101], v[140:141] op_sel_hi:[1,0]
	v_pk_mul_f32 v[78:79], v[78:79], v[140:141] op_sel_hi:[1,0]
	v_pk_mul_f32 v[76:77], v[76:77], v[140:141] op_sel_hi:[1,0]
	v_pk_mul_f32 v[74:75], v[74:75], v[140:141] op_sel_hi:[1,0]
	v_pk_mul_f32 v[72:73], v[72:73], v[140:141] op_sel_hi:[1,0]
	s_waitcnt vmcnt(0)
	v_fmamk_f32 v96, v96, 0x3a800000, v244
	v_cmp_gt_f32_e32 vcc, s76, v96
	v_mul_f32_e32 v97, 0x4b800000, v96
	s_nop 0
	v_cndmask_b32_e32 v96, v96, v97, vcc
	v_rsq_f32_e32 v96, v96
	s_nop 0
	v_mul_f32_e32 v97, 0x45800000, v96
	v_cndmask_b32_e32 v96, v96, v97, vcc
	global_load_dword v97, v[136:137], off offset:512
	s_waitcnt vmcnt(0)
	v_fmamk_f32 v97, v97, 0x3a800000, v244
	v_cmp_gt_f32_e32 vcc, s76, v97
	v_mul_f32_e32 v98, 0x4b800000, v97
	s_nop 0
	v_cndmask_b32_e32 v97, v97, v98, vcc
	v_rsq_f32_e32 v97, v97
	s_nop 0
	v_mul_f32_e32 v98, 0x45800000, v97
	v_cndmask_b32_e32 v97, v97, v98, vcc
	v_rcp_f32_e32 v97, v97
	s_nop 0
	v_mul_f32_e32 v140, v96, v97
	v_pk_mul_f32 v[96:97], v[80:81], v[140:141] op_sel_hi:[1,0]
	v_pk_mul_f32 v[80:81], v[128:129], v[140:141] op_sel_hi:[1,0]
	global_load_dword v128, v[138:139], off offset:576
	v_pk_mul_f32 v[98:99], v[82:83], v[140:141] op_sel_hi:[1,0]
	v_pk_mul_f32 v[82:83], v[130:131], v[140:141] op_sel_hi:[1,0]
	v_pk_mul_f32 v[102:103], v[86:87], v[140:141] op_sel_hi:[1,0]
	v_pk_mul_f32 v[100:101], v[84:85], v[140:141] op_sel_hi:[1,0]
	v_pk_mul_f32 v[86:87], v[134:135], v[140:141] op_sel_hi:[1,0]
	v_pk_mul_f32 v[84:85], v[132:133], v[140:141] op_sel_hi:[1,0]
	s_waitcnt vmcnt(0)
	v_fmamk_f32 v128, v128, 0x3a800000, v244
	v_cmp_gt_f32_e32 vcc, s76, v128
	v_mul_f32_e32 v129, 0x4b800000, v128
	s_nop 0
	v_cndmask_b32_e32 v128, v128, v129, vcc
	v_rsq_f32_e32 v128, v128
	s_nop 0
	v_mul_f32_e32 v129, 0x45800000, v128
	v_cndmask_b32_e32 v128, v128, v129, vcc
	global_load_dword v129, v[136:137], off offset:576
	s_waitcnt vmcnt(0)
	v_fmamk_f32 v129, v129, 0x3a800000, v244
	v_cmp_gt_f32_e32 vcc, s76, v129
	v_mul_f32_e32 v130, 0x4b800000, v129
	s_nop 0
	v_cndmask_b32_e32 v129, v129, v130, vcc
	v_rsq_f32_e32 v129, v129
	s_nop 0
	v_mul_f32_e32 v130, 0x45800000, v129
	v_cndmask_b32_e32 v129, v129, v130, vcc
	v_rcp_f32_e32 v129, v129
	s_nop 0
	v_mul_f32_e32 v140, v128, v129
	v_pk_mul_f32 v[128:129], v[104:105], v[140:141] op_sel_hi:[1,0]
	v_pk_mul_f32 v[104:105], v[120:121], v[140:141] op_sel_hi:[1,0]
	global_load_dword v120, v[138:139], off offset:640
	v_pk_mul_f32 v[130:131], v[106:107], v[140:141] op_sel_hi:[1,0]
	v_pk_mul_f32 v[106:107], v[122:123], v[140:141] op_sel_hi:[1,0]
	v_pk_mul_f32 v[134:135], v[110:111], v[140:141] op_sel_hi:[1,0]
	v_pk_mul_f32 v[132:133], v[108:109], v[140:141] op_sel_hi:[1,0]
	v_pk_mul_f32 v[110:111], v[126:127], v[140:141] op_sel_hi:[1,0]
	v_pk_mul_f32 v[108:109], v[124:125], v[140:141] op_sel_hi:[1,0]
	s_waitcnt vmcnt(0)
	v_fmamk_f32 v120, v120, 0x3a800000, v244
	v_cmp_gt_f32_e32 vcc, s76, v120
	v_mul_f32_e32 v121, 0x4b800000, v120
	s_nop 0
	v_cndmask_b32_e32 v120, v120, v121, vcc
	v_rsq_f32_e32 v120, v120
	s_nop 0
	v_mul_f32_e32 v121, 0x45800000, v120
	v_cndmask_b32_e32 v120, v120, v121, vcc
	global_load_dword v121, v[136:137], off offset:640
	s_waitcnt vmcnt(0)
; template <int K, int EPI, bool MIX = false>
; __device__ __forceinline__ void gemm_phase(const Params& p, const u16* __restrict__ A, const u16* __restrict__ Bt,
;                            const float* __restrict__ rs_in, float* __restrict__ ssq_out, float alpha, bool rev = false) {
;     ...
;               const float ra = rsqrtf(p.ssqa[row] * (1.f / 1024.f) + 1e-6f);
;               const float rb = rsqrtf(p.ssqb[row] * (1.f / 1024.f) + 1e-6f);
;               const float f = ra * __builtin_amdgcn_rcpf(rb);
; #pragma unroll
;               for (int bj = 0; bj < 2; ++bj)
; #pragma unroll
;                 for (int n = 0; n < 2; ++n) acc[ai][bj][m][n] *= f;
	v_fmamk_f32 v121, v121, 0x3a800000, v244
	v_cmp_gt_f32_e32 vcc, s76, v121
	v_mul_f32_e32 v122, 0x4b800000, v121
	s_nop 0
	v_cndmask_b32_e32 v121, v121, v122, vcc
	v_rsq_f32_e32 v121, v121
	s_nop 0
	v_mul_f32_e32 v122, 0x45800000, v121
	v_cndmask_b32_e32 v121, v121, v122, vcc
	v_rcp_f32_e32 v121, v121
	s_nop 0
	v_mul_f32_e32 v140, v120, v121
	v_pk_mul_f32 v[120:121], v[56:57], v[140:141] op_sel_hi:[1,0]
	v_pk_mul_f32 v[56:57], v[88:89], v[140:141] op_sel_hi:[1,0]
	global_load_dword v88, v[138:139], off offset:704
	v_pk_mul_f32 v[122:123], v[58:59], v[140:141] op_sel_hi:[1,0]
	v_pk_mul_f32 v[58:59], v[90:91], v[140:141] op_sel_hi:[1,0]
	v_pk_mul_f32 v[126:127], v[62:63], v[140:141] op_sel_hi:[1,0]
	v_pk_mul_f32 v[124:125], v[60:61], v[140:141] op_sel_hi:[1,0]
	v_pk_mul_f32 v[62:63], v[94:95], v[140:141] op_sel_hi:[1,0]
	v_pk_mul_f32 v[60:61], v[92:93], v[140:141] op_sel_hi:[1,0]
	s_waitcnt vmcnt(0)
	v_fmamk_f32 v88, v88, 0x3a800000, v244
	v_cmp_gt_f32_e32 vcc, s76, v88
	v_mul_f32_e32 v89, 0x4b800000, v88
	s_nop 0
	v_cndmask_b32_e32 v88, v88, v89, vcc
	v_rsq_f32_e32 v88, v88
	s_nop 0
	v_mul_f32_e32 v89, 0x45800000, v88
	v_cndmask_b32_e32 v88, v88, v89, vcc
	global_load_dword v89, v[136:137], off offset:704
	s_waitcnt vmcnt(0)
	v_fmamk_f32 v89, v89, 0x3a800000, v244
	v_cmp_gt_f32_e32 vcc, s76, v89
	v_mul_f32_e32 v90, 0x4b800000, v89
	s_nop 0
	v_cndmask_b32_e32 v89, v89, v90, vcc
	v_rsq_f32_e32 v89, v89
	s_nop 0
	v_mul_f32_e32 v90, 0x45800000, v89
	v_cndmask_b32_e32 v89, v89, v90, vcc
	v_rcp_f32_e32 v89, v89
	s_nop 0
	v_mul_f32_e32 v136, v88, v89
	v_pk_mul_f32 v[90:91], v[6:7], v[136:137] op_sel_hi:[1,0]
	v_pk_mul_f32 v[88:89], v[4:5], v[136:137] op_sel_hi:[1,0]
	v_pk_mul_f32 v[94:95], v[2:3], v[136:137] op_sel_hi:[1,0]
	v_pk_mul_f32 v[92:93], v[0:1], v[136:137] op_sel_hi:[1,0]
	v_pk_mul_f32 v[2:3], v[14:15], v[136:137] op_sel_hi:[1,0]
	v_pk_mul_f32 v[0:1], v[12:13], v[136:137] op_sel_hi:[1,0]
	v_pk_mul_f32 v[6:7], v[10:11], v[136:137] op_sel_hi:[1,0]
	v_pk_mul_f32 v[4:5], v[8:9], v[136:137] op_sel_hi:[1,0]
.LBB0_367:
	ds_read_b128 v[8:11], v234
	ds_read_b128 v[12:15], v234 offset:2048
	ds_read_b128 v[136:139], v235
	ds_read_b128 v[140:143], v235 offset:2048
	s_mov_b32 m0, s74
	ds_read_b128 v[144:147], v236
	ds_read_b128 v[148:151], v236 offset:2048
	ds_read_b128 v[152:155], v237
	ds_read_b128 v[156:159], v237 offset:2048
	ds_read_b128 v[160:163], v236 offset:4096
	ds_read_b128 v[164:167], v236 offset:6144
	ds_read_b128 v[168:171], v237 offset:4096
	ds_read_b128 v[172:175], v237 offset:6144
	s_add_u32 s80, s6, 0x80880
	s_addc_u32 s81, s7, 0x0
	s_nop 0
	global_load_lds_dwordx4 v222, s[80:81]
	s_mov_b32 m0, s75
	s_nop 0
	s_add_u32 s80, s6, 0xc0880
	s_addc_u32 s81, s7, 0x0
	s_nop 0
	global_load_lds_dwordx4 v222, s[80:81]
	s_waitcnt lgkmcnt(8)
	s_barrier
	s_waitcnt lgkmcnt(0)
	v_mfma_f32_16x16x32_bf16 v[28:31], v[8:11], v[144:147], v[28:31]
	v_mfma_f32_16x16x32_bf16 v[24:27], v[12:15], v[144:147], v[24:27]
	v_mfma_f32_16x16x32_bf16 v[44:47], v[8:11], v[148:151], v[44:47]
	v_mfma_f32_16x16x32_bf16 v[40:43], v[12:15], v[148:151], v[40:43]
	v_mfma_f32_16x16x32_bf16 v[68:71], v[8:11], v[160:163], v[68:71]
	v_mfma_f32_16x16x32_bf16 v[64:67], v[12:15], v[160:163], v[64:67]
	v_mfma_f32_16x16x32_bf16 v[116:119], v[8:11], v[164:167], v[116:119]
	v_mfma_f32_16x16x32_bf16 v[112:115], v[12:15], v[164:167], v[112:115]
	v_mfma_f32_16x16x32_bf16 v[28:31], v[136:139], v[152:155], v[28:31]
	v_mfma_f32_16x16x32_bf16 v[24:27], v[140:143], v[152:155], v[24:27]
	v_mfma_f32_16x16x32_bf16 v[44:47], v[136:139], v[156:159], v[44:47]
	v_mfma_f32_16x16x32_bf16 v[40:43], v[140:143], v[156:159], v[40:43]
	v_mfma_f32_16x16x32_bf16 v[68:71], v[136:139], v[168:171], v[68:71]
	v_mfma_f32_16x16x32_bf16 v[64:67], v[140:143], v[168:171], v[64:67]
	v_mfma_f32_16x16x32_bf16 v[116:119], v[136:139], v[172:175], v[116:119]
	v_mfma_f32_16x16x32_bf16 v[112:115], v[140:143], v[172:175], v[112:115]
	s_barrier
	s_mov_b32 m0, s42
	ds_read_b128 v[176:179], v238
	ds_read_b128 v[180:183], v238 offset:2048
	ds_read_b128 v[184:187], v239
	ds_read_b128 v[188:191], v239 offset:2048
	s_add_u32 s80, s60, s46
	s_addc_u32 s81, s61, s47
	s_nop 0
	global_load_lds_dwordx4 v222, s[80:81]
	s_mov_b32 m0, s43
	s_nop 0
	s_add_u32 s80, s60, s48
	s_addc_u32 s81, s61, s49
	s_nop 0
	global_load_lds_dwordx4 v222, s[80:81]
	s_barrier
	s_waitcnt lgkmcnt(0)
	v_mfma_f32_16x16x32_bf16 v[20:23], v[176:179], v[144:147], v[20:23]
	v_mfma_f32_16x16x32_bf16 v[16:19], v[180:183], v[144:147], v[16:19]
	v_mfma_f32_16x16x32_bf16 v[36:39], v[176:179], v[148:151], v[36:39]
	v_mfma_f32_16x16x32_bf16 v[32:35], v[180:183], v[148:151], v[32:35]
	v_mfma_f32_16x16x32_bf16 v[52:55], v[176:179], v[160:163], v[52:55]
	v_mfma_f32_16x16x32_bf16 v[48:51], v[180:183], v[160:163], v[48:51]
	v_mfma_f32_16x16x32_bf16 v[76:79], v[176:179], v[164:167], v[76:79]
	v_mfma_f32_16x16x32_bf16 v[72:75], v[180:183], v[164:167], v[72:75]
	v_mfma_f32_16x16x32_bf16 v[20:23], v[184:187], v[152:155], v[20:23]
	v_mfma_f32_16x16x32_bf16 v[16:19], v[188:191], v[152:155], v[16:19]
	v_mfma_f32_16x16x32_bf16 v[36:39], v[184:187], v[156:159], v[36:39]
	v_mfma_f32_16x16x32_bf16 v[32:35], v[188:191], v[156:159], v[32:35]
	v_mfma_f32_16x16x32_bf16 v[52:55], v[184:187], v[168:171], v[52:55]
	v_mfma_f32_16x16x32_bf16 v[48:51], v[188:191], v[168:171], v[48:51]
	v_mfma_f32_16x16x32_bf16 v[76:79], v[184:187], v[172:175], v[76:79]
	v_mfma_f32_16x16x32_bf16 v[72:75], v[188:191], v[172:175], v[72:75]
	s_barrier
	s_mov_b32 m0, s34
	ds_read_b128 v[144:147], v236 offset:16384
	ds_read_b128 v[148:151], v236 offset:18432
	ds_read_b128 v[152:155], v237 offset:16384
	ds_read_b128 v[156:159], v237 offset:18432
	ds_read_b128 v[160:163], v236 offset:20480
	ds_read_b128 v[164:167], v236 offset:22528
	ds_read_b128 v[168:171], v237 offset:20480
	ds_read_b128 v[172:175], v237 offset:22528
	s_add_u32 s80, s6, s46
	s_addc_u32 s81, s7, s47
	s_nop 0
	global_load_lds_dwordx4 v222, s[80:81]
	s_mov_b32 m0, s44
	s_nop 0
	s_add_u32 s80, s6, s48
	s_addc_u32 s81, s7, s49
	s_nop 0
	global_load_lds_dwordx4 v222, s[80:81]
	s_barrier
	s_waitcnt lgkmcnt(0)
	v_mfma_f32_16x16x32_bf16 v[100:103], v[8:11], v[144:147], v[100:103]
	v_mfma_f32_16x16x32_bf16 v[96:99], v[12:15], v[144:147], v[96:99]
	v_mfma_f32_16x16x32_bf16 v[132:135], v[8:11], v[148:151], v[132:135]
	v_mfma_f32_16x16x32_bf16 v[128:131], v[12:15], v[148:151], v[128:131]
	v_mfma_f32_16x16x32_bf16 v[124:127], v[8:11], v[160:163], v[124:127]
	v_mfma_f32_16x16x32_bf16 v[120:123], v[12:15], v[160:163], v[120:123]
	v_mfma_f32_16x16x32_bf16 v[100:103], v[136:139], v[152:155], v[100:103]
	v_mfma_f32_16x16x32_bf16 v[96:99], v[140:143], v[152:155], v[96:99]
	v_mfma_f32_16x16x32_bf16 v[132:135], v[136:139], v[156:159], v[132:135]
	v_mfma_f32_16x16x32_bf16 v[128:131], v[140:143], v[156:159], v[128:131]
	v_mfma_f32_16x16x32_bf16 v[124:127], v[136:139], v[168:171], v[124:127]
	v_mfma_f32_16x16x32_bf16 v[120:123], v[140:143], v[168:171], v[120:123]
	v_mfma_f32_16x16x32_bf16 v[8:11], v[8:11], v[164:167], v[88:91]
	v_mfma_f32_16x16x32_bf16 v[12:15], v[12:15], v[164:167], v[92:95]
	v_mfma_f32_16x16x32_bf16 v[8:11], v[136:139], v[172:175], v[8:11]
	v_mfma_f32_16x16x32_bf16 v[12:15], v[140:143], v[172:175], v[12:15]
	s_barrier
	s_mov_b32 m0, s45
	s_add_u32 s80, s4, s46
	s_addc_u32 s81, s5, s47
	s_nop 0
	global_load_lds_dwordx4 v222, s[80:81]
	s_mov_b32 m0, s62
	s_nop 0
	s_add_u32 s80, s4, s48
	s_addc_u32 s81, s5, s49
	s_nop 0
	global_load_lds_dwordx4 v222, s[80:81]
	s_waitcnt vmcnt(6)
	s_barrier
	v_mfma_f32_16x16x32_bf16 v[88:91], v[176:179], v[148:151], v[104:107]
	v_mfma_f32_16x16x32_bf16 v[80:83], v[176:179], v[144:147], v[80:83]
	v_mfma_f32_16x16x32_bf16 v[84:87], v[180:183], v[144:147], v[84:87]
	v_mfma_f32_16x16x32_bf16 v[104:107], v[184:187], v[156:159], v[88:91]
	v_mfma_f32_16x16x32_bf16 v[88:91], v[180:183], v[148:151], v[108:111]
	v_mfma_f32_16x16x32_bf16 v[56:59], v[176:179], v[160:163], v[56:59]
	v_mfma_f32_16x16x32_bf16 v[60:63], v[180:183], v[160:163], v[60:63]
	v_mfma_f32_16x16x32_bf16 v[0:3], v[176:179], v[164:167], v[0:3]
	v_mfma_f32_16x16x32_bf16 v[4:7], v[180:183], v[164:167], v[4:7]
	v_mfma_f32_16x16x32_bf16 v[80:83], v[184:187], v[152:155], v[80:83]
	v_mfma_f32_16x16x32_bf16 v[84:87], v[188:191], v[152:155], v[84:87]
	v_mfma_f32_16x16x32_bf16 v[108:111], v[188:191], v[156:159], v[88:91]
	v_mfma_f32_16x16x32_bf16 v[56:59], v[184:187], v[168:171], v[56:59]
	v_mfma_f32_16x16x32_bf16 v[60:63], v[188:191], v[168:171], v[60:63]
	v_mfma_f32_16x16x32_bf16 v[0:3], v[184:187], v[172:175], v[0:3]
	v_mfma_f32_16x16x32_bf16 v[4:7], v[188:191], v[172:175], v[4:7]
	s_barrier
	ds_read_b128 v[88:91], v240
	ds_read_b128 v[92:95], v240 offset:2048
	ds_read_b128 v[136:139], v241
	ds_read_b128 v[140:143], v241 offset:2048
	s_mov_b32 m0, s63
	ds_read_b128 v[144:147], v236 offset:32768
	ds_read_b128 v[148:151], v236 offset:34816
	ds_read_b128 v[152:155], v237 offset:32768
	ds_read_b128 v[156:159], v237 offset:34816
	ds_read_b128 v[160:163], v236 offset:36864
	ds_read_b128 v[164:167], v236 offset:38912
	ds_read_b128 v[168:171], v237 offset:36864
	ds_read_b128 v[172:175], v237 offset:38912
	s_add_u32 s80, s6, 0x80900
	s_addc_u32 s81, s7, 0x0
	s_nop 0
	global_load_lds_dwordx4 v222, s[80:81]
	s_mov_b32 m0, s64
	s_nop 0
	s_add_u32 s80, s6, 0xc0900
	s_addc_u32 s81, s7, 0x0
	s_nop 0
	global_load_lds_dwordx4 v222, s[80:81]
	s_waitcnt lgkmcnt(8)
	s_barrier
	s_waitcnt lgkmcnt(0)
	v_mfma_f32_16x16x32_bf16 v[28:31], v[88:91], v[144:147], v[28:31]
	v_mfma_f32_16x16x32_bf16 v[24:27], v[92:95], v[144:147], v[24:27]
	v_mfma_f32_16x16x32_bf16 v[44:47], v[88:91], v[148:151], v[44:47]
	v_mfma_f32_16x16x32_bf16 v[40:43], v[92:95], v[148:151], v[40:43]
	v_mfma_f32_16x16x32_bf16 v[68:71], v[88:91], v[160:163], v[68:71]
	v_mfma_f32_16x16x32_bf16 v[64:67], v[92:95], v[160:163], v[64:67]
	v_mfma_f32_16x16x32_bf16 v[116:119], v[88:91], v[164:167], v[116:119]
	v_mfma_f32_16x16x32_bf16 v[112:115], v[92:95], v[164:167], v[112:115]
	v_mfma_f32_16x16x32_bf16 v[28:31], v[136:139], v[152:155], v[28:31]
	v_mfma_f32_16x16x32_bf16 v[24:27], v[140:143], v[152:155], v[24:27]
	v_mfma_f32_16x16x32_bf16 v[44:47], v[136:139], v[156:159], v[44:47]
	v_mfma_f32_16x16x32_bf16 v[40:43], v[140:143], v[156:159], v[40:43]
	v_mfma_f32_16x16x32_bf16 v[68:71], v[136:139], v[168:171], v[68:71]
	v_mfma_f32_16x16x32_bf16 v[64:67], v[140:143], v[168:171], v[64:67]
	v_mfma_f32_16x16x32_bf16 v[116:119], v[136:139], v[172:175], v[116:119]
	v_mfma_f32_16x16x32_bf16 v[112:115], v[140:143], v[172:175], v[112:115]
	s_barrier
	s_mov_b32 m0, s65
	ds_read_b128 v[176:179], v242
	ds_read_b128 v[180:183], v242 offset:2048
	ds_read_b128 v[184:187], v243
	ds_read_b128 v[188:191], v243 offset:2048
	s_add_u32 s80, s60, s50
	s_addc_u32 s81, s61, s51
	s_nop 0
	global_load_lds_dwordx4 v222, s[80:81]
	s_mov_b32 m0, s68
	s_nop 0
	s_add_u32 s80, s60, s58
	s_addc_u32 s81, s61, s59
	s_nop 0
	global_load_lds_dwordx4 v222, s[80:81]
	s_barrier
	s_waitcnt lgkmcnt(0)
	v_mfma_f32_16x16x32_bf16 v[20:23], v[176:179], v[144:147], v[20:23]
	v_mfma_f32_16x16x32_bf16 v[16:19], v[180:183], v[144:147], v[16:19]
	v_mfma_f32_16x16x32_bf16 v[36:39], v[176:179], v[148:151], v[36:39]
	v_mfma_f32_16x16x32_bf16 v[32:35], v[180:183], v[148:151], v[32:35]
	v_mfma_f32_16x16x32_bf16 v[52:55], v[176:179], v[160:163], v[52:55]
	v_mfma_f32_16x16x32_bf16 v[48:51], v[180:183], v[160:163], v[48:51]
	v_mfma_f32_16x16x32_bf16 v[76:79], v[176:179], v[164:167], v[76:79]
	v_mfma_f32_16x16x32_bf16 v[72:75], v[180:183], v[164:167], v[72:75]
	v_mfma_f32_16x16x32_bf16 v[20:23], v[184:187], v[152:155], v[20:23]
	v_mfma_f32_16x16x32_bf16 v[16:19], v[188:191], v[152:155], v[16:19]
	v_mfma_f32_16x16x32_bf16 v[36:39], v[184:187], v[156:159], v[36:39]
	v_mfma_f32_16x16x32_bf16 v[32:35], v[188:191], v[156:159], v[32:35]
	v_mfma_f32_16x16x32_bf16 v[52:55], v[184:187], v[168:171], v[52:55]
	v_mfma_f32_16x16x32_bf16 v[48:51], v[188:191], v[168:171], v[48:51]
	v_mfma_f32_16x16x32_bf16 v[76:79], v[184:187], v[172:175], v[76:79]
	v_mfma_f32_16x16x32_bf16 v[72:75], v[188:191], v[172:175], v[72:75]
	s_barrier
	s_mov_b32 m0, s69
	ds_read_b128 v[144:147], v236 offset:49152
	ds_read_b128 v[148:151], v236 offset:51200
	ds_read_b128 v[152:155], v237 offset:49152
	ds_read_b128 v[156:159], v237 offset:51200
	ds_read_b128 v[160:163], v236 offset:53248
	ds_read_b128 v[164:167], v236 offset:55296
	ds_read_b128 v[168:171], v237 offset:53248
	ds_read_b128 v[172:175], v237 offset:55296
	s_add_u32 s80, s6, s50
	s_addc_u32 s81, s7, s51
	s_nop 0
	global_load_lds_dwordx4 v222, s[80:81]
	s_mov_b32 m0, s70
	s_nop 0
	s_add_u32 s80, s6, s58
	s_addc_u32 s81, s7, s59
	s_nop 0
	global_load_lds_dwordx4 v222, s[80:81]
	s_barrier
	s_waitcnt lgkmcnt(0)
	v_mfma_f32_16x16x32_bf16 v[8:11], v[88:91], v[164:167], v[8:11]
	v_mfma_f32_16x16x32_bf16 v[100:103], v[88:91], v[144:147], v[100:103]
	v_mfma_f32_16x16x32_bf16 v[96:99], v[92:95], v[144:147], v[96:99]
	v_mfma_f32_16x16x32_bf16 v[132:135], v[88:91], v[148:151], v[132:135]
	v_mfma_f32_16x16x32_bf16 v[128:131], v[92:95], v[148:151], v[128:131]
	v_mfma_f32_16x16x32_bf16 v[124:127], v[88:91], v[160:163], v[124:127]
	v_mfma_f32_16x16x32_bf16 v[120:123], v[92:95], v[160:163], v[120:123]
	v_mfma_f32_16x16x32_bf16 v[88:91], v[136:139], v[172:175], v[8:11]
	v_mfma_f32_16x16x32_bf16 v[8:11], v[92:95], v[164:167], v[12:15]
	v_mfma_f32_16x16x32_bf16 v[100:103], v[136:139], v[152:155], v[100:103]
	v_mfma_f32_16x16x32_bf16 v[96:99], v[140:143], v[152:155], v[96:99]
	v_mfma_f32_16x16x32_bf16 v[132:135], v[136:139], v[156:159], v[132:135]
	v_mfma_f32_16x16x32_bf16 v[128:131], v[140:143], v[156:159], v[128:131]
	v_mfma_f32_16x16x32_bf16 v[124:127], v[136:139], v[168:171], v[124:127]
	v_mfma_f32_16x16x32_bf16 v[120:123], v[140:143], v[168:171], v[120:123]
	v_mfma_f32_16x16x32_bf16 v[92:95], v[140:143], v[172:175], v[8:11]
	s_barrier
	s_mov_b32 m0, s71
	s_add_u32 s80, s4, s50
	s_addc_u32 s81, s5, s51
	s_nop 0
	global_load_lds_dwordx4 v222, s[80:81]
	s_mov_b32 m0, s72
	s_nop 0
	s_add_u32 s80, s4, s58
	s_addc_u32 s81, s5, s59
	s_nop 0
	global_load_lds_dwordx4 v222, s[80:81]
	s_waitcnt vmcnt(6)
	s_barrier
	v_mfma_f32_16x16x32_bf16 v[8:11], v[176:179], v[144:147], v[80:83]
	v_mfma_f32_16x16x32_bf16 v[80:83], v[184:187], v[152:155], v[8:11]
	v_mfma_f32_16x16x32_bf16 v[8:11], v[180:183], v[144:147], v[84:87]
	v_mfma_f32_16x16x32_bf16 v[84:87], v[188:191], v[152:155], v[8:11]
	v_mfma_f32_16x16x32_bf16 v[8:11], v[176:179], v[148:151], v[104:107]
	v_mfma_f32_16x16x32_bf16 v[104:107], v[184:187], v[156:159], v[8:11]
	v_mfma_f32_16x16x32_bf16 v[8:11], v[180:183], v[148:151], v[108:111]
	v_mfma_f32_16x16x32_bf16 v[108:111], v[188:191], v[156:159], v[8:11]
	v_mfma_f32_16x16x32_bf16 v[8:11], v[176:179], v[160:163], v[56:59]
	v_mfma_f32_16x16x32_bf16 v[56:59], v[184:187], v[168:171], v[8:11]
	v_mfma_f32_16x16x32_bf16 v[8:11], v[180:183], v[160:163], v[60:63]
	v_mfma_f32_16x16x32_bf16 v[0:3], v[176:179], v[164:167], v[0:3]
	v_mfma_f32_16x16x32_bf16 v[4:7], v[180:183], v[164:167], v[4:7]
	v_mfma_f32_16x16x32_bf16 v[60:63], v[188:191], v[168:171], v[8:11]
	v_mfma_f32_16x16x32_bf16 v[0:3], v[184:187], v[172:175], v[0:3]
	v_mfma_f32_16x16x32_bf16 v[4:7], v[188:191], v[172:175], v[4:7]
	s_barrier
; #define LDA(dst,b,h) _Pragma("unroll") for(int m=0;m<4;++m) _Pragma("unroll") for(int k=0;k<2;++k) \
;     dst[m][k]=*reinterpret_cast<const bf16x8*>(SA(b,h)+(wr*64+m*16)*128+koff[k])
; #define LDB(dst,b,h) _Pragma("unroll") for(int n=0;n<2;++n) _Pragma("unroll") for(int k=0;k<2;++k) \
;     dst[n][k]=*reinterpret_cast<const bf16x8*>(SB(b,h)+(wc*32+n*16)*128+koff[k])
; #define MMA(ai,bj,Af,Bf) do{__builtin_amdgcn_s_setprio(1); \
;     _Pragma("unroll") for(int m=0;m<4;++m) _Pragma("unroll") for(int n=0;n<2;++n) _Pragma("unroll") for(int k=0;k<2;++k) \
;       acc[ai][bj][m][n]=__builtin_amdgcn_mfma_f32_16x16x32_bf16(Bf[n][k],Af[m][k],acc[ai][bj][m][n],0,0,0); \
;     __builtin_amdgcn_s_setprio(0);}while(0)
; #define WAIT_L(n) asm volatile("s_waitcnt lgkmcnt(" #n ")":::"memory")
; #define BAR __builtin_amdgcn_s_barrier()
; #define SCHED __builtin_amdgcn_sched_barrier(0)
; #define STAGE_A(b,h,kt) do{ unsigned char* _d = SA(b,h) + wbase; \
;     if constexpr (BLK) { const char* _s = baseA + ((size_t)(h)*(K/64) + (kt)) * 16384; GLDS(_s + voa, _d); GLDS(_s + 8192 + voa, _d + 8192); } \
;     else { const char* _s = baseA + ((size_t)(h)*128*K + (kt)*64) * 2; GLDS(_s + voa, _d); GLDS(_s + (size_t)128*K + voa, _d + 8192); } }while(0)
; template <int K, int EPI, bool MIX = false>
; __device__ __forceinline__ void gemm_phase(const Params& p, const u16* __restrict__ A, const u16* __restrict__ Bt,
;                            const float* __restrict__ rs_in, float* __restrict__ ssq_out, float alpha, bool rev = false) {
;     ...
;       const float* rsrc = MIX ? p.ssqb : rs_in;
;       int fr_p = fr;
;       asm volatile("" : "+v"(fr_p));
; #pragma unroll
;       for (int ai = 0; ai < 2; ++ai)
; #pragma unroll
;         for (int m = 0; m < 4; ++m) rsq[ai][m] = rsrc[cpm * 256 + ai * 128 + wr * 64 + m * 16 + fr_p];
;     }
;     ++it;
;     id = item_id(it);
;     const bool more = id < ntiles;
;     if (rev) id = ntiles - 1 - id;
;     {
;       LDB(B0,0,0); SCHED; LDA(At,0,0); STAGE_A(1,1,nt-1);
;       WAIT_L(8); BAR; WAIT_L(0); MMA(0,0,At,B0); BAR; SCHED;
;       if (more) SETUP_TILE();
	s_add_i32 s33, s33, 2
	s_add_u32 s60, s60, 0x100
	s_addc_u32 s61, s61, 0
	s_add_u32 s6, s6, 0x100
	s_addc_u32 s7, s7, 0
	s_add_u32 s4, s4, 0x100
	s_addc_u32 s5, s5, 0
	s_cmp_lt_u32 s33, 28
	s_cbranch_scc1 .LBB0_367
	v_mov_b32_e32 v8, v233
	s_add_i32 s77, s77, 1
	v_add_u32_e32 v8, s79, v8
	v_ashrrev_i32_e32 v9, 31, v8
	v_lshl_add_u64 v[8:9], v[8:9], 2, s[88:89]
	global_load_dword v253, v[8:9], off
	global_load_dword v252, v[8:9], off offset:64
	global_load_dword v251, v[8:9], off offset:128
	global_load_dword v250, v[8:9], off offset:192
	global_load_dword v249, v[8:9], off offset:512
	global_load_dword v248, v[8:9], off offset:576
	global_load_dword v247, v[8:9], off offset:640
	global_load_dword v246, v[8:9], off offset:704
	ds_read_b128 v[136:139], v234
	ds_read_b128 v[140:143], v234 offset:2048
	ds_read_b128 v[148:151], v235
	ds_read_b128 v[144:147], v235 offset:2048
	s_mul_i32 s4, s77, s57
	s_add_i32 s4, s4, s56
	v_lshl_add_u64 v[8:9], s[8:9], 0, v[220:221]
	s_mov_b64 s[6:7], 0x80f80
	s_mov_b32 m0, s74
	v_lshl_add_u64 v[10:11], v[8:9], 0, s[6:7]
	s_mov_b64 s[6:7], 0xc0f80
	ds_read_b128 v[176:179], v236
	ds_read_b128 v[164:167], v236 offset:2048
	ds_read_b128 v[180:183], v237
	ds_read_b128 v[168:171], v237 offset:2048
	ds_read_b128 v[152:155], v236 offset:4096
	ds_read_b128 v[156:159], v236 offset:6144
	ds_read_b128 v[172:175], v237 offset:4096
	ds_read_b128 v[160:163], v237 offset:6144
	global_load_lds_dwordx4 v[10:11], off
	v_lshl_add_u64 v[8:9], v[8:9], 0, s[6:7]
	s_mov_b32 m0, s75
	s_nop 0
	global_load_lds_dwordx4 v[8:9], off
	s_waitcnt lgkmcnt(8)
	s_barrier
	s_waitcnt lgkmcnt(0)
	v_mfma_f32_16x16x32_bf16 v[8:11], v[136:139], v[176:179], v[28:31]
	s_cmpk_lt_i32 s4, 0x600
	s_cselect_b64 s[6:7], -1, 0
	s_cmpk_gt_i32 s4, 0x5ff
	v_mfma_f32_16x16x32_bf16 v[12:15], v[140:143], v[176:179], v[24:27]
	v_mfma_f32_16x16x32_bf16 v[24:27], v[136:139], v[164:167], v[44:47]
	v_mfma_f32_16x16x32_bf16 v[28:31], v[140:143], v[164:167], v[40:43]
	v_mfma_f32_16x16x32_bf16 v[40:43], v[136:139], v[152:155], v[68:71]
	v_mfma_f32_16x16x32_bf16 v[44:47], v[140:143], v[152:155], v[64:67]
	v_mfma_f32_16x16x32_bf16 v[64:67], v[136:139], v[156:159], v[116:119]
	v_mfma_f32_16x16x32_bf16 v[68:71], v[140:143], v[156:159], v[112:115]
	v_mfma_f32_16x16x32_bf16 v[8:11], v[148:151], v[180:183], v[8:11]
	v_mfma_f32_16x16x32_bf16 v[12:15], v[144:147], v[180:183], v[12:15]
	v_mfma_f32_16x16x32_bf16 v[24:27], v[148:151], v[168:171], v[24:27]
	v_mfma_f32_16x16x32_bf16 v[28:31], v[144:147], v[168:171], v[28:31]
	v_mfma_f32_16x16x32_bf16 v[40:43], v[148:151], v[172:175], v[40:43]
	v_mfma_f32_16x16x32_bf16 v[44:47], v[144:147], v[172:175], v[44:47]
	v_mfma_f32_16x16x32_bf16 v[64:67], v[148:151], v[160:163], v[64:67]
	v_mfma_f32_16x16x32_bf16 v[68:71], v[144:147], v[160:163], v[68:71]
	s_barrier
	s_mov_b32 s33, s78
	s_cbranch_scc1 .LBB0_370
	s_ashr_i32 s5, s4, 31
	s_lshr_b32 s5, s5, 26
	s_add_i32 s5, s4, s5
	s_ashr_i32 s8, s5, 6
	s_andn2_b32 s5, s5, 63
	s_lshl_b32 s8, s8, 3
	s_sub_i32 s5, s4, s5
	s_and_b32 s4, s4, 7
	s_or_b32 s35, s8, s4
	s_lshl_b32 s4, s35, 8
	s_ashr_i32 s33, s5, 3
	s_ashr_i32 s5, s4, 31
	s_lshl_b64 s[4:5], s[4:5], 12
	s_add_u32 s8, s94, s4
	s_addc_u32 s9, s95, s5
	s_lshl_b32 s4, s33, 8
	s_ashr_i32 s5, s4, 31
	s_lshl_b64 s[4:5], s[4:5], 12
	v_readlane_b32 s80, v254, 32
	v_readlane_b32 s81, v254, 33
	s_add_u32 s12, s80, s4
	v_readlane_b32 s84, v254, 36
	v_readlane_b32 s85, v254, 37
	v_readlane_b32 s86, v254, 38
	v_readlane_b32 s87, v254, 39
	v_readlane_b32 s88, v254, 40
	v_readlane_b32 s89, v254, 41
	v_readlane_b32 s90, v254, 42
	v_readlane_b32 s91, v254, 43
	s_addc_u32 s13, s81, s5
	v_readlane_b32 s84, v254, 0
	s_add_u32 s16, s12, 0x80000
	v_readlane_b32 s90, v254, 6
	v_readlane_b32 s91, v254, 7
	s_addc_u32 s17, s13, 0
	v_readlane_b32 s82, v254, 34
	v_readlane_b32 s83, v254, 35
	v_readlane_b32 s92, v254, 44
	v_readlane_b32 s93, v254, 45
	v_readlane_b32 s94, v254, 46
	v_readlane_b32 s95, v254, 47
	v_readlane_b32 s85, v254, 1
	v_readlane_b32 s86, v254, 2
	v_readlane_b32 s87, v254, 3
	v_readlane_b32 s88, v254, 4
	v_readlane_b32 s89, v254, 5

.Llate_p6_done:
.LBB0_423:
	ds_read_b128 v[128:131], v224
	ds_read_b128 v[132:135], v224 offset:2048
	ds_read_b128 v[136:139], v225
	ds_read_b128 v[140:143], v225 offset:2048
	s_mov_b32 m0, s72
	ds_read_b128 v[144:147], v226
	ds_read_b128 v[148:151], v226 offset:2048
	ds_read_b128 v[152:155], v227
	ds_read_b128 v[156:159], v227 offset:2048
	ds_read_b128 v[160:163], v226 offset:4096
	ds_read_b128 v[164:167], v226 offset:6144
	ds_read_b128 v[168:171], v227 offset:4096
	ds_read_b128 v[172:175], v227 offset:6144
	s_add_u32 s96, s52, s24
	s_addc_u32 s97, s53, s25
	s_nop 0
	global_load_lds_dwordx4 v216, s[96:97]
	s_mov_b32 m0, s73
	s_nop 0
	s_add_u32 s96, s52, s26
	s_addc_u32 s97, s53, s27
	s_nop 0
	global_load_lds_dwordx4 v216, s[96:97]
	s_waitcnt lgkmcnt(8)
	s_barrier
	s_waitcnt lgkmcnt(0)
	v_mfma_f32_16x16x32_bf16 v[124:127], v[128:131], v[144:147], v[124:127]
	v_mfma_f32_16x16x32_bf16 v[120:123], v[132:135], v[144:147], v[120:123]
	v_mfma_f32_16x16x32_bf16 v[116:119], v[128:131], v[148:151], v[116:119]
	v_mfma_f32_16x16x32_bf16 v[112:115], v[132:135], v[148:151], v[112:115]
	v_mfma_f32_16x16x32_bf16 v[108:111], v[128:131], v[160:163], v[108:111]
	v_mfma_f32_16x16x32_bf16 v[104:107], v[132:135], v[160:163], v[104:107]
	v_mfma_f32_16x16x32_bf16 v[100:103], v[128:131], v[164:167], v[100:103]
	v_mfma_f32_16x16x32_bf16 v[96:99], v[132:135], v[164:167], v[96:99]
	v_mfma_f32_16x16x32_bf16 v[124:127], v[136:139], v[152:155], v[124:127]
	v_mfma_f32_16x16x32_bf16 v[120:123], v[140:143], v[152:155], v[120:123]
	v_mfma_f32_16x16x32_bf16 v[116:119], v[136:139], v[156:159], v[116:119]
	v_mfma_f32_16x16x32_bf16 v[112:115], v[140:143], v[156:159], v[112:115]
	v_mfma_f32_16x16x32_bf16 v[108:111], v[136:139], v[168:171], v[108:111]
	v_mfma_f32_16x16x32_bf16 v[104:107], v[140:143], v[168:171], v[104:107]
	v_mfma_f32_16x16x32_bf16 v[100:103], v[136:139], v[172:175], v[100:103]
	v_mfma_f32_16x16x32_bf16 v[96:99], v[140:143], v[172:175], v[96:99]
	s_barrier
	s_mov_b32 m0, s35
	ds_read_b128 v[176:179], v228
	ds_read_b128 v[180:183], v228 offset:2048
	ds_read_b128 v[184:187], v229
	ds_read_b128 v[188:191], v229 offset:2048
	s_add_u32 s96, s58, s28
	s_addc_u32 s97, s59, s29
	s_nop 0
	global_load_lds_dwordx4 v216, s[96:97]
	s_mov_b32 m0, s42
	s_nop 0
	s_add_u32 s96, s58, s30
	s_addc_u32 s97, s59, s31
	s_nop 0
	global_load_lds_dwordx4 v216, s[96:97]
	s_barrier
	s_waitcnt lgkmcnt(0)
	v_mfma_f32_16x16x32_bf16 v[92:95], v[176:179], v[144:147], v[92:95]
	v_mfma_f32_16x16x32_bf16 v[88:91], v[180:183], v[144:147], v[88:91]
	v_mfma_f32_16x16x32_bf16 v[84:87], v[176:179], v[148:151], v[84:87]
	v_mfma_f32_16x16x32_bf16 v[80:83], v[180:183], v[148:151], v[80:83]
	v_mfma_f32_16x16x32_bf16 v[76:79], v[176:179], v[160:163], v[76:79]
	v_mfma_f32_16x16x32_bf16 v[72:75], v[180:183], v[160:163], v[72:75]
	v_mfma_f32_16x16x32_bf16 v[68:71], v[176:179], v[164:167], v[68:71]
	v_mfma_f32_16x16x32_bf16 v[64:67], v[180:183], v[164:167], v[64:67]
	v_mfma_f32_16x16x32_bf16 v[92:95], v[184:187], v[152:155], v[92:95]
	v_mfma_f32_16x16x32_bf16 v[88:91], v[188:191], v[152:155], v[88:91]
	v_mfma_f32_16x16x32_bf16 v[84:87], v[184:187], v[156:159], v[84:87]
	v_mfma_f32_16x16x32_bf16 v[80:83], v[188:191], v[156:159], v[80:83]
	v_mfma_f32_16x16x32_bf16 v[76:79], v[184:187], v[168:171], v[76:79]
	v_mfma_f32_16x16x32_bf16 v[72:75], v[188:191], v[168:171], v[72:75]
	v_mfma_f32_16x16x32_bf16 v[68:71], v[184:187], v[172:175], v[68:71]
	v_mfma_f32_16x16x32_bf16 v[64:67], v[188:191], v[172:175], v[64:67]
	s_barrier
	s_mov_b32 m0, s33
	ds_read_b128 v[144:147], v226 offset:16384
	ds_read_b128 v[148:151], v226 offset:18432
	ds_read_b128 v[152:155], v227 offset:16384
	ds_read_b128 v[156:159], v227 offset:18432
	ds_read_b128 v[160:163], v226 offset:20480
	ds_read_b128 v[164:167], v226 offset:22528
	ds_read_b128 v[168:171], v227 offset:20480
	ds_read_b128 v[172:175], v227 offset:22528
	s_add_u32 s96, s52, s28
	s_addc_u32 s97, s53, s29
	s_nop 0
	global_load_lds_dwordx4 v216, s[96:97]
	s_mov_b32 m0, s43
	s_nop 0
	s_add_u32 s96, s52, s30
	s_addc_u32 s97, s53, s31
	s_nop 0
	global_load_lds_dwordx4 v216, s[96:97]
	s_barrier
	s_waitcnt lgkmcnt(0)
	v_mfma_f32_16x16x32_bf16 v[28:31], v[128:131], v[144:147], v[28:31]
	v_mfma_f32_16x16x32_bf16 v[24:27], v[132:135], v[144:147], v[24:27]
	v_mfma_f32_16x16x32_bf16 v[20:23], v[128:131], v[148:151], v[20:23]
	v_mfma_f32_16x16x32_bf16 v[16:19], v[132:135], v[148:151], v[16:19]
	v_mfma_f32_16x16x32_bf16 v[12:15], v[128:131], v[160:163], v[12:15]
	v_mfma_f32_16x16x32_bf16 v[8:11], v[132:135], v[160:163], v[8:11]
	v_mfma_f32_16x16x32_bf16 v[4:7], v[128:131], v[164:167], v[4:7]
	v_mfma_f32_16x16x32_bf16 v[0:3], v[132:135], v[164:167], v[0:3]
	v_mfma_f32_16x16x32_bf16 v[28:31], v[136:139], v[152:155], v[28:31]
	v_mfma_f32_16x16x32_bf16 v[24:27], v[140:143], v[152:155], v[24:27]
	v_mfma_f32_16x16x32_bf16 v[20:23], v[136:139], v[156:159], v[20:23]
	v_mfma_f32_16x16x32_bf16 v[16:19], v[140:143], v[156:159], v[16:19]
	v_mfma_f32_16x16x32_bf16 v[12:15], v[136:139], v[168:171], v[12:15]
	v_mfma_f32_16x16x32_bf16 v[8:11], v[140:143], v[168:171], v[8:11]
	v_mfma_f32_16x16x32_bf16 v[4:7], v[136:139], v[172:175], v[4:7]
	v_mfma_f32_16x16x32_bf16 v[0:3], v[140:143], v[172:175], v[0:3]
	s_barrier
	s_mov_b32 m0, s44
	s_add_u32 s96, s4, s28
	s_addc_u32 s97, s5, s29
	s_nop 0
	global_load_lds_dwordx4 v216, s[96:97]
	s_mov_b32 m0, s45
	s_nop 0
	s_add_u32 s96, s4, s30
	s_addc_u32 s97, s5, s31
	s_nop 0
	global_load_lds_dwordx4 v216, s[96:97]
	s_waitcnt vmcnt(6)
	s_barrier
	v_mfma_f32_16x16x32_bf16 v[32:35], v[176:179], v[144:147], v[32:35]
	v_mfma_f32_16x16x32_bf16 v[36:39], v[180:183], v[144:147], v[36:39]
	v_mfma_f32_16x16x32_bf16 v[40:43], v[176:179], v[148:151], v[40:43]
	v_mfma_f32_16x16x32_bf16 v[44:47], v[180:183], v[148:151], v[44:47]
	v_mfma_f32_16x16x32_bf16 v[48:51], v[176:179], v[160:163], v[48:51]
	v_mfma_f32_16x16x32_bf16 v[52:55], v[180:183], v[160:163], v[52:55]
	v_mfma_f32_16x16x32_bf16 v[56:59], v[176:179], v[164:167], v[56:59]
	v_mfma_f32_16x16x32_bf16 v[60:63], v[180:183], v[164:167], v[60:63]
	v_mfma_f32_16x16x32_bf16 v[32:35], v[184:187], v[152:155], v[32:35]
	v_mfma_f32_16x16x32_bf16 v[36:39], v[188:191], v[152:155], v[36:39]
	v_mfma_f32_16x16x32_bf16 v[40:43], v[184:187], v[156:159], v[40:43]
	v_mfma_f32_16x16x32_bf16 v[44:47], v[188:191], v[156:159], v[44:47]
	v_mfma_f32_16x16x32_bf16 v[48:51], v[184:187], v[168:171], v[48:51]
	v_mfma_f32_16x16x32_bf16 v[52:55], v[188:191], v[168:171], v[52:55]
	v_mfma_f32_16x16x32_bf16 v[56:59], v[184:187], v[172:175], v[56:59]
	v_mfma_f32_16x16x32_bf16 v[60:63], v[188:191], v[172:175], v[60:63]
	s_barrier
	ds_read_b128 v[128:131], v232
	ds_read_b128 v[132:135], v232 offset:2048
	ds_read_b128 v[136:139], v233
	ds_read_b128 v[140:143], v233 offset:2048
	s_mov_b32 m0, s60
	ds_read_b128 v[144:147], v226 offset:32768
	ds_read_b128 v[148:151], v226 offset:34816
	ds_read_b128 v[152:155], v227 offset:32768
	ds_read_b128 v[156:159], v227 offset:34816
	ds_read_b128 v[160:163], v226 offset:36864
	ds_read_b128 v[164:167], v226 offset:38912
	ds_read_b128 v[168:171], v227 offset:36864
	ds_read_b128 v[172:175], v227 offset:38912
	s_add_u32 s96, s52, s36
	s_addc_u32 s97, s53, s37
	s_nop 0
	global_load_lds_dwordx4 v216, s[96:97]
	s_mov_b32 m0, s61
	s_nop 0
	s_add_u32 s96, s52, s38
	s_addc_u32 s97, s53, s39
	s_nop 0
	global_load_lds_dwordx4 v216, s[96:97]
	s_waitcnt lgkmcnt(8)
	s_barrier
	s_waitcnt lgkmcnt(0)
	v_mfma_f32_16x16x32_bf16 v[124:127], v[128:131], v[144:147], v[124:127]
	v_mfma_f32_16x16x32_bf16 v[120:123], v[132:135], v[144:147], v[120:123]
	v_mfma_f32_16x16x32_bf16 v[116:119], v[128:131], v[148:151], v[116:119]
	v_mfma_f32_16x16x32_bf16 v[112:115], v[132:135], v[148:151], v[112:115]
	v_mfma_f32_16x16x32_bf16 v[108:111], v[128:131], v[160:163], v[108:111]
	v_mfma_f32_16x16x32_bf16 v[104:107], v[132:135], v[160:163], v[104:107]
	v_mfma_f32_16x16x32_bf16 v[100:103], v[128:131], v[164:167], v[100:103]
	v_mfma_f32_16x16x32_bf16 v[96:99], v[132:135], v[164:167], v[96:99]
	v_mfma_f32_16x16x32_bf16 v[124:127], v[136:139], v[152:155], v[124:127]
	v_mfma_f32_16x16x32_bf16 v[120:123], v[140:143], v[152:155], v[120:123]
	v_mfma_f32_16x16x32_bf16 v[116:119], v[136:139], v[156:159], v[116:119]
	v_mfma_f32_16x16x32_bf16 v[112:115], v[140:143], v[156:159], v[112:115]
	v_mfma_f32_16x16x32_bf16 v[108:111], v[136:139], v[168:171], v[108:111]
	v_mfma_f32_16x16x32_bf16 v[104:107], v[140:143], v[168:171], v[104:107]
	v_mfma_f32_16x16x32_bf16 v[100:103], v[136:139], v[172:175], v[100:103]
	v_mfma_f32_16x16x32_bf16 v[96:99], v[140:143], v[172:175], v[96:99]
	s_barrier
	s_mov_b32 m0, s62
	ds_read_b128 v[176:179], v234
	ds_read_b128 v[180:183], v234 offset:2048
	ds_read_b128 v[184:187], v235
	ds_read_b128 v[188:191], v235 offset:2048
	s_add_u32 s96, s58, s40
	s_addc_u32 s97, s59, s41
	s_nop 0
	global_load_lds_dwordx4 v216, s[96:97]
	s_mov_b32 m0, s63
	s_nop 0
	s_add_u32 s96, s58, s46
	s_addc_u32 s97, s59, s47
	s_nop 0
	global_load_lds_dwordx4 v216, s[96:97]
	s_barrier
	s_waitcnt lgkmcnt(0)
	v_mfma_f32_16x16x32_bf16 v[92:95], v[176:179], v[144:147], v[92:95]
	v_mfma_f32_16x16x32_bf16 v[88:91], v[180:183], v[144:147], v[88:91]
	v_mfma_f32_16x16x32_bf16 v[84:87], v[176:179], v[148:151], v[84:87]
	v_mfma_f32_16x16x32_bf16 v[80:83], v[180:183], v[148:151], v[80:83]
	v_mfma_f32_16x16x32_bf16 v[76:79], v[176:179], v[160:163], v[76:79]
	v_mfma_f32_16x16x32_bf16 v[72:75], v[180:183], v[160:163], v[72:75]
	v_mfma_f32_16x16x32_bf16 v[68:71], v[176:179], v[164:167], v[68:71]
	v_mfma_f32_16x16x32_bf16 v[64:67], v[180:183], v[164:167], v[64:67]
	v_mfma_f32_16x16x32_bf16 v[92:95], v[184:187], v[152:155], v[92:95]
	v_mfma_f32_16x16x32_bf16 v[88:91], v[188:191], v[152:155], v[88:91]
	v_mfma_f32_16x16x32_bf16 v[84:87], v[184:187], v[156:159], v[84:87]
	v_mfma_f32_16x16x32_bf16 v[80:83], v[188:191], v[156:159], v[80:83]
	v_mfma_f32_16x16x32_bf16 v[76:79], v[184:187], v[168:171], v[76:79]
	v_mfma_f32_16x16x32_bf16 v[72:75], v[188:191], v[168:171], v[72:75]
	v_mfma_f32_16x16x32_bf16 v[68:71], v[184:187], v[172:175], v[68:71]
	v_mfma_f32_16x16x32_bf16 v[64:67], v[188:191], v[172:175], v[64:67]
	s_barrier
	s_mov_b32 m0, s64
	ds_read_b128 v[144:147], v226 offset:49152
	ds_read_b128 v[148:151], v226 offset:51200
	ds_read_b128 v[152:155], v227 offset:49152
	ds_read_b128 v[156:159], v227 offset:51200
	ds_read_b128 v[160:163], v226 offset:53248
	ds_read_b128 v[164:167], v226 offset:55296
	ds_read_b128 v[168:171], v227 offset:53248
	ds_read_b128 v[172:175], v227 offset:55296
	s_add_u32 s96, s52, s40
	s_addc_u32 s97, s53, s41
	s_nop 0
	global_load_lds_dwordx4 v216, s[96:97]
	s_mov_b32 m0, s65
	s_nop 0
	s_add_u32 s96, s52, s46
	s_addc_u32 s97, s53, s47
	s_nop 0
	global_load_lds_dwordx4 v216, s[96:97]
	s_barrier
	s_waitcnt lgkmcnt(0)
	v_mfma_f32_16x16x32_bf16 v[28:31], v[128:131], v[144:147], v[28:31]
	v_mfma_f32_16x16x32_bf16 v[24:27], v[132:135], v[144:147], v[24:27]
	v_mfma_f32_16x16x32_bf16 v[20:23], v[128:131], v[148:151], v[20:23]
	v_mfma_f32_16x16x32_bf16 v[16:19], v[132:135], v[148:151], v[16:19]
	v_mfma_f32_16x16x32_bf16 v[12:15], v[128:131], v[160:163], v[12:15]
	v_mfma_f32_16x16x32_bf16 v[8:11], v[132:135], v[160:163], v[8:11]
	v_mfma_f32_16x16x32_bf16 v[4:7], v[128:131], v[164:167], v[4:7]
	v_mfma_f32_16x16x32_bf16 v[0:3], v[132:135], v[164:167], v[0:3]
	v_mfma_f32_16x16x32_bf16 v[28:31], v[136:139], v[152:155], v[28:31]
	v_mfma_f32_16x16x32_bf16 v[24:27], v[140:143], v[152:155], v[24:27]
	v_mfma_f32_16x16x32_bf16 v[20:23], v[136:139], v[156:159], v[20:23]
	v_mfma_f32_16x16x32_bf16 v[16:19], v[140:143], v[156:159], v[16:19]
	v_mfma_f32_16x16x32_bf16 v[12:15], v[136:139], v[168:171], v[12:15]
	v_mfma_f32_16x16x32_bf16 v[8:11], v[140:143], v[168:171], v[8:11]
	v_mfma_f32_16x16x32_bf16 v[4:7], v[136:139], v[172:175], v[4:7]
	v_mfma_f32_16x16x32_bf16 v[0:3], v[140:143], v[172:175], v[0:3]
	s_barrier
	s_mov_b32 m0, s68
	s_add_u32 s96, s4, s40
	s_addc_u32 s97, s5, s41
	s_nop 0
	global_load_lds_dwordx4 v216, s[96:97]
	s_mov_b32 m0, s69
	s_nop 0
	s_add_u32 s96, s4, s46
	s_addc_u32 s97, s5, s47
	s_nop 0
	global_load_lds_dwordx4 v216, s[96:97]
	s_waitcnt vmcnt(6)
	s_barrier
	v_mfma_f32_16x16x32_bf16 v[32:35], v[176:179], v[144:147], v[32:35]
	v_mfma_f32_16x16x32_bf16 v[36:39], v[180:183], v[144:147], v[36:39]
	v_mfma_f32_16x16x32_bf16 v[40:43], v[176:179], v[148:151], v[40:43]
	v_mfma_f32_16x16x32_bf16 v[44:47], v[180:183], v[148:151], v[44:47]
	v_mfma_f32_16x16x32_bf16 v[48:51], v[176:179], v[160:163], v[48:51]
	v_mfma_f32_16x16x32_bf16 v[52:55], v[180:183], v[160:163], v[52:55]
	v_mfma_f32_16x16x32_bf16 v[56:59], v[176:179], v[164:167], v[56:59]
	v_mfma_f32_16x16x32_bf16 v[60:63], v[180:183], v[164:167], v[60:63]
	v_mfma_f32_16x16x32_bf16 v[32:35], v[184:187], v[152:155], v[32:35]
	v_mfma_f32_16x16x32_bf16 v[36:39], v[188:191], v[152:155], v[36:39]
	v_mfma_f32_16x16x32_bf16 v[40:43], v[184:187], v[156:159], v[40:43]
	v_mfma_f32_16x16x32_bf16 v[44:47], v[188:191], v[156:159], v[44:47]
	v_mfma_f32_16x16x32_bf16 v[48:51], v[184:187], v[168:171], v[48:51]
	v_mfma_f32_16x16x32_bf16 v[52:55], v[188:191], v[168:171], v[52:55]
	v_mfma_f32_16x16x32_bf16 v[56:59], v[184:187], v[172:175], v[56:59]
	v_mfma_f32_16x16x32_bf16 v[60:63], v[188:191], v[172:175], v[60:63]
	s_barrier
	s_add_i32 s77, s77, 2
	s_add_u32 s58, s58, 0x100
	s_addc_u32 s59, s59, 0
	s_add_u32 s52, s52, 0x100
	s_addc_u32 s53, s53, 0
	s_add_u32 s4, s4, 0x100
	s_addc_u32 s5, s5, 0
	s_cmp_lt_u32 s77, 28
	s_cbranch_scc1 .LBB0_423
; #define LDA(dst,b,h) _Pragma("unroll") for(int m=0;m<4;++m) _Pragma("unroll") for(int k=0;k<2;++k) \
;     dst[m][k]=*reinterpret_cast<const bf16x8*>(SA(b,h)+(wr*64+m*16)*128+koff[k])
; #define LDB(dst,b,h) _Pragma("unroll") for(int n=0;n<2;++n) _Pragma("unroll") for(int k=0;k<2;++k) \
;     dst[n][k]=*reinterpret_cast<const bf16x8*>(SB(b,h)+(wc*32+n*16)*128+koff[k])
; #define MMA(ai,bj,Af,Bf) do{__builtin_amdgcn_s_setprio(1); \
;     _Pragma("unroll") for(int m=0;m<4;++m) _Pragma("unroll") for(int n=0;n<2;++n) _Pragma("unroll") for(int k=0;k<2;++k) \
;       acc[ai][bj][m][n]=__builtin_amdgcn_mfma_f32_16x16x32_bf16(Bf[n][k],Af[m][k],acc[ai][bj][m][n],0,0,0); \
;     __builtin_amdgcn_s_setprio(0);}while(0)
; #define WAIT_L(n) asm volatile("s_waitcnt lgkmcnt(" #n ")":::"memory")
; #define BAR __builtin_amdgcn_s_barrier()
; #define SCHED __builtin_amdgcn_sched_barrier(0)
; #define STAGE_A(b,h,kt) do{ unsigned char* _d = SA(b,h) + wbase; \
;     if constexpr (BLK) { const char* _s = baseA + ((size_t)(h)*(K/64) + (kt)) * 16384; GLDS(_s + voa, _d); GLDS(_s + 8192 + voa, _d + 8192); } \
;     else { const char* _s = baseA + ((size_t)(h)*128*K + (kt)*64) * 2; GLDS(_s + voa, _d); GLDS(_s + (size_t)128*K + voa, _d + 8192); } }while(0)
; template <int K, int EPI, bool MIX = false>
; __device__ __forceinline__ void gemm_phase(const Params& p, const u16* __restrict__ A, const u16* __restrict__ Bt,
;                            const float* __restrict__ rs_in, float* __restrict__ ssq_out, float alpha, bool rev = false) {
;     ...
;         for (int m = 0; m < 4; ++m) rsq[ai][m] = rsrc[cpm * 256 + ai * 128 + wr * 64 + m * 16 + fr_p];
;     }
;     ++it;
;     id = item_id(it);
;     const bool more = id < ntiles;
;     if (rev) id = ntiles - 1 - id;
;     {
;       LDB(B0,0,0); SCHED; LDA(At,0,0); STAGE_A(1,1,nt-1);
;       WAIT_L(8); BAR; WAIT_L(0); MMA(0,0,At,B0); BAR; SCHED;
;       if (more) SETUP_TILE();
	v_mov_b32_e32 v128, v223
	s_lshl_b32 s59, s34, 8
	s_add_i32 s59, s59, s70
	v_add_u32_e32 v128, s59, v128
	v_readlane_b32 s80, v254, 32
	v_ashrrev_i32_e32 v129, 31, v128
	v_readlane_b32 s94, v254, 46
	v_readlane_b32 s95, v254, 47
	s_add_i32 s75, s75, 1
	s_mul_i32 s4, s75, s57
	v_lshl_add_u64 v[128:129], v[128:129], 2, s[94:95]
	global_load_dword v214, v[128:129], off
	global_load_dword v243, v[128:129], off offset:64
	global_load_dword v242, v[128:129], off offset:128
	global_load_dword v241, v[128:129], off offset:192
	global_load_dword v240, v[128:129], off offset:512
	global_load_dword v239, v[128:129], off offset:576
	global_load_dword v238, v[128:129], off offset:640
	global_load_dword v237, v[128:129], off offset:704
	ds_read_b128 v[136:139], v224
	ds_read_b128 v[140:143], v224 offset:2048
	ds_read_b128 v[148:151], v225
	ds_read_b128 v[144:147], v225 offset:2048
	s_add_i32 s4, s4, s56
	v_readlane_b32 s81, v254, 33
	v_readlane_b32 s82, v254, 34
	v_readlane_b32 s83, v254, 35
	v_readlane_b32 s84, v254, 36
	v_readlane_b32 s85, v254, 37
	v_readlane_b32 s86, v254, 38
	v_readlane_b32 s87, v254, 39
	v_readlane_b32 s88, v254, 40
	v_readlane_b32 s89, v254, 41
	v_readlane_b32 s90, v254, 42
	v_readlane_b32 s91, v254, 43
	v_readlane_b32 s92, v254, 44
	v_readlane_b32 s93, v254, 45
	v_lshl_add_u64 v[128:129], s[0:1], 0, v[212:213]
	s_mov_b32 m0, s72
	v_lshl_add_u64 v[130:131], v[128:129], 0, s[48:49]
	ds_read_b128 v[152:155], v226
	ds_read_b128 v[156:159], v226 offset:2048
	ds_read_b128 v[180:183], v227
	ds_read_b128 v[172:175], v227 offset:2048
	ds_read_b128 v[160:163], v226 offset:4096
	ds_read_b128 v[164:167], v226 offset:6144
	ds_read_b128 v[176:179], v227 offset:4096
	ds_read_b128 v[168:171], v227 offset:6144
	global_load_lds_dwordx4 v[130:131], off
	v_lshl_add_u64 v[128:129], v[128:129], 0, s[50:51]
	s_mov_b32 m0, s73
	s_nop 0
	global_load_lds_dwordx4 v[128:129], off
	s_waitcnt lgkmcnt(8)
	s_barrier
	s_waitcnt lgkmcnt(0)
	v_mfma_f32_16x16x32_bf16 v[124:127], v[136:139], v[152:155], v[124:127]
	s_cmpk_lt_i32 s4, 0x2100
	s_cselect_b64 s[52:53], -1, 0
	s_cmpk_gt_i32 s4, 0x20ff
	v_mfma_f32_16x16x32_bf16 v[120:123], v[140:143], v[152:155], v[120:123]
	v_mfma_f32_16x16x32_bf16 v[116:119], v[136:139], v[156:159], v[116:119]
	v_mfma_f32_16x16x32_bf16 v[112:115], v[140:143], v[156:159], v[112:115]
	v_mfma_f32_16x16x32_bf16 v[108:111], v[136:139], v[160:163], v[108:111]
	v_mfma_f32_16x16x32_bf16 v[104:107], v[140:143], v[160:163], v[104:107]
	v_mfma_f32_16x16x32_bf16 v[100:103], v[136:139], v[164:167], v[100:103]
	v_mfma_f32_16x16x32_bf16 v[96:99], v[140:143], v[164:167], v[96:99]
	v_mfma_f32_16x16x32_bf16 v[124:127], v[148:151], v[180:183], v[124:127]
	v_mfma_f32_16x16x32_bf16 v[120:123], v[144:147], v[180:183], v[120:123]
	v_mfma_f32_16x16x32_bf16 v[116:119], v[148:151], v[172:175], v[116:119]
	v_mfma_f32_16x16x32_bf16 v[112:115], v[144:147], v[172:175], v[112:115]
	v_mfma_f32_16x16x32_bf16 v[108:111], v[148:151], v[176:179], v[108:111]
	v_mfma_f32_16x16x32_bf16 v[104:107], v[144:147], v[176:179], v[104:107]
	v_mfma_f32_16x16x32_bf16 v[128:131], v[148:151], v[168:171], v[100:103]
	v_mfma_f32_16x16x32_bf16 v[132:135], v[144:147], v[168:171], v[96:99]
	s_barrier
	s_mov_b32 s58, s76
	s_cbranch_scc1 .LBB0_426
	s_mul_hi_i32 s0, s4, 0x2e8ba2e9
	s_lshr_b32 s1, s0, 31
	s_ashr_i32 s0, s0, 6
	s_add_i32 s0, s0, s1
	s_lshl_b32 s1, s0, 3
	s_mulk_i32 s0, 0xfea0
	s_add_i32 s0, s0, s4
	s_and_b32 s4, s4, 7
	s_or_b32 s34, s1, s4
	s_ashr_i32 s58, s0, 3
	s_lshl_b32 s0, s34, 8
	v_readlane_b32 s80, v254, 0
	s_ashr_i32 s1, s0, 31
	v_readlane_b32 s86, v254, 6
	v_readlane_b32 s87, v254, 7
	s_lshl_b64 s[0:1], s[0:1], 12
	s_mov_b64 s[10:11], s[86:87]
	v_readlane_b32 s81, v254, 1
	v_readlane_b32 s82, v254, 2
	v_readlane_b32 s83, v254, 3
	v_readlane_b32 s84, v254, 4
	v_readlane_b32 s85, v254, 5
	s_add_u32 s0, s10, s0
	s_addc_u32 s1, s11, s1
	s_lshl_b32 s4, s58, 7
	v_readlane_b32 s80, v254, 32
	s_ashr_i32 s5, s4, 31
	v_readlane_b32 s82, v254, 34
	v_readlane_b32 s83, v254, 35
	s_lshl_b64 s[4:5], s[4:5], 12
	s_mov_b64 s[78:79], s[82:83]
	s_add_u32 s8, s78, s4
	s_addc_u32 s9, s79, s5
	s_add_u32 s10, s8, 0x1600000
	s_addc_u32 s11, s9, 0
	v_readlane_b32 s81, v254, 33
	v_readlane_b32 s84, v254, 36
	v_readlane_b32 s85, v254, 37
	v_readlane_b32 s86, v254, 38
	v_readlane_b32 s87, v254, 39
	v_readlane_b32 s88, v254, 40
	v_readlane_b32 s89, v254, 41
	v_readlane_b32 s90, v254, 42
	v_readlane_b32 s91, v254, 43
	v_readlane_b32 s92, v254, 44
	v_readlane_b32 s93, v254, 45
	v_readlane_b32 s94, v254, 46
	v_readlane_b32 s95, v254, 47

.Llate_p7_done:
.LBB0_463:
	ds_read_b128 v[128:131], v225
	ds_read_b128 v[132:135], v225 offset:2048
	ds_read_b128 v[136:139], v226
	ds_read_b128 v[140:143], v226 offset:2048
	s_mov_b32 m0, s64
	ds_read_b128 v[144:147], v227
	ds_read_b128 v[148:151], v227 offset:2048
	ds_read_b128 v[152:155], v228
	ds_read_b128 v[156:159], v228 offset:2048
	ds_read_b128 v[160:163], v227 offset:4096
	ds_read_b128 v[164:167], v227 offset:6144
	ds_read_b128 v[168:171], v228 offset:4096
	ds_read_b128 v[172:175], v228 offset:6144
	s_add_u32 s96, s50, s18
	s_addc_u32 s97, s51, s19
	s_nop 0
	global_load_lds_dwordx4 v218, s[96:97]
	s_mov_b32 m0, s65
	s_nop 0
	s_add_u32 s96, s50, s20
	s_addc_u32 s97, s51, s21
	s_nop 0
	global_load_lds_dwordx4 v218, s[96:97]
	s_waitcnt lgkmcnt(8)
	s_barrier
	s_waitcnt lgkmcnt(0)
	v_mfma_f32_16x16x32_bf16 v[124:127], v[128:131], v[144:147], v[124:127]
	v_mfma_f32_16x16x32_bf16 v[120:123], v[132:135], v[144:147], v[120:123]
	v_mfma_f32_16x16x32_bf16 v[116:119], v[128:131], v[148:151], v[116:119]
	v_mfma_f32_16x16x32_bf16 v[112:115], v[132:135], v[148:151], v[112:115]
	v_mfma_f32_16x16x32_bf16 v[108:111], v[128:131], v[160:163], v[108:111]
	v_mfma_f32_16x16x32_bf16 v[104:107], v[132:135], v[160:163], v[104:107]
	v_mfma_f32_16x16x32_bf16 v[100:103], v[128:131], v[164:167], v[100:103]
	v_mfma_f32_16x16x32_bf16 v[96:99], v[132:135], v[164:167], v[96:99]
	v_mfma_f32_16x16x32_bf16 v[124:127], v[136:139], v[152:155], v[124:127]
	v_mfma_f32_16x16x32_bf16 v[120:123], v[140:143], v[152:155], v[120:123]
	v_mfma_f32_16x16x32_bf16 v[116:119], v[136:139], v[156:159], v[116:119]
	v_mfma_f32_16x16x32_bf16 v[112:115], v[140:143], v[156:159], v[112:115]
	v_mfma_f32_16x16x32_bf16 v[108:111], v[136:139], v[168:171], v[108:111]
	v_mfma_f32_16x16x32_bf16 v[104:107], v[140:143], v[168:171], v[104:107]
	v_mfma_f32_16x16x32_bf16 v[100:103], v[136:139], v[172:175], v[100:103]
	v_mfma_f32_16x16x32_bf16 v[96:99], v[140:143], v[172:175], v[96:99]
	s_barrier
	s_mov_b32 m0, s34
	ds_read_b128 v[176:179], v229
	ds_read_b128 v[180:183], v229 offset:2048
	ds_read_b128 v[184:187], v232
	ds_read_b128 v[188:191], v232 offset:2048
	s_add_u32 s96, s52, s26
	s_addc_u32 s97, s53, s27
	s_nop 0
	global_load_lds_dwordx4 v218, s[96:97]
	s_mov_b32 m0, s35
	s_nop 0
	s_add_u32 s96, s52, s28
	s_addc_u32 s97, s53, s29
	s_nop 0
	global_load_lds_dwordx4 v218, s[96:97]
	s_barrier
	s_waitcnt lgkmcnt(0)
	v_mfma_f32_16x16x32_bf16 v[92:95], v[176:179], v[144:147], v[92:95]
	v_mfma_f32_16x16x32_bf16 v[88:91], v[180:183], v[144:147], v[88:91]
	v_mfma_f32_16x16x32_bf16 v[84:87], v[176:179], v[148:151], v[84:87]
	v_mfma_f32_16x16x32_bf16 v[80:83], v[180:183], v[148:151], v[80:83]
	v_mfma_f32_16x16x32_bf16 v[76:79], v[176:179], v[160:163], v[76:79]
	v_mfma_f32_16x16x32_bf16 v[72:75], v[180:183], v[160:163], v[72:75]
	v_mfma_f32_16x16x32_bf16 v[68:71], v[176:179], v[164:167], v[68:71]
	v_mfma_f32_16x16x32_bf16 v[64:67], v[180:183], v[164:167], v[64:67]
	v_mfma_f32_16x16x32_bf16 v[92:95], v[184:187], v[152:155], v[92:95]
	v_mfma_f32_16x16x32_bf16 v[88:91], v[188:191], v[152:155], v[88:91]
	v_mfma_f32_16x16x32_bf16 v[84:87], v[184:187], v[156:159], v[84:87]
	v_mfma_f32_16x16x32_bf16 v[80:83], v[188:191], v[156:159], v[80:83]
	v_mfma_f32_16x16x32_bf16 v[76:79], v[184:187], v[168:171], v[76:79]
	v_mfma_f32_16x16x32_bf16 v[72:75], v[188:191], v[168:171], v[72:75]
	v_mfma_f32_16x16x32_bf16 v[68:71], v[184:187], v[172:175], v[68:71]
	v_mfma_f32_16x16x32_bf16 v[64:67], v[188:191], v[172:175], v[64:67]
	s_barrier
	s_mov_b32 m0, s33
	ds_read_b128 v[144:147], v227 offset:16384
	ds_read_b128 v[148:151], v227 offset:18432
	ds_read_b128 v[152:155], v228 offset:16384
	ds_read_b128 v[156:159], v228 offset:18432
	ds_read_b128 v[160:163], v227 offset:20480
	ds_read_b128 v[164:167], v227 offset:22528
	ds_read_b128 v[168:171], v228 offset:20480
	ds_read_b128 v[172:175], v228 offset:22528
	s_add_u32 s96, s50, s26
	s_addc_u32 s97, s51, s27
	s_nop 0
	global_load_lds_dwordx4 v218, s[96:97]
	s_mov_b32 m0, s42
	s_nop 0
	s_add_u32 s96, s50, s28
	s_addc_u32 s97, s51, s29
	s_nop 0
	global_load_lds_dwordx4 v218, s[96:97]
	s_barrier
	s_waitcnt lgkmcnt(0)
	v_mfma_f32_16x16x32_bf16 v[60:63], v[128:131], v[144:147], v[60:63]
	v_mfma_f32_16x16x32_bf16 v[56:59], v[132:135], v[144:147], v[56:59]
	v_mfma_f32_16x16x32_bf16 v[52:55], v[128:131], v[148:151], v[52:55]
	v_mfma_f32_16x16x32_bf16 v[48:51], v[132:135], v[148:151], v[48:51]
	v_mfma_f32_16x16x32_bf16 v[44:47], v[128:131], v[160:163], v[44:47]
	v_mfma_f32_16x16x32_bf16 v[40:43], v[132:135], v[160:163], v[40:43]
	v_mfma_f32_16x16x32_bf16 v[36:39], v[128:131], v[164:167], v[36:39]
	v_mfma_f32_16x16x32_bf16 v[32:35], v[132:135], v[164:167], v[32:35]
	v_mfma_f32_16x16x32_bf16 v[60:63], v[136:139], v[152:155], v[60:63]
	v_mfma_f32_16x16x32_bf16 v[56:59], v[140:143], v[152:155], v[56:59]
	v_mfma_f32_16x16x32_bf16 v[52:55], v[136:139], v[156:159], v[52:55]
	v_mfma_f32_16x16x32_bf16 v[48:51], v[140:143], v[156:159], v[48:51]
	v_mfma_f32_16x16x32_bf16 v[44:47], v[136:139], v[168:171], v[44:47]
	v_mfma_f32_16x16x32_bf16 v[40:43], v[140:143], v[168:171], v[40:43]
	v_mfma_f32_16x16x32_bf16 v[36:39], v[136:139], v[172:175], v[36:39]
	v_mfma_f32_16x16x32_bf16 v[32:35], v[140:143], v[172:175], v[32:35]
	s_barrier
	s_mov_b32 m0, s43
	s_add_u32 s96, s2, s26
	s_addc_u32 s97, s3, s27
	s_nop 0
	global_load_lds_dwordx4 v218, s[96:97]
	s_mov_b32 m0, s44
	s_nop 0
	s_add_u32 s96, s2, s28
	s_addc_u32 s97, s3, s29
	s_nop 0
	global_load_lds_dwordx4 v218, s[96:97]
	s_waitcnt vmcnt(6)
	s_barrier
	v_mfma_f32_16x16x32_bf16 v[28:31], v[176:179], v[144:147], v[28:31]
	v_mfma_f32_16x16x32_bf16 v[24:27], v[180:183], v[144:147], v[24:27]
	v_mfma_f32_16x16x32_bf16 v[20:23], v[176:179], v[148:151], v[20:23]
	v_mfma_f32_16x16x32_bf16 v[16:19], v[180:183], v[148:151], v[16:19]
	v_mfma_f32_16x16x32_bf16 v[12:15], v[176:179], v[160:163], v[12:15]
	v_mfma_f32_16x16x32_bf16 v[8:11], v[180:183], v[160:163], v[8:11]
	v_mfma_f32_16x16x32_bf16 v[4:7], v[176:179], v[164:167], v[4:7]
	v_mfma_f32_16x16x32_bf16 v[0:3], v[180:183], v[164:167], v[0:3]
	v_mfma_f32_16x16x32_bf16 v[28:31], v[184:187], v[152:155], v[28:31]
	v_mfma_f32_16x16x32_bf16 v[24:27], v[188:191], v[152:155], v[24:27]
	v_mfma_f32_16x16x32_bf16 v[20:23], v[184:187], v[156:159], v[20:23]
	v_mfma_f32_16x16x32_bf16 v[16:19], v[188:191], v[156:159], v[16:19]
	v_mfma_f32_16x16x32_bf16 v[12:15], v[184:187], v[168:171], v[12:15]
	v_mfma_f32_16x16x32_bf16 v[8:11], v[188:191], v[168:171], v[8:11]
	v_mfma_f32_16x16x32_bf16 v[4:7], v[184:187], v[172:175], v[4:7]
	v_mfma_f32_16x16x32_bf16 v[0:3], v[188:191], v[172:175], v[0:3]
	s_barrier
	ds_read_b128 v[128:131], v233
	ds_read_b128 v[132:135], v233 offset:2048
	ds_read_b128 v[136:139], v234
	ds_read_b128 v[140:143], v234 offset:2048
	s_mov_b32 m0, s45
	ds_read_b128 v[144:147], v227 offset:32768
	ds_read_b128 v[148:151], v227 offset:34816
	ds_read_b128 v[152:155], v228 offset:32768
	ds_read_b128 v[156:159], v228 offset:34816
	ds_read_b128 v[160:163], v227 offset:36864
	ds_read_b128 v[164:167], v227 offset:38912
	ds_read_b128 v[168:171], v228 offset:36864
	ds_read_b128 v[172:175], v228 offset:38912
	s_add_u32 s96, s50, s30
	s_addc_u32 s97, s51, s31
	s_nop 0
	global_load_lds_dwordx4 v218, s[96:97]
	s_mov_b32 m0, s54
	s_nop 0
	s_add_u32 s96, s50, s36
	s_addc_u32 s97, s51, s37
	s_nop 0
	global_load_lds_dwordx4 v218, s[96:97]
	s_waitcnt lgkmcnt(8)
	s_barrier
	s_waitcnt lgkmcnt(0)
	v_mfma_f32_16x16x32_bf16 v[124:127], v[128:131], v[144:147], v[124:127]
	v_mfma_f32_16x16x32_bf16 v[120:123], v[132:135], v[144:147], v[120:123]
	v_mfma_f32_16x16x32_bf16 v[116:119], v[128:131], v[148:151], v[116:119]
	v_mfma_f32_16x16x32_bf16 v[112:115], v[132:135], v[148:151], v[112:115]
	v_mfma_f32_16x16x32_bf16 v[108:111], v[128:131], v[160:163], v[108:111]
	v_mfma_f32_16x16x32_bf16 v[104:107], v[132:135], v[160:163], v[104:107]
	v_mfma_f32_16x16x32_bf16 v[100:103], v[128:131], v[164:167], v[100:103]
	v_mfma_f32_16x16x32_bf16 v[96:99], v[132:135], v[164:167], v[96:99]
	v_mfma_f32_16x16x32_bf16 v[124:127], v[136:139], v[152:155], v[124:127]
	v_mfma_f32_16x16x32_bf16 v[120:123], v[140:143], v[152:155], v[120:123]
	v_mfma_f32_16x16x32_bf16 v[116:119], v[136:139], v[156:159], v[116:119]
	v_mfma_f32_16x16x32_bf16 v[112:115], v[140:143], v[156:159], v[112:115]
	v_mfma_f32_16x16x32_bf16 v[108:111], v[136:139], v[168:171], v[108:111]
	v_mfma_f32_16x16x32_bf16 v[104:107], v[140:143], v[168:171], v[104:107]
	v_mfma_f32_16x16x32_bf16 v[100:103], v[136:139], v[172:175], v[100:103]
	v_mfma_f32_16x16x32_bf16 v[96:99], v[140:143], v[172:175], v[96:99]
	s_barrier
	s_mov_b32 m0, s55
	ds_read_b128 v[176:179], v235
	ds_read_b128 v[180:183], v235 offset:2048
	ds_read_b128 v[184:187], v236
	ds_read_b128 v[188:191], v236 offset:2048
	s_add_u32 s96, s52, s38
	s_addc_u32 s97, s53, s39
	s_nop 0
	global_load_lds_dwordx4 v218, s[96:97]
	s_mov_b32 m0, s58
	s_nop 0
	s_add_u32 s96, s52, s40
	s_addc_u32 s97, s53, s41
	s_nop 0
	global_load_lds_dwordx4 v218, s[96:97]
	s_barrier
	s_waitcnt lgkmcnt(0)
	v_mfma_f32_16x16x32_bf16 v[92:95], v[176:179], v[144:147], v[92:95]
	v_mfma_f32_16x16x32_bf16 v[88:91], v[180:183], v[144:147], v[88:91]
	v_mfma_f32_16x16x32_bf16 v[84:87], v[176:179], v[148:151], v[84:87]
	v_mfma_f32_16x16x32_bf16 v[80:83], v[180:183], v[148:151], v[80:83]
	v_mfma_f32_16x16x32_bf16 v[76:79], v[176:179], v[160:163], v[76:79]
	v_mfma_f32_16x16x32_bf16 v[72:75], v[180:183], v[160:163], v[72:75]
	v_mfma_f32_16x16x32_bf16 v[68:71], v[176:179], v[164:167], v[68:71]
	v_mfma_f32_16x16x32_bf16 v[64:67], v[180:183], v[164:167], v[64:67]
	v_mfma_f32_16x16x32_bf16 v[92:95], v[184:187], v[152:155], v[92:95]
	v_mfma_f32_16x16x32_bf16 v[88:91], v[188:191], v[152:155], v[88:91]
	v_mfma_f32_16x16x32_bf16 v[84:87], v[184:187], v[156:159], v[84:87]
	v_mfma_f32_16x16x32_bf16 v[80:83], v[188:191], v[156:159], v[80:83]
	v_mfma_f32_16x16x32_bf16 v[76:79], v[184:187], v[168:171], v[76:79]
	v_mfma_f32_16x16x32_bf16 v[72:75], v[188:191], v[168:171], v[72:75]
	v_mfma_f32_16x16x32_bf16 v[68:71], v[184:187], v[172:175], v[68:71]
	v_mfma_f32_16x16x32_bf16 v[64:67], v[188:191], v[172:175], v[64:67]
	s_barrier
	s_mov_b32 m0, s59
	ds_read_b128 v[144:147], v227 offset:49152
	ds_read_b128 v[148:151], v227 offset:51200
	ds_read_b128 v[152:155], v228 offset:49152
	ds_read_b128 v[156:159], v228 offset:51200
	ds_read_b128 v[160:163], v227 offset:53248
	ds_read_b128 v[164:167], v227 offset:55296
	ds_read_b128 v[168:171], v228 offset:53248
	ds_read_b128 v[172:175], v228 offset:55296
	s_add_u32 s96, s50, s38
	s_addc_u32 s97, s51, s39
	s_nop 0
	global_load_lds_dwordx4 v218, s[96:97]
	s_mov_b32 m0, s60
	s_nop 0
	s_add_u32 s96, s50, s40
	s_addc_u32 s97, s51, s41
	s_nop 0
	global_load_lds_dwordx4 v218, s[96:97]
	s_barrier
; #define LDA(dst,b,h) _Pragma("unroll") for(int m=0;m<4;++m) _Pragma("unroll") for(int k=0;k<2;++k) \
;     dst[m][k]=*reinterpret_cast<const bf16x8*>(SA(b,h)+(wr*64+m*16)*128+koff[k])
; #define LDB(dst,b,h) _Pragma("unroll") for(int n=0;n<2;++n) _Pragma("unroll") for(int k=0;k<2;++k) \
;     dst[n][k]=*reinterpret_cast<const bf16x8*>(SB(b,h)+(wc*32+n*16)*128+koff[k])
; #define MMA(ai,bj,Af,Bf) do{__builtin_amdgcn_s_setprio(1); \
;     _Pragma("unroll") for(int m=0;m<4;++m) _Pragma("unroll") for(int n=0;n<2;++n) _Pragma("unroll") for(int k=0;k<2;++k) \
;       acc[ai][bj][m][n]=__builtin_amdgcn_mfma_f32_16x16x32_bf16(Bf[n][k],Af[m][k],acc[ai][bj][m][n],0,0,0); \
;     __builtin_amdgcn_s_setprio(0);}while(0)
; #define WAIT_V(n) asm volatile("s_waitcnt vmcnt(" #n ")":::"memory")
; #define WAIT_L(n) asm volatile("s_waitcnt lgkmcnt(" #n ")":::"memory")
; #define BAR __builtin_amdgcn_s_barrier()
; #define SCHED __builtin_amdgcn_sched_barrier(0)
; #define STAGE_A(b,h,kt) do{ unsigned char* _d = SA(b,h) + wbase; \
;     if constexpr (BLK) { const char* _s = baseA + ((size_t)(h)*(K/64) + (kt)) * 16384; GLDS(_s + voa, _d); GLDS(_s + 8192 + voa, _d + 8192); } \
;     else { const char* _s = baseA + ((size_t)(h)*128*K + (kt)*64) * 2; GLDS(_s + voa, _d); GLDS(_s + (size_t)128*K + voa, _d + 8192); } }while(0)
; template <int K, int EPI, bool MIX = false>
; __device__ __forceinline__ void gemm_phase(const Params& p, const u16* __restrict__ A, const u16* __restrict__ Bt,
;                            const float* __restrict__ rs_in, float* __restrict__ ssq_out, float alpha, bool rev = false) {
;     ...
;     {
;       LDB(B0,0,0); SCHED; LDA(At,0,0); STAGE_A(1,1,nt-1);
;       WAIT_L(8); BAR; WAIT_L(0); MMA(0,0,At,B0); BAR; SCHED;
;       if (more) SETUP_TILE();
;       LDB(B1,0,1); if (more) STAGE_B(0,0,0);
;       BAR; WAIT_L(0); MMA(0,1,At,B1); BAR;
;       LDA(At,0,1); if (more) STAGE_A(0,0,0);
;       BAR; WAIT_L(0); MMA(1,0,At,B0); BAR; SCHED;
;       if (more) { STAGE_B(0,1,0); WAIT_V(6); } else { WAIT_V(0); }
;       BAR; MMA(1,1,At,B1); BAR;
;       LDB(B0,1,0); SCHED; LDA(At,1,0); if (more) STAGE_A(0,1,0);
;       WAIT_L(8); BAR; WAIT_L(0); MMA(0,0,At,B0); BAR; SCHED;
;       LDB(B1,1,1); if (more) STAGE_B(1,0,1);
;       BAR; WAIT_L(0); MMA(0,1,At,B1); BAR;
;       LDA(At,1,1); if (more) STAGE_A(1,0,1);
	s_waitcnt lgkmcnt(0)
	v_mfma_f32_16x16x32_bf16 v[60:63], v[128:131], v[144:147], v[60:63]
	v_mfma_f32_16x16x32_bf16 v[56:59], v[132:135], v[144:147], v[56:59]
	v_mfma_f32_16x16x32_bf16 v[52:55], v[128:131], v[148:151], v[52:55]
	v_mfma_f32_16x16x32_bf16 v[48:51], v[132:135], v[148:151], v[48:51]
	v_mfma_f32_16x16x32_bf16 v[44:47], v[128:131], v[160:163], v[44:47]
	v_mfma_f32_16x16x32_bf16 v[40:43], v[132:135], v[160:163], v[40:43]
	v_mfma_f32_16x16x32_bf16 v[36:39], v[128:131], v[164:167], v[36:39]
	v_mfma_f32_16x16x32_bf16 v[32:35], v[132:135], v[164:167], v[32:35]
	v_mfma_f32_16x16x32_bf16 v[60:63], v[136:139], v[152:155], v[60:63]
	v_mfma_f32_16x16x32_bf16 v[56:59], v[140:143], v[152:155], v[56:59]
	v_mfma_f32_16x16x32_bf16 v[52:55], v[136:139], v[156:159], v[52:55]
	v_mfma_f32_16x16x32_bf16 v[48:51], v[140:143], v[156:159], v[48:51]
	v_mfma_f32_16x16x32_bf16 v[44:47], v[136:139], v[168:171], v[44:47]
	v_mfma_f32_16x16x32_bf16 v[40:43], v[140:143], v[168:171], v[40:43]
	v_mfma_f32_16x16x32_bf16 v[36:39], v[136:139], v[172:175], v[36:39]
	v_mfma_f32_16x16x32_bf16 v[32:35], v[140:143], v[172:175], v[32:35]
	s_barrier
	s_mov_b32 m0, s61
	s_add_u32 s96, s2, s38
	s_addc_u32 s97, s3, s39
	s_nop 0
	global_load_lds_dwordx4 v218, s[96:97]
	s_mov_b32 m0, s62
	s_nop 0
	s_add_u32 s96, s2, s40
	s_addc_u32 s97, s3, s41
	s_nop 0
	global_load_lds_dwordx4 v218, s[96:97]
	s_waitcnt vmcnt(6)
	s_barrier
	v_mfma_f32_16x16x32_bf16 v[28:31], v[176:179], v[144:147], v[28:31]
	v_mfma_f32_16x16x32_bf16 v[24:27], v[180:183], v[144:147], v[24:27]
	v_mfma_f32_16x16x32_bf16 v[20:23], v[176:179], v[148:151], v[20:23]
	v_mfma_f32_16x16x32_bf16 v[16:19], v[180:183], v[148:151], v[16:19]
	v_mfma_f32_16x16x32_bf16 v[12:15], v[176:179], v[160:163], v[12:15]
	v_mfma_f32_16x16x32_bf16 v[8:11], v[180:183], v[160:163], v[8:11]
	v_mfma_f32_16x16x32_bf16 v[4:7], v[176:179], v[164:167], v[4:7]
	v_mfma_f32_16x16x32_bf16 v[0:3], v[180:183], v[164:167], v[0:3]
	v_mfma_f32_16x16x32_bf16 v[28:31], v[184:187], v[152:155], v[28:31]
	v_mfma_f32_16x16x32_bf16 v[24:27], v[188:191], v[152:155], v[24:27]
	v_mfma_f32_16x16x32_bf16 v[20:23], v[184:187], v[156:159], v[20:23]
	v_mfma_f32_16x16x32_bf16 v[16:19], v[188:191], v[156:159], v[16:19]
	v_mfma_f32_16x16x32_bf16 v[12:15], v[184:187], v[168:171], v[12:15]
	v_mfma_f32_16x16x32_bf16 v[8:11], v[188:191], v[168:171], v[8:11]
	v_mfma_f32_16x16x32_bf16 v[4:7], v[184:187], v[172:175], v[4:7]
	v_mfma_f32_16x16x32_bf16 v[0:3], v[188:191], v[172:175], v[0:3]
	s_barrier
	s_add_i32 s67, s67, 2
	s_add_u32 s52, s52, 0x8000
	s_addc_u32 s53, s53, 0
	s_add_u32 s50, s50, 0x8000
	s_addc_u32 s51, s51, 0
	s_add_u32 s2, s2, 0x8000
	s_addc_u32 s3, s3, 0
	s_cmpk_lt_u32 s67, 0x54
	s_cbranch_scc1 .LBB0_463
	ds_read_b128 v[144:147], v225
	ds_read_b128 v[148:151], v225 offset:2048
	ds_read_b128 v[156:159], v226
	ds_read_b128 v[152:155], v226 offset:2048
	s_add_i32 s66, s66, 1
	s_mul_i32 s2, s66, s76
	s_add_i32 s2, s2, s77
	s_cmpk_lt_i32 s2, 0x600
	s_cselect_b64 s[50:51], -1, 0
	s_cmpk_gt_i32 s2, 0x5ff
	v_lshl_add_u64 v[128:129], s[4:5], 0, v[216:217]
	s_mov_b32 m0, s64
	v_lshl_add_u64 v[130:131], v[128:129], 0, s[46:47]
	ds_read_b128 v[160:163], v227
	ds_read_b128 v[164:167], v227 offset:2048
	ds_read_b128 v[188:191], v228
	ds_read_b128 v[180:183], v228 offset:2048
	ds_read_b128 v[168:171], v227 offset:4096
	ds_read_b128 v[172:175], v227 offset:6144
	ds_read_b128 v[184:187], v228 offset:4096
	ds_read_b128 v[176:179], v228 offset:6144
	global_load_lds_dwordx4 v[130:131], off
	v_lshl_add_u64 v[128:129], v[128:129], 0, s[48:49]
	s_mov_b32 m0, s65
	s_nop 0
	global_load_lds_dwordx4 v[128:129], off
	s_waitcnt lgkmcnt(8)
	s_barrier
	s_waitcnt lgkmcnt(0)
	v_mfma_f32_16x16x32_bf16 v[124:127], v[144:147], v[160:163], v[124:127]
	v_mfma_f32_16x16x32_bf16 v[120:123], v[148:151], v[160:163], v[120:123]
	v_mfma_f32_16x16x32_bf16 v[116:119], v[144:147], v[164:167], v[116:119]
	v_mfma_f32_16x16x32_bf16 v[112:115], v[148:151], v[164:167], v[112:115]
	v_mfma_f32_16x16x32_bf16 v[108:111], v[144:147], v[168:171], v[108:111]
	v_mfma_f32_16x16x32_bf16 v[104:107], v[148:151], v[168:171], v[104:107]
	v_mfma_f32_16x16x32_bf16 v[100:103], v[144:147], v[172:175], v[100:103]
	v_mfma_f32_16x16x32_bf16 v[96:99], v[148:151], v[172:175], v[96:99]
	v_mfma_f32_16x16x32_bf16 v[124:127], v[156:159], v[188:191], v[124:127]
	v_mfma_f32_16x16x32_bf16 v[120:123], v[152:155], v[188:191], v[120:123]
	v_mfma_f32_16x16x32_bf16 v[128:131], v[156:159], v[180:183], v[116:119]
	v_mfma_f32_16x16x32_bf16 v[132:135], v[152:155], v[180:183], v[112:115]
	v_mfma_f32_16x16x32_bf16 v[108:111], v[156:159], v[184:187], v[108:111]
	v_mfma_f32_16x16x32_bf16 v[104:107], v[152:155], v[184:187], v[104:107]
	v_mfma_f32_16x16x32_bf16 v[136:139], v[156:159], v[176:179], v[100:103]
	v_mfma_f32_16x16x32_bf16 v[140:143], v[152:155], v[176:179], v[96:99]
	s_barrier
	s_mov_b32 s67, s69
	s_mov_b32 s68, s70
	s_cbranch_scc1 .LBB0_466
	s_sub_i32 s2, 0x5ff, s2
	s_lshr_b32 s3, s2, 3
	s_and_b32 s3, s3, 0x1ffffff8
	s_lshl_b32 s4, s3, 3
	s_sub_i32 s4, s2, s4
	s_and_b32 s2, s2, 7
	s_or_b32 s68, s3, s2
	s_ashr_i32 s67, s4, 3
	s_lshl_b32 s2, s68, 1
	s_mul_i32 s3, s68, 0x2c0000
	v_readlane_b32 s76, v254, 32
	s_mul_hi_u32 s2, s2, 0x160000
	s_add_u32 s4, s92, s3
	v_readlane_b32 s80, v254, 36
	v_readlane_b32 s81, v254, 37
	s_addc_u32 s5, s93, s2
	s_lshl_b32 s2, s67, 1
	s_mul_i32 s3, s67, 0x2c0000
	s_mov_b64 s[8:9], s[80:81]
	s_mul_hi_i32 s2, s2, 0x160000
	s_add_u32 s8, s8, s3
	v_readlane_b32 s84, v254, 40
	v_readlane_b32 s85, v254, 41
	v_readlane_b32 s86, v254, 42
	v_readlane_b32 s87, v254, 43
	v_readlane_b32 s88, v254, 44
	v_readlane_b32 s89, v254, 45
	v_readlane_b32 s90, v254, 46
	v_readlane_b32 s91, v254, 47
	s_addc_u32 s9, s9, s2
	v_readlane_b32 s77, v254, 33
	v_readlane_b32 s84, v254, 0
	s_add_u32 s10, s8, 0x160000
	s_mov_b32 s76, s57
	s_mov_b32 s77, s56
	v_readlane_b32 s85, v254, 1
	v_readlane_b32 s90, v254, 6
	v_readlane_b32 s91, v254, 7
	s_addc_u32 s11, s9, 0
	v_readlane_b32 s78, v254, 34
	v_readlane_b32 s79, v254, 35
	v_readlane_b32 s82, v254, 38
	v_readlane_b32 s83, v254, 39
	v_readlane_b32 s86, v254, 2
	v_readlane_b32 s87, v254, 3
	v_readlane_b32 s88, v254, 4
	v_readlane_b32 s89, v254, 5
